# GEMM epilogue tile stores marked nt (cache-policy lever: streaming stores should not evict the A/B tiles from L2)
# baseline (speedup 1.0000x reference)
.LBB0_274:
	s_lshl_b32 s21, s30, 8
	v_add_u32_e32 v168, s21, v155
	v_ashrrev_i32_e32 v169, 31, v168
	v_lshl_or_b32 v136, s55, 7, v158
	v_lshlrev_b64 v[138:139], 11, v[168:169]
	v_ashrrev_i32_e32 v137, 31, v136
	v_lshl_add_u64 v[138:139], s[84:85], 0, v[138:139]
	v_lshl_add_u64 v[138:139], v[136:137], 1, v[138:139]
	global_load_dwordx4 v[164:167], v[138:139], off
	v_lshl_add_u64 v[136:137], v[168:169], 2, s[8:9]
	global_load_dword v168, v[136:137], off
	global_load_dword v190, v[136:137], off offset:64
	global_load_dword v196, v[136:137], off offset:128
	v_add_co_u32_e32 v188, vcc, s46, v138
	v_and_b32_e32 v169, 64, v162
	s_nop 0
	v_addc_co_u32_e32 v189, vcc, 0, v139, vcc
	global_load_dwordx4 v[180:183], v[188:189], off
	v_xor_b32_e32 v163, 16, v162
	v_mul_f32_e32 v124, 0xbfb8aa3b, v124
	v_mul_f32_e32 v120, 0xbfb8aa3b, v120
	v_mul_f32_e32 v125, 0xbfb8aa3b, v125
	v_mul_f32_e32 v121, 0xbfb8aa3b, v121
	v_mul_f32_e32 v126, 0xbfb8aa3b, v126
	v_mul_f32_e32 v122, 0xbfb8aa3b, v122
	v_mul_f32_e32 v127, 0xbfb8aa3b, v127
	v_mul_f32_e32 v123, 0xbfb8aa3b, v123
	v_add_u32_e32 v169, 64, v169
	v_xor_b32_e32 v184, 32, v162
	v_exp_f32_e32 v124, v124
	v_exp_f32_e32 v120, v120
	v_exp_f32_e32 v125, v125
	v_exp_f32_e32 v121, v121
	v_exp_f32_e32 v126, v126
	v_exp_f32_e32 v122, v122
	v_exp_f32_e32 v185, v127
	v_exp_f32_e32 v123, v123
	v_cmp_lt_i32_e32 vcc, v163, v169
	v_add_f32_e32 v120, 1.0, v120
	v_add_f32_e32 v121, 1.0, v121
	v_cndmask_b32_e32 v127, v162, v163, vcc
	v_cmp_lt_i32_e32 vcc, v184, v169
	v_lshlrev_b32_e32 v163, 2, v127
	v_add_f32_e32 v126, 1.0, v126
	v_cndmask_b32_e32 v169, v162, v184, vcc
	v_add_co_u32_e32 v192, vcc, s42, v138
	v_lshlrev_b32_e32 v127, 2, v169
	s_nop 0
	v_addc_co_u32_e32 v193, vcc, 0, v139, vcc
	v_add_f32_e32 v169, 1.0, v124
	v_add_f32_e32 v184, 1.0, v125
	v_add_f32_e32 v122, 1.0, v122
	v_add_f32_e32 v185, 1.0, v185
	v_add_f32_e32 v123, 1.0, v123
	v_add_co_u32_e32 v124, vcc, s45, v138
	v_rcp_f32_e32 v200, v120
	s_nop 0
	v_addc_co_u32_e32 v125, vcc, 0, v139, vcc
	v_rcp_f32_e32 v199, v184
	v_rcp_f32_e32 v201, v121
	v_rcp_f32_e32 v202, v126
	v_rcp_f32_e32 v204, v122
	v_rcp_f32_e32 v203, v185
	v_rcp_f32_e32 v205, v123
	global_load_dwordx4 v[184:187], v[192:193], off
	global_load_dwordx4 v[120:123], v[124:125], off
	global_load_dword v126, v[136:137], off offset:192
	v_rcp_f32_e32 v198, v169
	v_mul_f32_e32 v100, 0xbfb8aa3b, v100
	v_mul_f32_e32 v96, 0xbfb8aa3b, v96
	v_exp_f32_e32 v100, v100
	v_mul_f32_e32 v101, 0xbfb8aa3b, v101
	v_mul_f32_e32 v97, 0xbfb8aa3b, v97
	v_exp_f32_e32 v101, v101
	v_mul_f32_e32 v102, 0xbfb8aa3b, v102
	v_mul_f32_e32 v98, 0xbfb8aa3b, v98
	v_exp_f32_e32 v102, v102
	v_mul_f32_e32 v103, 0xbfb8aa3b, v103
	v_mul_f32_e32 v99, 0xbfb8aa3b, v99
	v_exp_f32_e32 v103, v103
	v_mul_f32_e32 v84, 0xbfb8aa3b, v84
	v_mul_f32_e32 v80, 0xbfb8aa3b, v80
	v_exp_f32_e32 v84, v84
	v_mul_f32_e32 v85, 0xbfb8aa3b, v85
	v_mul_f32_e32 v81, 0xbfb8aa3b, v81
	v_exp_f32_e32 v85, v85
	v_mul_f32_e32 v86, 0xbfb8aa3b, v86
	s_waitcnt vmcnt(0)
	v_lshlrev_b32_e32 v206, 16, v164
	v_and_b32_e32 v207, 0xffff0000, v164
	v_lshlrev_b32_e32 v164, 16, v165
	v_and_b32_e32 v165, 0xffff0000, v165
	v_lshlrev_b32_e32 v208, 16, v166
	v_and_b32_e32 v209, 0xffff0000, v166
	v_lshlrev_b32_e32 v166, 16, v167
	v_and_b32_e32 v167, 0xffff0000, v167
	v_pk_mul_f32 v[164:165], v[168:169], v[164:165] op_sel_hi:[0,1]
	v_pk_mul_f32 v[206:207], v[168:169], v[206:207] op_sel_hi:[0,1]
	v_pk_mul_f32 v[166:167], v[168:169], v[166:167] op_sel_hi:[0,1]
	v_pk_mul_f32 v[168:169], v[168:169], v[208:209] op_sel_hi:[0,1]
	v_pk_fma_f32 v[116:117], v[116:117], v[198:199], v[206:207]
	v_pk_fma_f32 v[168:169], v[112:113], v[200:201], v[168:169]
	v_pk_fma_f32 v[118:119], v[118:119], v[202:203], v[164:165]
	v_pk_fma_f32 v[164:165], v[114:115], v[204:205], v[166:167]
	v_cvt_pk_bf16_f32 v112, v116, v117
	v_cvt_pk_bf16_f32 v113, v118, v119
	v_cvt_pk_bf16_f32 v114, v168, v169
	v_cvt_pk_bf16_f32 v115, v164, v165
	global_store_dwordx4 v[138:139], v[112:115], off nt
	v_mul_f32_e32 v82, 0xbfb8aa3b, v82
	v_exp_f32_e32 v86, v86
	v_pk_mul_f32 v[114:115], v[118:119], v[118:119]
	v_pk_mul_f32 v[118:119], v[164:165], v[164:165]
	v_exp_f32_e32 v165, v96
	v_add_f32_e32 v96, 1.0, v100
	v_pk_mul_f32 v[112:113], v[116:117], v[116:117]
	v_pk_mul_f32 v[116:117], v[168:169], v[168:169]
	v_add_f32_e32 v100, 1.0, v165
	v_exp_f32_e32 v165, v97
	v_add_f32_e32 v97, 1.0, v101
	v_add_f32_e32 v114, v114, v115
	v_add_f32_e32 v112, v112, v113
	v_add_f32_e32 v101, 1.0, v165
	v_exp_f32_e32 v165, v98
	v_add_f32_e32 v98, 1.0, v102
	v_add_f32_e32 v112, v112, v114
	v_add_f32_e32 v113, v116, v117
	v_add_f32_e32 v102, 1.0, v165
	v_exp_f32_e32 v165, v99
	v_add_f32_e32 v99, 1.0, v103
	v_rcp_f32_e32 v96, v96
	v_rcp_f32_e32 v100, v100
	v_add_f32_e32 v103, 1.0, v165
	v_rcp_f32_e32 v97, v97
	v_rcp_f32_e32 v101, v101
	v_rcp_f32_e32 v98, v98
	v_rcp_f32_e32 v102, v102
	v_rcp_f32_e32 v99, v99
	v_rcp_f32_e32 v103, v103
	v_add_f32_e32 v112, v113, v112
	v_add_f32_e32 v113, v118, v119
	v_add_f32_e32 v164, v113, v112
	v_lshlrev_b32_e32 v112, 16, v180
	v_and_b32_e32 v113, 0xffff0000, v180
	v_lshlrev_b32_e32 v114, 16, v181
	v_and_b32_e32 v115, 0xffff0000, v181
	v_lshlrev_b32_e32 v116, 16, v182
	v_and_b32_e32 v117, 0xffff0000, v182
	v_lshlrev_b32_e32 v118, 16, v183
	v_and_b32_e32 v119, 0xffff0000, v183
	v_pk_mul_f32 v[114:115], v[190:191], v[114:115] op_sel_hi:[0,1]
	v_pk_mul_f32 v[112:113], v[190:191], v[112:113] op_sel_hi:[0,1]
	v_pk_mul_f32 v[118:119], v[190:191], v[118:119] op_sel_hi:[0,1]
	v_pk_mul_f32 v[116:117], v[190:191], v[116:117] op_sel_hi:[0,1]
	v_pk_fma_f32 v[108:109], v[108:109], v[96:97], v[112:113]
	v_pk_fma_f32 v[100:101], v[104:105], v[100:101], v[116:117]
	v_pk_fma_f32 v[104:105], v[110:111], v[98:99], v[114:115]
	v_pk_fma_f32 v[102:103], v[106:107], v[102:103], v[118:119]
	v_cvt_pk_bf16_f32 v96, v108, v109
	v_cvt_pk_bf16_f32 v97, v104, v105
	v_cvt_pk_bf16_f32 v98, v100, v101
	v_cvt_pk_bf16_f32 v99, v102, v103
	global_store_dwordx4 v[188:189], v[96:99], off nt
	v_mul_f32_e32 v87, 0xbfb8aa3b, v87
	v_mul_f32_e32 v83, 0xbfb8aa3b, v83
	v_pk_mul_f32 v[98:99], v[104:105], v[104:105]
	v_exp_f32_e32 v105, v80
	v_add_f32_e32 v80, 1.0, v84
	v_exp_f32_e32 v87, v87
	v_pk_mul_f32 v[96:97], v[108:109], v[108:109]
	v_add_f32_e32 v84, 1.0, v105
	v_exp_f32_e32 v105, v81
	v_add_f32_e32 v81, 1.0, v85
	v_pk_mul_f32 v[100:101], v[100:101], v[100:101]
	v_add_f32_e32 v98, v98, v99
	v_add_f32_e32 v85, 1.0, v105
	v_exp_f32_e32 v105, v82
	v_add_f32_e32 v82, 1.0, v86
	v_add_f32_e32 v96, v96, v97
	v_pk_mul_f32 v[102:103], v[102:103], v[102:103]
	v_add_f32_e32 v86, 1.0, v105
	v_exp_f32_e32 v105, v83
	v_add_f32_e32 v83, 1.0, v87
	v_add_f32_e32 v96, v96, v98
	v_add_f32_e32 v97, v100, v101
	v_add_f32_e32 v87, 1.0, v105
	v_rcp_f32_e32 v80, v80
	v_rcp_f32_e32 v84, v84
	v_rcp_f32_e32 v81, v81
	v_rcp_f32_e32 v85, v85
	v_rcp_f32_e32 v82, v82
	v_rcp_f32_e32 v86, v86
	v_rcp_f32_e32 v83, v83
	v_rcp_f32_e32 v87, v87
	v_add_f32_e32 v96, v97, v96
	v_add_f32_e32 v97, v102, v103
	v_add_f32_e32 v104, v97, v96
	v_lshlrev_b32_e32 v96, 16, v184
	v_and_b32_e32 v97, 0xffff0000, v184
	v_lshlrev_b32_e32 v98, 16, v185
	v_and_b32_e32 v99, 0xffff0000, v185
	v_lshlrev_b32_e32 v100, 16, v186
	v_and_b32_e32 v101, 0xffff0000, v186
	v_lshlrev_b32_e32 v102, 16, v187
	v_and_b32_e32 v103, 0xffff0000, v187
	v_pk_mul_f32 v[98:99], v[196:197], v[98:99] op_sel_hi:[0,1]
	v_pk_mul_f32 v[96:97], v[196:197], v[96:97] op_sel_hi:[0,1]
	v_pk_mul_f32 v[102:103], v[196:197], v[102:103] op_sel_hi:[0,1]
	v_pk_mul_f32 v[100:101], v[196:197], v[100:101] op_sel_hi:[0,1]
	v_pk_fma_f32 v[92:93], v[92:93], v[80:81], v[96:97]
	v_pk_fma_f32 v[84:85], v[88:89], v[84:85], v[100:101]
	v_pk_fma_f32 v[88:89], v[94:95], v[82:83], v[98:99]
	v_pk_fma_f32 v[86:87], v[90:91], v[86:87], v[102:103]
	v_cvt_pk_bf16_f32 v80, v92, v93
	v_cvt_pk_bf16_f32 v81, v88, v89
	v_cvt_pk_bf16_f32 v82, v84, v85
	v_cvt_pk_bf16_f32 v83, v86, v87
	v_mul_f32_e32 v68, 0xbfb8aa3b, v68
	v_mul_f32_e32 v64, 0xbfb8aa3b, v64
	global_store_dwordx4 v[192:193], v[80:83], off nt
	v_exp_f32_e32 v68, v68
	v_mul_f32_e32 v69, 0xbfb8aa3b, v69
	v_pk_mul_f32 v[82:83], v[88:89], v[88:89]
	v_exp_f32_e32 v89, v64
	v_mul_f32_e32 v65, 0xbfb8aa3b, v65
	v_add_f32_e32 v64, 1.0, v68
	v_exp_f32_e32 v69, v69
	v_add_f32_e32 v68, 1.0, v89
	v_exp_f32_e32 v89, v65
	v_mul_f32_e32 v70, 0xbfb8aa3b, v70
	v_mul_f32_e32 v66, 0xbfb8aa3b, v66
	v_add_f32_e32 v65, 1.0, v69
	v_add_f32_e32 v69, 1.0, v89
	v_exp_f32_e32 v70, v70
	v_exp_f32_e32 v89, v66
	v_mul_f32_e32 v71, 0xbfb8aa3b, v71
	v_exp_f32_e32 v71, v71
	v_mul_f32_e32 v67, 0xbfb8aa3b, v67
	v_add_f32_e32 v66, 1.0, v70
	v_add_f32_e32 v70, 1.0, v89
	v_exp_f32_e32 v89, v67
	v_pk_mul_f32 v[80:81], v[92:93], v[92:93]
	v_pk_mul_f32 v[84:85], v[84:85], v[84:85]
	v_add_f32_e32 v82, v82, v83
	v_add_f32_e32 v80, v80, v81
	v_add_f32_e32 v67, 1.0, v71
	v_pk_mul_f32 v[86:87], v[86:87], v[86:87]
	v_add_f32_e32 v80, v80, v82
	v_add_f32_e32 v81, v84, v85
	v_rcp_f32_e32 v64, v64
	v_rcp_f32_e32 v65, v65
	v_rcp_f32_e32 v66, v66
	v_rcp_f32_e32 v67, v67
	v_add_f32_e32 v71, 1.0, v89
	v_add_f32_e32 v80, v81, v80
	v_add_f32_e32 v81, v86, v87
	v_rcp_f32_e32 v68, v68
	v_rcp_f32_e32 v69, v69
	v_rcp_f32_e32 v70, v70
	v_rcp_f32_e32 v71, v71
	v_add_f32_e32 v88, v81, v80
	v_lshlrev_b32_e32 v80, 16, v120
	v_and_b32_e32 v81, 0xffff0000, v120
	v_lshlrev_b32_e32 v82, 16, v121
	v_and_b32_e32 v83, 0xffff0000, v121
	v_lshlrev_b32_e32 v84, 16, v122
	v_and_b32_e32 v85, 0xffff0000, v122
	v_lshlrev_b32_e32 v86, 16, v123
	v_and_b32_e32 v87, 0xffff0000, v123
	v_pk_mul_f32 v[82:83], v[126:127], v[82:83] op_sel_hi:[0,1]
	v_pk_mul_f32 v[80:81], v[126:127], v[80:81] op_sel_hi:[0,1]
	v_pk_mul_f32 v[86:87], v[126:127], v[86:87] op_sel_hi:[0,1]
	v_pk_mul_f32 v[84:85], v[126:127], v[84:85] op_sel_hi:[0,1]
	v_pk_fma_f32 v[64:65], v[76:77], v[64:65], v[80:81]
	v_pk_fma_f32 v[78:79], v[78:79], v[66:67], v[82:83]
	v_pk_fma_f32 v[76:77], v[72:73], v[68:69], v[84:85]
	v_pk_fma_f32 v[80:81], v[74:75], v[70:71], v[86:87]
	v_cvt_pk_bf16_f32 v74, v64, v65
	v_pk_mul_f32 v[64:65], v[64:65], v[64:65]
	v_pk_mul_f32 v[66:67], v[78:79], v[78:79]
	v_pk_mul_f32 v[68:69], v[76:77], v[76:77]
	v_add_f32_e32 v66, v66, v67
	v_add_f32_e32 v64, v64, v65
	v_pk_mul_f32 v[70:71], v[80:81], v[80:81]
	v_add_f32_e32 v64, v64, v66
	v_add_f32_e32 v65, v68, v69
	v_add_f32_e32 v64, v65, v64
	v_add_f32_e32 v65, v70, v71
	v_add_f32_e32 v64, v65, v64
	ds_bpermute_b32 v66, v163, v164
	ds_bpermute_b32 v65, v163, v104
	ds_bpermute_b32 v69, v163, v88
	ds_bpermute_b32 v71, v163, v64
	v_cvt_pk_bf16_f32 v75, v78, v79
	s_waitcnt lgkmcnt(3)
	v_add_f32_e32 v67, v164, v66
	s_waitcnt lgkmcnt(2)
	v_add_f32_e32 v65, v104, v65
	s_waitcnt lgkmcnt(1)
	v_add_f32_e32 v69, v88, v69
	s_waitcnt lgkmcnt(0)
	v_add_f32_e32 v71, v64, v71
	ds_bpermute_b32 v68, v127, v67
	ds_bpermute_b32 v66, v127, v65
	ds_bpermute_b32 v70, v127, v69
	ds_bpermute_b32 v72, v127, v71
	v_cvt_pk_bf16_f32 v76, v76, v77
	v_cvt_pk_bf16_f32 v77, v80, v81
	v_cmp_lt_i32_e32 vcc, 0, v171
	global_store_dwordx4 v[124:125], v[74:77], off nt
	s_and_saveexec_b64 s[2:3], vcc
	s_xor_b64 s[2:3], exec, s[2:3]
	s_cbranch_execz .LBB0_280
	v_cmp_ne_u32_e32 vcc, 1, v171
	s_and_saveexec_b64 s[14:15], vcc
	s_xor_b64 s[14:15], exec, s[14:15]
	s_cbranch_execz .LBB0_277
	s_waitcnt lgkmcnt(0)
	v_add_f32_e32 v64, v71, v72
	v_add_f32_e32 v65, v69, v70
	v_cndmask_b32_e64 v64, v64, v65, s[0:1]

.LBB0_282:
	s_or_b64 exec, exec, s[2:3]
	v_mul_f32_e32 v64, 0x49800000, v64
	v_trunc_f32_e32 v64, v64
	v_mul_f32_e32 v65, 0x2f800000, v64
	v_floor_f32_e32 v65, v65
	v_fmac_f32_e32 v64, 0xcf800000, v65
	s_waitcnt lgkmcnt(2)
	v_cvt_u32_f32_e32 v66, v64
	v_cvt_u32_f32_e32 v67, v65
	v_add_u32_e32 v64, s21, v157
	v_ashrrev_i32_e32 v65, 31, v64
	v_lshl_add_u64 v[68:69], v[64:65], 3, s[62:63]
	v_add_co_u32_e32 v80, vcc, s51, v138
	global_atomic_add_x2 v[68:69], v[66:67], off
	s_nop 0
	v_addc_co_u32_e32 v81, vcc, 0, v139, vcc
	s_waitcnt lgkmcnt(1)
	global_load_dwordx4 v[68:71], v[80:81], off
	global_load_dword v82, v[136:137], off offset:512
	v_add_co_u32_e32 v84, vcc, s52, v138
	global_load_dword v86, v[136:137], off offset:576
	s_nop 0
	v_addc_co_u32_e32 v85, vcc, 0, v139, vcc
	s_waitcnt lgkmcnt(0)
	global_load_dwordx4 v[72:75], v[84:85], off
	v_mul_f32_e32 v56, 0xbfb8aa3b, v56
	v_mul_f32_e32 v61, 0xbfb8aa3b, v61
	v_mul_f32_e32 v57, 0xbfb8aa3b, v57
	v_mul_f32_e32 v62, 0xbfb8aa3b, v62
	v_mul_f32_e32 v58, 0xbfb8aa3b, v58
	v_mul_f32_e32 v59, 0xbfb8aa3b, v59
	v_exp_f32_e32 v56, v56
	v_exp_f32_e32 v76, v61
	v_exp_f32_e32 v57, v57
	v_exp_f32_e32 v62, v62
	v_exp_f32_e32 v58, v58
	v_exp_f32_e32 v59, v59
	v_add_co_u32_e32 v66, vcc, s53, v138
	v_mul_f32_e32 v60, 0xbfb8aa3b, v60
	s_nop 0
	v_addc_co_u32_e32 v67, vcc, 0, v139, vcc
	v_exp_f32_e32 v65, v60
	v_add_co_u32_e32 v60, vcc, s54, v138
	v_add_f32_e32 v56, 1.0, v56
	v_add_f32_e32 v76, 1.0, v76
	v_add_f32_e32 v57, 1.0, v57
	v_add_f32_e32 v62, 1.0, v62
	v_add_f32_e32 v58, 1.0, v58
	v_add_f32_e32 v59, 1.0, v59
	v_addc_co_u32_e32 v61, vcc, 0, v139, vcc
	v_rcp_f32_e32 v90, v56
	v_rcp_f32_e32 v89, v76
	v_rcp_f32_e32 v91, v57
	v_rcp_f32_e32 v92, v62
	v_rcp_f32_e32 v94, v58
	v_rcp_f32_e32 v95, v59
	global_load_dwordx4 v[76:79], v[66:67], off
	global_load_dwordx4 v[56:59], v[60:61], off
	global_load_dword v96, v[136:137], off offset:640
	global_load_dword v62, v[136:137], off offset:704
	v_add_f32_e32 v65, 1.0, v65
	v_mul_f32_e32 v36, 0xbfb8aa3b, v36
	v_mul_f32_e32 v32, 0xbfb8aa3b, v32
	v_rcp_f32_e32 v88, v65
	v_exp_f32_e32 v36, v36
	v_exp_f32_e32 v65, v32
	v_mul_f32_e32 v37, 0xbfb8aa3b, v37
	v_mul_f32_e32 v33, 0xbfb8aa3b, v33
	v_mul_f32_e32 v63, 0xbfb8aa3b, v63
	v_add_f32_e32 v32, 1.0, v36
	v_add_f32_e32 v36, 1.0, v65
	v_exp_f32_e32 v37, v37
	v_exp_f32_e32 v65, v33
	v_exp_f32_e32 v63, v63
	v_mul_f32_e32 v38, 0xbfb8aa3b, v38
	v_mul_f32_e32 v34, 0xbfb8aa3b, v34
	v_add_f32_e32 v33, 1.0, v37
	v_add_f32_e32 v37, 1.0, v65
	v_exp_f32_e32 v38, v38
	v_exp_f32_e32 v65, v34
	v_add_f32_e32 v63, 1.0, v63
	v_rcp_f32_e32 v93, v63
	v_mul_f32_e32 v39, 0xbfb8aa3b, v39
	v_mul_f32_e32 v35, 0xbfb8aa3b, v35
	v_add_f32_e32 v34, 1.0, v38
	v_add_f32_e32 v38, 1.0, v65
	v_exp_f32_e32 v39, v39
	v_exp_f32_e32 v65, v35
	v_rcp_f32_e32 v32, v32
	v_rcp_f32_e32 v36, v36
	v_add_f32_e32 v35, 1.0, v39
	v_add_f32_e32 v39, 1.0, v65
	v_rcp_f32_e32 v33, v33
	v_rcp_f32_e32 v37, v37
	v_rcp_f32_e32 v34, v34
	v_rcp_f32_e32 v38, v38
	v_rcp_f32_e32 v35, v35
	s_waitcnt vmcnt(7)
	v_lshlrev_b32_e32 v98, 16, v68
	v_and_b32_e32 v99, 0xffff0000, v68
	v_lshlrev_b32_e32 v68, 16, v69
	v_and_b32_e32 v69, 0xffff0000, v69
	v_lshlrev_b32_e32 v100, 16, v70
	v_and_b32_e32 v101, 0xffff0000, v70
	v_lshlrev_b32_e32 v70, 16, v71
	v_and_b32_e32 v71, 0xffff0000, v71
	s_waitcnt vmcnt(6)
	v_pk_mul_f32 v[68:69], v[82:83], v[68:69] op_sel_hi:[0,1]
	v_pk_mul_f32 v[98:99], v[82:83], v[98:99] op_sel_hi:[0,1]
	v_pk_mul_f32 v[70:71], v[82:83], v[70:71] op_sel_hi:[0,1]
	v_pk_mul_f32 v[82:83], v[82:83], v[100:101] op_sel_hi:[0,1]
	v_pk_fma_f32 v[52:53], v[52:53], v[88:89], v[98:99]
	v_pk_fma_f32 v[82:83], v[48:49], v[90:91], v[82:83]
	v_pk_fma_f32 v[54:55], v[54:55], v[92:93], v[68:69]
	v_pk_fma_f32 v[68:69], v[50:51], v[94:95], v[70:71]
	v_cvt_pk_bf16_f32 v48, v52, v53
	v_cvt_pk_bf16_f32 v49, v54, v55
	v_cvt_pk_bf16_f32 v50, v82, v83
	v_cvt_pk_bf16_f32 v51, v68, v69
	v_pk_mul_f32 v[52:53], v[52:53], v[52:53]
	v_pk_mul_f32 v[54:55], v[54:55], v[54:55]
	v_pk_mul_f32 v[70:71], v[82:83], v[82:83]
	global_store_dwordx4 v[80:81], v[48:51], off nt
	v_rcp_f32_e32 v39, v39
	v_mul_f32_e32 v20, 0xbfb8aa3b, v20
	v_add_f32_e32 v50, v54, v55
	v_add_f32_e32 v51, v52, v53
	v_pk_mul_f32 v[48:49], v[68:69], v[68:69]
	v_add_f32_e32 v50, v51, v50
	v_add_f32_e32 v51, v70, v71
	v_add_f32_e32 v50, v51, v50
	v_add_f32_e32 v48, v48, v49
	v_add_f32_e32 v63, v48, v50
	s_waitcnt vmcnt(5)
	v_lshlrev_b32_e32 v48, 16, v72
	v_and_b32_e32 v49, 0xffff0000, v72
	v_lshlrev_b32_e32 v50, 16, v73
	v_and_b32_e32 v51, 0xffff0000, v73
	v_lshlrev_b32_e32 v52, 16, v74
	v_and_b32_e32 v53, 0xffff0000, v74
	v_lshlrev_b32_e32 v54, 16, v75
	v_and_b32_e32 v55, 0xffff0000, v75
	v_pk_mul_f32 v[50:51], v[86:87], v[50:51] op_sel_hi:[0,1]
	v_pk_mul_f32 v[48:49], v[86:87], v[48:49] op_sel_hi:[0,1]
	v_pk_mul_f32 v[54:55], v[86:87], v[54:55] op_sel_hi:[0,1]
	v_pk_mul_f32 v[52:53], v[86:87], v[52:53] op_sel_hi:[0,1]
	v_pk_fma_f32 v[44:45], v[44:45], v[32:33], v[48:49]
	v_pk_fma_f32 v[36:37], v[40:41], v[36:37], v[52:53]
	v_pk_fma_f32 v[40:41], v[46:47], v[34:35], v[50:51]
	v_pk_fma_f32 v[38:39], v[42:43], v[38:39], v[54:55]
	v_cvt_pk_bf16_f32 v32, v44, v45
	v_cvt_pk_bf16_f32 v33, v40, v41
	v_cvt_pk_bf16_f32 v34, v36, v37
	v_cvt_pk_bf16_f32 v35, v38, v39
	v_mul_f32_e32 v16, 0xbfb8aa3b, v16
	global_store_dwordx4 v[84:85], v[32:35], off nt
	v_exp_f32_e32 v20, v20
	v_mul_f32_e32 v21, 0xbfb8aa3b, v21
	v_pk_mul_f32 v[34:35], v[40:41], v[40:41]
	v_exp_f32_e32 v41, v16
	v_mul_f32_e32 v17, 0xbfb8aa3b, v17
	v_add_f32_e32 v16, 1.0, v20
	v_exp_f32_e32 v21, v21
	v_add_f32_e32 v20, 1.0, v41
	v_exp_f32_e32 v41, v17
	v_mul_f32_e32 v22, 0xbfb8aa3b, v22
	v_mul_f32_e32 v18, 0xbfb8aa3b, v18
	v_add_f32_e32 v17, 1.0, v21
	v_add_f32_e32 v21, 1.0, v41
	v_exp_f32_e32 v22, v22
	v_exp_f32_e32 v41, v18
	v_mul_f32_e32 v23, 0xbfb8aa3b, v23
	v_mul_f32_e32 v19, 0xbfb8aa3b, v19
	v_add_f32_e32 v18, 1.0, v22
	v_add_f32_e32 v22, 1.0, v41
	v_exp_f32_e32 v23, v23
	v_exp_f32_e32 v41, v19
	v_pk_mul_f32 v[32:33], v[44:45], v[44:45]
	v_pk_mul_f32 v[36:37], v[36:37], v[36:37]
	v_add_f32_e32 v34, v34, v35
	v_add_f32_e32 v32, v32, v33
	v_add_f32_e32 v19, 1.0, v23
	v_add_f32_e32 v23, 1.0, v41
	v_pk_mul_f32 v[38:39], v[38:39], v[38:39]
	v_add_f32_e32 v32, v32, v34
	v_add_f32_e32 v33, v36, v37
	v_rcp_f32_e32 v16, v16
	v_rcp_f32_e32 v20, v20
	v_rcp_f32_e32 v17, v17
	v_rcp_f32_e32 v21, v21
	v_rcp_f32_e32 v18, v18
	v_rcp_f32_e32 v22, v22
	v_rcp_f32_e32 v19, v19
	v_rcp_f32_e32 v23, v23
	v_add_f32_e32 v32, v33, v32
	v_add_f32_e32 v33, v38, v39
	v_add_f32_e32 v40, v33, v32
	s_waitcnt vmcnt(5)
	v_lshlrev_b32_e32 v32, 16, v76
	v_and_b32_e32 v33, 0xffff0000, v76
	v_lshlrev_b32_e32 v34, 16, v77
	v_and_b32_e32 v35, 0xffff0000, v77
	v_lshlrev_b32_e32 v36, 16, v78
	v_and_b32_e32 v37, 0xffff0000, v78
	v_lshlrev_b32_e32 v38, 16, v79
	v_and_b32_e32 v39, 0xffff0000, v79
	s_waitcnt vmcnt(3)
	v_pk_mul_f32 v[34:35], v[96:97], v[34:35] op_sel_hi:[0,1]
	v_pk_mul_f32 v[32:33], v[96:97], v[32:33] op_sel_hi:[0,1]
	v_pk_mul_f32 v[38:39], v[96:97], v[38:39] op_sel_hi:[0,1]
	v_pk_mul_f32 v[36:37], v[96:97], v[36:37] op_sel_hi:[0,1]
	v_pk_fma_f32 v[28:29], v[28:29], v[16:17], v[32:33]
	v_pk_fma_f32 v[20:21], v[24:25], v[20:21], v[36:37]
	v_pk_fma_f32 v[24:25], v[30:31], v[18:19], v[34:35]
	v_pk_fma_f32 v[22:23], v[26:27], v[22:23], v[38:39]
	v_cvt_pk_bf16_f32 v16, v28, v29
	v_cvt_pk_bf16_f32 v17, v24, v25
	v_cvt_pk_bf16_f32 v18, v20, v21
	v_cvt_pk_bf16_f32 v19, v22, v23
	v_mul_f32_e32 v4, 0xbfb8aa3b, v4
	v_mul_f32_e32 v0, 0xbfb8aa3b, v0
	global_store_dwordx4 v[66:67], v[16:19], off nt
	v_exp_f32_e32 v4, v4
	v_mul_f32_e32 v5, 0xbfb8aa3b, v5
	v_pk_mul_f32 v[18:19], v[24:25], v[24:25]
	v_exp_f32_e32 v25, v0
	v_mul_f32_e32 v1, 0xbfb8aa3b, v1
	v_add_f32_e32 v0, 1.0, v4
	v_exp_f32_e32 v5, v5
	v_add_f32_e32 v4, 1.0, v25
	v_exp_f32_e32 v25, v1
	v_mul_f32_e32 v6, 0xbfb8aa3b, v6
	v_mul_f32_e32 v2, 0xbfb8aa3b, v2
	v_add_f32_e32 v1, 1.0, v5
	v_add_f32_e32 v5, 1.0, v25
	v_exp_f32_e32 v6, v6
	v_exp_f32_e32 v25, v2
	v_mul_f32_e32 v7, 0xbfb8aa3b, v7
	v_exp_f32_e32 v7, v7
	v_mul_f32_e32 v3, 0xbfb8aa3b, v3
	v_add_f32_e32 v2, 1.0, v6
	v_add_f32_e32 v6, 1.0, v25
	v_exp_f32_e32 v25, v3
	v_pk_mul_f32 v[16:17], v[28:29], v[28:29]
	v_pk_mul_f32 v[20:21], v[20:21], v[20:21]
	v_add_f32_e32 v18, v18, v19
	v_add_f32_e32 v16, v16, v17
	v_add_f32_e32 v3, 1.0, v7
	v_pk_mul_f32 v[22:23], v[22:23], v[22:23]
	v_add_f32_e32 v16, v16, v18
	v_add_f32_e32 v17, v20, v21
	v_rcp_f32_e32 v0, v0
	v_rcp_f32_e32 v1, v1
	v_rcp_f32_e32 v2, v2
	v_rcp_f32_e32 v3, v3
	v_add_f32_e32 v7, 1.0, v25
	v_add_f32_e32 v16, v17, v16
	v_add_f32_e32 v17, v22, v23
	v_rcp_f32_e32 v4, v4
	v_rcp_f32_e32 v5, v5
	v_rcp_f32_e32 v6, v6
	v_rcp_f32_e32 v7, v7
	v_add_f32_e32 v24, v17, v16
	v_lshlrev_b32_e32 v16, 16, v56
	v_and_b32_e32 v17, 0xffff0000, v56
	v_lshlrev_b32_e32 v18, 16, v57
	v_and_b32_e32 v19, 0xffff0000, v57
	v_lshlrev_b32_e32 v20, 16, v58
	v_and_b32_e32 v21, 0xffff0000, v58
	v_lshlrev_b32_e32 v22, 16, v59
	v_and_b32_e32 v23, 0xffff0000, v59
	s_waitcnt vmcnt(3)
	v_pk_mul_f32 v[18:19], v[62:63], v[18:19] op_sel_hi:[0,1]
	v_pk_mul_f32 v[16:17], v[62:63], v[16:17] op_sel_hi:[0,1]
	v_pk_mul_f32 v[22:23], v[62:63], v[22:23] op_sel_hi:[0,1]
	v_pk_mul_f32 v[20:21], v[62:63], v[20:21] op_sel_hi:[0,1]
	v_pk_fma_f32 v[0:1], v[12:13], v[0:1], v[16:17]
	v_pk_fma_f32 v[14:15], v[14:15], v[2:3], v[18:19]
	v_pk_fma_f32 v[12:13], v[8:9], v[4:5], v[20:21]
	v_pk_fma_f32 v[16:17], v[10:11], v[6:7], v[22:23]
	v_cvt_pk_bf16_f32 v10, v0, v1
	v_pk_mul_f32 v[0:1], v[0:1], v[0:1]
	v_pk_mul_f32 v[2:3], v[14:15], v[14:15]
	v_pk_mul_f32 v[4:5], v[12:13], v[12:13]
	v_add_f32_e32 v2, v2, v3
	v_add_f32_e32 v0, v0, v1
	v_pk_mul_f32 v[6:7], v[16:17], v[16:17]
	v_add_f32_e32 v0, v0, v2
	v_add_f32_e32 v1, v4, v5
	v_add_f32_e32 v0, v1, v0
	v_add_f32_e32 v1, v6, v7
	v_add_f32_e32 v0, v1, v0
	ds_bpermute_b32 v2, v163, v63
	ds_bpermute_b32 v1, v163, v40
	ds_bpermute_b32 v5, v163, v24
	ds_bpermute_b32 v7, v163, v0
	v_cvt_pk_bf16_f32 v11, v14, v15
	s_waitcnt lgkmcnt(3)
	v_add_f32_e32 v3, v63, v2
	s_waitcnt lgkmcnt(2)
	v_add_f32_e32 v1, v40, v1
	s_waitcnt lgkmcnt(1)
	v_add_f32_e32 v5, v24, v5
	s_waitcnt lgkmcnt(0)
	v_add_f32_e32 v7, v0, v7
	ds_bpermute_b32 v4, v127, v3
	ds_bpermute_b32 v2, v127, v1
	ds_bpermute_b32 v6, v127, v5
	ds_bpermute_b32 v8, v127, v7
	v_cvt_pk_bf16_f32 v12, v12, v13
	v_cvt_pk_bf16_f32 v13, v16, v17
	v_cmp_lt_i32_e32 vcc, 0, v171
	global_store_dwordx4 v[60:61], v[10:13], off nt
	s_and_saveexec_b64 s[2:3], vcc
	s_xor_b64 s[2:3], exec, s[2:3]
	s_cbranch_execz .LBB0_288
	v_cmp_ne_u32_e32 vcc, 1, v171
	s_and_saveexec_b64 s[14:15], vcc
	s_xor_b64 s[14:15], exec, s[14:15]
	s_cbranch_execz .LBB0_285
	s_waitcnt lgkmcnt(0)
	v_add_f32_e32 v0, v7, v8
	v_add_f32_e32 v1, v5, v6
	v_cndmask_b32_e64 v0, v0, v1, s[0:1]

.LBB0_371:
	v_lshl_add_u32 v136, s4, 8, v138
	v_ashrrev_i32_e32 v137, 31, v136
	v_lshl_add_u64 v[162:163], v[136:137], 3, s[62:63]
	global_load_dwordx2 v[164:165], v[162:163], off
	global_load_dwordx2 v[166:167], v[162:163], off offset:128
	v_lshl_or_b32 v168, s5, 7, v153
	v_pk_mul_f32 v[188:189], v[108:109], v[120:121]
	v_mov_b64_e32 v[120:121], s[16:17]
	v_ashrrev_i32_e32 v169, 31, v168
	v_pk_mul_f32 v[192:193], v[104:105], v[116:117]
	v_or_b32_e32 v161, 16, v136
	v_or_b32_e32 v199, 32, v136
	v_or_b32_e32 v200, 48, v136
	v_add_u32_e32 v201, 0x80, v136
	v_add_u32_e32 v160, 0x90, v136
	v_add_u32_e32 v159, 0xa0, v136
	v_add_u32_e32 v158, 0xb0, v136
	v_mad_i64_i32 v[196:197], s[2:3], v136, s49, v[120:121]
	v_lshlrev_b64 v[116:117], 1, v[168:169]
	global_load_dwordx2 v[168:169], v[162:163], off offset:256
	global_load_dwordx2 v[136:137], v[162:163], off offset:384
	v_pk_mul_f32 v[190:191], v[106:107], v[118:119]
	v_pk_mul_f32 v[184:185], v[112:113], v[124:125]
	v_pk_mul_f32 v[186:187], v[110:111], v[122:123]
	v_pk_mul_f32 v[182:183], v[114:115], v[126:127]
	v_pk_mul_f32 v[96:97], v[100:101], v[96:97]
	v_pk_mul_f32 v[98:99], v[102:103], v[98:99]
	v_pk_mul_f32 v[88:89], v[92:93], v[88:89]
	v_pk_mul_f32 v[90:91], v[94:95], v[90:91]
	v_pk_mul_f32 v[80:81], v[84:85], v[80:81]
	v_pk_mul_f32 v[82:83], v[86:87], v[82:83]
	v_pk_mul_f32 v[72:73], v[76:77], v[72:73]
	v_pk_mul_f32 v[74:75], v[78:79], v[74:75]
	v_pk_mul_f32 v[64:65], v[68:69], v[64:65]
	v_pk_mul_f32 v[66:67], v[70:71], v[66:67]
	v_pk_mul_f32 v[56:57], v[60:61], v[56:57]
	v_pk_mul_f32 v[58:59], v[62:63], v[58:59]
	v_pk_mul_f32 v[48:49], v[52:53], v[48:49]
	v_pk_mul_f32 v[50:51], v[54:55], v[50:51]
	v_pk_mul_f32 v[40:41], v[44:45], v[40:41]
	v_pk_mul_f32 v[42:43], v[46:47], v[42:43]
	v_pk_mul_f32 v[32:33], v[36:37], v[32:33]
	v_pk_mul_f32 v[34:35], v[38:39], v[34:35]
	v_pk_mul_f32 v[24:25], v[28:29], v[24:25]
	v_pk_mul_f32 v[26:27], v[30:31], v[26:27]
	v_pk_mul_f32 v[16:17], v[20:21], v[16:17]
	v_pk_mul_f32 v[18:19], v[22:23], v[18:19]
	v_pk_mul_f32 v[8:9], v[12:13], v[8:9]
	v_pk_mul_f32 v[10:11], v[14:15], v[10:11]
	v_pk_mul_f32 v[0:1], v[4:5], v[0:1]
	v_pk_mul_f32 v[2:3], v[6:7], v[2:3]
	s_waitcnt vmcnt(0)
	v_ffbh_u32_e32 v118, v165
	v_ffbh_u32_e32 v119, v167
	v_min_u32_e32 v124, 32, v118
	v_min_u32_e32 v125, 32, v119
	v_lshlrev_b64 v[118:119], v124, v[164:165]
	v_lshlrev_b64 v[122:123], v125, v[166:167]
	v_min_u32_e32 v118, 1, v118
	v_min_u32_e32 v122, 1, v122
	v_or_b32_e32 v118, v119, v118
	v_or_b32_e32 v119, v123, v122
	v_cvt_f32_u32_e32 v118, v118
	v_cvt_f32_u32_e32 v119, v119
	v_sub_u32_e32 v122, 32, v124
	v_sub_u32_e32 v123, 32, v125
	v_ldexp_f32 v118, v118, v122
	v_ldexp_f32 v119, v119, v123
	v_fmamk_f32 v118, v118, 0x30800000, v157
	v_fmamk_f32 v119, v119, 0x30800000, v157
	v_rsq_f32_e32 v164, v118
	v_rsq_f32_e32 v165, v119
	global_load_dwordx2 v[126:127], v[162:163], off offset:1024
	global_load_dwordx2 v[124:125], v[162:163], off offset:1152
	global_load_dwordx2 v[122:123], v[162:163], off offset:1280
	global_load_dwordx2 v[118:119], v[162:163], off offset:1408
	v_mov_b32_e32 v166, v164
	v_mul_f32_e32 v164, 0xbfb8aa3b, v166
	v_lshl_add_u64 v[162:163], v[196:197], 0, v[116:117]
	v_mul_f32_e32 v196, 0xbfb8aa3b, v165
	v_pk_mul_f32 v[112:113], v[112:113], v[164:165] op_sel_hi:[1,0]
	v_pk_mul_f32 v[114:115], v[114:115], v[164:165] op_sel_hi:[1,0]
	v_pk_mul_f32 v[108:109], v[108:109], v[164:165] op_sel_hi:[1,0]
	v_pk_mul_f32 v[110:111], v[110:111], v[164:165] op_sel_hi:[1,0]
	v_pk_mul_f32 v[104:105], v[104:105], v[196:197] op_sel_hi:[1,0]
	v_exp_f32_e32 v112, v112
	v_exp_f32_e32 v113, v113
	v_exp_f32_e32 v114, v114
	v_exp_f32_e32 v115, v115
	v_exp_f32_e32 v108, v108
	v_exp_f32_e32 v109, v109
	v_exp_f32_e32 v110, v110
	v_exp_f32_e32 v111, v111
	v_exp_f32_e32 v104, v104
	v_exp_f32_e32 v105, v105
	v_pk_mul_f32 v[106:107], v[106:107], v[196:197] op_sel_hi:[1,0]
	v_pk_add_f32 v[112:113], v[112:113], 1.0 op_sel_hi:[1,0]
	v_exp_f32_e32 v106, v106
	v_exp_f32_e32 v107, v107
	v_pk_add_f32 v[114:115], v[114:115], 1.0 op_sel_hi:[1,0]
	v_pk_add_f32 v[108:109], v[108:109], 1.0 op_sel_hi:[1,0]
	v_pk_add_f32 v[110:111], v[110:111], 1.0 op_sel_hi:[1,0]
	v_pk_add_f32 v[104:105], v[104:105], 1.0 op_sel_hi:[1,0]
	v_rcp_f32_e32 v112, v112
	v_rcp_f32_e32 v113, v113
	v_rcp_f32_e32 v114, v114
	v_rcp_f32_e32 v115, v115
	v_rcp_f32_e32 v108, v108
	v_rcp_f32_e32 v109, v109
	v_rcp_f32_e32 v110, v110
	v_rcp_f32_e32 v111, v111
	v_rcp_f32_e32 v104, v104
	v_rcp_f32_e32 v105, v105
	v_mul_f32_e32 v166, v166, v166
	v_pk_add_f32 v[106:107], v[106:107], 1.0 op_sel_hi:[1,0]
	v_mul_f32_e32 v198, v165, v165
	v_rcp_f32_e32 v164, v106
	v_rcp_f32_e32 v165, v107
	v_pk_mul_f32 v[106:107], v[166:167], v[112:113] op_sel_hi:[0,1]
	v_pk_mul_f32 v[112:113], v[166:167], v[114:115] op_sel_hi:[0,1]
	v_pk_mul_f32 v[108:109], v[166:167], v[108:109] op_sel_hi:[0,1]
	v_pk_mul_f32 v[110:111], v[166:167], v[110:111] op_sel_hi:[0,1]
	v_pk_mul_f32 v[104:105], v[198:199], v[104:105] op_sel_hi:[0,1]
	v_pk_mul_f32 v[106:107], v[184:185], v[106:107]
	v_pk_mul_f32 v[112:113], v[182:183], v[112:113]
	v_pk_mul_f32 v[108:109], v[188:189], v[108:109]
	v_pk_mul_f32 v[110:111], v[186:187], v[110:111]
	v_pk_mul_f32 v[114:115], v[192:193], v[104:105]
	v_cvt_pk_bf16_f32 v104, v106, v107
	v_cvt_pk_bf16_f32 v105, v112, v113
	v_cvt_pk_bf16_f32 v106, v108, v109
	v_cvt_pk_bf16_f32 v107, v110, v111
	global_store_dwordx4 v[162:163], v[104:107], off nt
	v_cvt_pk_bf16_f32 v108, v114, v115
	s_nop 0
	v_pk_mul_f32 v[104:105], v[100:101], v[196:197] op_sel_hi:[1,0]
	v_pk_mul_f32 v[100:101], v[102:103], v[196:197] op_sel_hi:[1,0]
	v_exp_f32_e32 v104, v104
	v_exp_f32_e32 v105, v105
	v_exp_f32_e32 v100, v100
	v_exp_f32_e32 v101, v101
	v_pk_mul_f32 v[106:107], v[198:199], v[164:165] op_sel_hi:[0,1]
	v_pk_add_f32 v[104:105], v[104:105], 1.0 op_sel_hi:[1,0]
	v_pk_mul_f32 v[106:107], v[190:191], v[106:107]
	v_rcp_f32_e32 v104, v104
	v_rcp_f32_e32 v105, v105
	v_cvt_pk_bf16_f32 v109, v106, v107
	v_pk_mul_f32 v[102:103], v[198:199], v[104:105] op_sel_hi:[0,1]
	v_pk_mul_f32 v[96:97], v[96:97], v[102:103]
	s_nop 0
	v_cvt_pk_bf16_f32 v110, v96, v97
	v_pk_add_f32 v[96:97], v[100:101], 1.0 op_sel_hi:[1,0]
	v_ffbh_u32_e32 v100, v169
	v_min_u32_e32 v102, 32, v100
	v_lshlrev_b64 v[100:101], v102, v[168:169]
	v_rcp_f32_e32 v96, v96
	v_rcp_f32_e32 v97, v97
	v_min_u32_e32 v100, 1, v100
	v_or_b32_e32 v100, v101, v100
	v_cvt_f32_u32_e32 v100, v100
	v_pk_mul_f32 v[96:97], v[198:199], v[96:97] op_sel_hi:[0,1]
	v_pk_mul_f32 v[96:97], v[98:99], v[96:97]
	v_sub_u32_e32 v98, 32, v102
	v_ldexp_f32 v98, v100, v98
	v_fmamk_f32 v98, v98, 0x30800000, v157
	v_cvt_pk_bf16_f32 v111, v96, v97
	v_mad_i64_i32 v[96:97], s[2:3], v161, s49, v[120:121]
	v_rsq_f32_e32 v98, v98
	v_lshl_add_u64 v[96:97], v[96:97], 0, v[116:117]
	global_store_dwordx4 v[96:97], v[108:111], off nt
	v_mov_b32_e32 v99, v98
	v_mul_f32_e32 v98, 0xbfb8aa3b, v99
	v_pk_mul_f32 v[100:101], v[92:93], v[98:99] op_sel_hi:[1,0]
	v_pk_mul_f32 v[92:93], v[94:95], v[98:99] op_sel_hi:[1,0]
	v_exp_f32_e32 v100, v100
	v_exp_f32_e32 v101, v101
	v_exp_f32_e32 v92, v92
	v_exp_f32_e32 v93, v93
	v_mul_f32_e32 v96, v99, v99
	v_pk_add_f32 v[100:101], v[100:101], 1.0 op_sel_hi:[1,0]
	v_pk_add_f32 v[92:93], v[92:93], 1.0 op_sel_hi:[1,0]
	v_rcp_f32_e32 v100, v100
	v_rcp_f32_e32 v101, v101
	v_rcp_f32_e32 v92, v92
	v_rcp_f32_e32 v93, v93
	v_pk_mul_f32 v[94:95], v[96:97], v[100:101] op_sel_hi:[0,1]
	v_pk_mul_f32 v[88:89], v[88:89], v[94:95]
	v_pk_mul_f32 v[94:95], v[84:85], v[98:99] op_sel_hi:[1,0]
	v_pk_mul_f32 v[92:93], v[96:97], v[92:93] op_sel_hi:[0,1]
	v_exp_f32_e32 v94, v94
	v_exp_f32_e32 v95, v95
	v_pk_mul_f32 v[90:91], v[90:91], v[92:93]
	v_cvt_pk_bf16_f32 v88, v88, v89
	v_cvt_pk_bf16_f32 v89, v90, v91
	v_pk_add_f32 v[90:91], v[94:95], 1.0 op_sel_hi:[1,0]
	v_pk_mul_f32 v[84:85], v[86:87], v[98:99] op_sel_hi:[1,0]
	v_rcp_f32_e32 v90, v90
	v_rcp_f32_e32 v91, v91
	v_exp_f32_e32 v84, v84
	v_exp_f32_e32 v85, v85
	v_pk_mul_f32 v[86:87], v[96:97], v[90:91] op_sel_hi:[0,1]
	v_pk_mul_f32 v[80:81], v[80:81], v[86:87]
	s_nop 0
	v_cvt_pk_bf16_f32 v90, v80, v81
	v_pk_add_f32 v[80:81], v[84:85], 1.0 op_sel_hi:[1,0]
	v_ffbh_u32_e32 v84, v137
	v_min_u32_e32 v86, 32, v84
	v_lshlrev_b64 v[84:85], v86, v[136:137]
	v_rcp_f32_e32 v80, v80
	v_rcp_f32_e32 v81, v81
	v_min_u32_e32 v84, 1, v84
	v_or_b32_e32 v84, v85, v84
	v_cvt_f32_u32_e32 v84, v84
	v_pk_mul_f32 v[80:81], v[96:97], v[80:81] op_sel_hi:[0,1]
	v_pk_mul_f32 v[80:81], v[82:83], v[80:81]
	v_sub_u32_e32 v82, 32, v86
	v_ldexp_f32 v82, v84, v82
	v_fmamk_f32 v82, v82, 0x30800000, v157
	v_cvt_pk_bf16_f32 v91, v80, v81
	v_mad_i64_i32 v[80:81], s[2:3], v199, s49, v[120:121]
	v_rsq_f32_e32 v82, v82
	v_lshl_add_u64 v[80:81], v[80:81], 0, v[116:117]
	global_store_dwordx4 v[80:81], v[88:91], off nt
	v_mov_b32_e32 v83, v82
	v_mul_f32_e32 v82, 0xbfb8aa3b, v83
	v_pk_mul_f32 v[84:85], v[76:77], v[82:83] op_sel_hi:[1,0]
	v_pk_mul_f32 v[76:77], v[78:79], v[82:83] op_sel_hi:[1,0]
	v_exp_f32_e32 v84, v84
	v_exp_f32_e32 v85, v85
	v_exp_f32_e32 v76, v76
	v_exp_f32_e32 v77, v77
	v_mul_f32_e32 v80, v83, v83
	v_pk_add_f32 v[84:85], v[84:85], 1.0 op_sel_hi:[1,0]
	v_pk_add_f32 v[76:77], v[76:77], 1.0 op_sel_hi:[1,0]
	v_rcp_f32_e32 v84, v84
	v_rcp_f32_e32 v85, v85
	v_rcp_f32_e32 v76, v76
	v_rcp_f32_e32 v77, v77
	v_pk_mul_f32 v[78:79], v[80:81], v[84:85] op_sel_hi:[0,1]
	v_pk_mul_f32 v[72:73], v[72:73], v[78:79]
	v_pk_mul_f32 v[78:79], v[68:69], v[82:83] op_sel_hi:[1,0]
	v_pk_mul_f32 v[76:77], v[80:81], v[76:77] op_sel_hi:[0,1]
	v_exp_f32_e32 v78, v78
	v_exp_f32_e32 v79, v79
	v_pk_mul_f32 v[74:75], v[74:75], v[76:77]
	v_cvt_pk_bf16_f32 v72, v72, v73
	v_cvt_pk_bf16_f32 v73, v74, v75
	v_pk_add_f32 v[74:75], v[78:79], 1.0 op_sel_hi:[1,0]
	v_pk_mul_f32 v[68:69], v[70:71], v[82:83] op_sel_hi:[1,0]
	v_rcp_f32_e32 v74, v74
	v_rcp_f32_e32 v75, v75
	v_exp_f32_e32 v68, v68
	v_exp_f32_e32 v69, v69
	v_pk_mul_f32 v[70:71], v[80:81], v[74:75] op_sel_hi:[0,1]
	v_pk_mul_f32 v[64:65], v[64:65], v[70:71]
	s_nop 0
	v_cvt_pk_bf16_f32 v74, v64, v65
	v_pk_add_f32 v[64:65], v[68:69], 1.0 op_sel_hi:[1,0]
	s_waitcnt vmcnt(6)
	v_ffbh_u32_e32 v68, v127
	v_min_u32_e32 v70, 32, v68
	v_lshlrev_b64 v[68:69], v70, v[126:127]
	v_rcp_f32_e32 v64, v64
	v_rcp_f32_e32 v65, v65
	v_min_u32_e32 v68, 1, v68
	v_or_b32_e32 v68, v69, v68
	v_cvt_f32_u32_e32 v68, v68
	v_pk_mul_f32 v[64:65], v[80:81], v[64:65] op_sel_hi:[0,1]
	v_pk_mul_f32 v[64:65], v[66:67], v[64:65]
	v_sub_u32_e32 v66, 32, v70
	v_ldexp_f32 v66, v68, v66
	v_fmamk_f32 v66, v66, 0x30800000, v157
	v_cvt_pk_bf16_f32 v75, v64, v65
	v_mad_i64_i32 v[64:65], s[2:3], v200, s49, v[120:121]
	v_rsq_f32_e32 v66, v66
	v_lshl_add_u64 v[64:65], v[64:65], 0, v[116:117]
	global_store_dwordx4 v[64:65], v[72:75], off nt
	v_mov_b32_e32 v67, v66
	v_mul_f32_e32 v66, 0xbfb8aa3b, v67
	v_pk_mul_f32 v[68:69], v[60:61], v[66:67] op_sel_hi:[1,0]
	v_pk_mul_f32 v[60:61], v[62:63], v[66:67] op_sel_hi:[1,0]
	v_exp_f32_e32 v68, v68
	v_exp_f32_e32 v69, v69
	v_exp_f32_e32 v60, v60
	v_exp_f32_e32 v61, v61
	v_mul_f32_e32 v64, v67, v67
	v_pk_add_f32 v[68:69], v[68:69], 1.0 op_sel_hi:[1,0]
	v_pk_add_f32 v[60:61], v[60:61], 1.0 op_sel_hi:[1,0]
	v_rcp_f32_e32 v68, v68
	v_rcp_f32_e32 v69, v69
	v_rcp_f32_e32 v60, v60
	v_rcp_f32_e32 v61, v61
	v_pk_mul_f32 v[62:63], v[64:65], v[68:69] op_sel_hi:[0,1]
	v_pk_mul_f32 v[56:57], v[56:57], v[62:63]
	v_pk_mul_f32 v[62:63], v[52:53], v[66:67] op_sel_hi:[1,0]
	v_pk_mul_f32 v[60:61], v[64:65], v[60:61] op_sel_hi:[0,1]
	v_exp_f32_e32 v62, v62
	v_exp_f32_e32 v63, v63
	v_pk_mul_f32 v[58:59], v[58:59], v[60:61]
	v_cvt_pk_bf16_f32 v56, v56, v57
	v_cvt_pk_bf16_f32 v57, v58, v59
	v_pk_add_f32 v[58:59], v[62:63], 1.0 op_sel_hi:[1,0]
	v_pk_mul_f32 v[52:53], v[54:55], v[66:67] op_sel_hi:[1,0]
	v_rcp_f32_e32 v58, v58
	v_rcp_f32_e32 v59, v59
	v_exp_f32_e32 v52, v52
	v_exp_f32_e32 v53, v53
	v_pk_mul_f32 v[54:55], v[64:65], v[58:59] op_sel_hi:[0,1]
	v_pk_mul_f32 v[48:49], v[48:49], v[54:55]
	s_nop 0
	v_cvt_pk_bf16_f32 v58, v48, v49
	v_pk_add_f32 v[48:49], v[52:53], 1.0 op_sel_hi:[1,0]
	s_waitcnt vmcnt(6)
	v_ffbh_u32_e32 v52, v125
	v_min_u32_e32 v54, 32, v52
	v_lshlrev_b64 v[52:53], v54, v[124:125]
	v_rcp_f32_e32 v48, v48
	v_rcp_f32_e32 v49, v49
	v_min_u32_e32 v52, 1, v52
	v_or_b32_e32 v52, v53, v52
	v_cvt_f32_u32_e32 v52, v52
	v_pk_mul_f32 v[48:49], v[64:65], v[48:49] op_sel_hi:[0,1]
	v_pk_mul_f32 v[48:49], v[50:51], v[48:49]
	v_sub_u32_e32 v50, 32, v54
	v_ldexp_f32 v50, v52, v50
	v_fmamk_f32 v50, v50, 0x30800000, v157
	v_cvt_pk_bf16_f32 v59, v48, v49
	v_mad_i64_i32 v[48:49], s[2:3], v201, s49, v[120:121]
	v_rsq_f32_e32 v50, v50
	v_lshl_add_u64 v[48:49], v[48:49], 0, v[116:117]
	global_store_dwordx4 v[48:49], v[56:59], off nt
	v_mov_b32_e32 v51, v50
	v_mul_f32_e32 v50, 0xbfb8aa3b, v51
	v_pk_mul_f32 v[52:53], v[44:45], v[50:51] op_sel_hi:[1,0]
	v_pk_mul_f32 v[44:45], v[46:47], v[50:51] op_sel_hi:[1,0]
	v_exp_f32_e32 v52, v52
	v_exp_f32_e32 v53, v53
	v_exp_f32_e32 v44, v44
	v_exp_f32_e32 v45, v45
	v_mul_f32_e32 v48, v51, v51
	v_pk_add_f32 v[52:53], v[52:53], 1.0 op_sel_hi:[1,0]
	v_pk_add_f32 v[44:45], v[44:45], 1.0 op_sel_hi:[1,0]
	v_rcp_f32_e32 v52, v52
	v_rcp_f32_e32 v53, v53
	v_rcp_f32_e32 v44, v44
	v_rcp_f32_e32 v45, v45
	v_pk_mul_f32 v[46:47], v[48:49], v[52:53] op_sel_hi:[0,1]
	v_pk_mul_f32 v[40:41], v[40:41], v[46:47]
	v_pk_mul_f32 v[46:47], v[36:37], v[50:51] op_sel_hi:[1,0]
	v_pk_mul_f32 v[44:45], v[48:49], v[44:45] op_sel_hi:[0,1]
	v_exp_f32_e32 v46, v46
	v_exp_f32_e32 v47, v47
	v_pk_mul_f32 v[42:43], v[42:43], v[44:45]
	v_cvt_pk_bf16_f32 v40, v40, v41
	v_cvt_pk_bf16_f32 v41, v42, v43
	v_pk_add_f32 v[42:43], v[46:47], 1.0 op_sel_hi:[1,0]
	v_pk_mul_f32 v[36:37], v[38:39], v[50:51] op_sel_hi:[1,0]
	v_rcp_f32_e32 v42, v42
	v_rcp_f32_e32 v43, v43
	v_exp_f32_e32 v36, v36
	v_exp_f32_e32 v37, v37
	v_pk_mul_f32 v[38:39], v[48:49], v[42:43] op_sel_hi:[0,1]
	v_pk_mul_f32 v[32:33], v[32:33], v[38:39]
	s_nop 0
	v_cvt_pk_bf16_f32 v42, v32, v33
	v_pk_add_f32 v[32:33], v[36:37], 1.0 op_sel_hi:[1,0]
	s_waitcnt vmcnt(6)
	v_ffbh_u32_e32 v36, v123
	v_min_u32_e32 v38, 32, v36
	v_lshlrev_b64 v[36:37], v38, v[122:123]
	v_rcp_f32_e32 v32, v32
	v_rcp_f32_e32 v33, v33
	v_min_u32_e32 v36, 1, v36
	v_or_b32_e32 v36, v37, v36
	v_cvt_f32_u32_e32 v36, v36
	v_pk_mul_f32 v[32:33], v[48:49], v[32:33] op_sel_hi:[0,1]
	v_pk_mul_f32 v[32:33], v[34:35], v[32:33]
	v_sub_u32_e32 v34, 32, v38
	v_ldexp_f32 v34, v36, v34
	v_fmamk_f32 v34, v34, 0x30800000, v157
	v_cvt_pk_bf16_f32 v43, v32, v33
	v_mad_i64_i32 v[32:33], s[2:3], v160, s49, v[120:121]
	v_rsq_f32_e32 v34, v34
	v_lshl_add_u64 v[32:33], v[32:33], 0, v[116:117]
	global_store_dwordx4 v[32:33], v[40:43], off nt
	v_mov_b32_e32 v35, v34
	v_mul_f32_e32 v34, 0xbfb8aa3b, v35
	v_pk_mul_f32 v[36:37], v[28:29], v[34:35] op_sel_hi:[1,0]
	v_pk_mul_f32 v[28:29], v[30:31], v[34:35] op_sel_hi:[1,0]
	v_exp_f32_e32 v36, v36
	v_exp_f32_e32 v37, v37
	v_exp_f32_e32 v28, v28
	v_exp_f32_e32 v29, v29
	v_mul_f32_e32 v32, v35, v35
	v_pk_add_f32 v[36:37], v[36:37], 1.0 op_sel_hi:[1,0]
	v_pk_add_f32 v[28:29], v[28:29], 1.0 op_sel_hi:[1,0]
	v_rcp_f32_e32 v36, v36
	v_rcp_f32_e32 v37, v37
	v_rcp_f32_e32 v28, v28
	v_rcp_f32_e32 v29, v29
	v_pk_mul_f32 v[30:31], v[32:33], v[36:37] op_sel_hi:[0,1]
	v_pk_mul_f32 v[24:25], v[24:25], v[30:31]
	v_pk_mul_f32 v[30:31], v[20:21], v[34:35] op_sel_hi:[1,0]
	v_pk_mul_f32 v[28:29], v[32:33], v[28:29] op_sel_hi:[0,1]
	v_exp_f32_e32 v30, v30
	v_exp_f32_e32 v31, v31
	v_pk_mul_f32 v[26:27], v[26:27], v[28:29]
	v_cvt_pk_bf16_f32 v24, v24, v25
	v_cvt_pk_bf16_f32 v25, v26, v27
	v_pk_add_f32 v[26:27], v[30:31], 1.0 op_sel_hi:[1,0]
	v_pk_mul_f32 v[20:21], v[22:23], v[34:35] op_sel_hi:[1,0]
	v_rcp_f32_e32 v26, v26
	v_rcp_f32_e32 v27, v27
	v_exp_f32_e32 v20, v20
	v_exp_f32_e32 v21, v21
	v_pk_mul_f32 v[22:23], v[32:33], v[26:27] op_sel_hi:[0,1]
	v_pk_mul_f32 v[16:17], v[16:17], v[22:23]
	s_nop 0
	v_cvt_pk_bf16_f32 v26, v16, v17
	v_pk_add_f32 v[16:17], v[20:21], 1.0 op_sel_hi:[1,0]
	s_waitcnt vmcnt(6)
	v_ffbh_u32_e32 v20, v119
	v_min_u32_e32 v22, 32, v20
	v_lshlrev_b64 v[20:21], v22, v[118:119]
	v_rcp_f32_e32 v16, v16
	v_rcp_f32_e32 v17, v17
	v_min_u32_e32 v20, 1, v20
	v_or_b32_e32 v20, v21, v20
	v_cvt_f32_u32_e32 v20, v20
	v_pk_mul_f32 v[16:17], v[32:33], v[16:17] op_sel_hi:[0,1]
	v_pk_mul_f32 v[16:17], v[18:19], v[16:17]
	v_sub_u32_e32 v18, 32, v22
	v_ldexp_f32 v18, v20, v18
	v_fmamk_f32 v18, v18, 0x30800000, v157
	v_cvt_pk_bf16_f32 v27, v16, v17
	v_mad_i64_i32 v[16:17], s[2:3], v159, s49, v[120:121]
	v_rsq_f32_e32 v18, v18
	v_lshl_add_u64 v[16:17], v[16:17], 0, v[116:117]
	global_store_dwordx4 v[16:17], v[24:27], off nt
	v_mov_b32_e32 v19, v18
	v_mul_f32_e32 v18, 0xbfb8aa3b, v19
	v_pk_mul_f32 v[20:21], v[12:13], v[18:19] op_sel_hi:[1,0]
	v_pk_mul_f32 v[12:13], v[14:15], v[18:19] op_sel_hi:[1,0]
	v_exp_f32_e32 v20, v20
	v_exp_f32_e32 v21, v21
	v_exp_f32_e32 v12, v12
	v_exp_f32_e32 v13, v13
	v_mul_f32_e32 v16, v19, v19
	v_pk_add_f32 v[20:21], v[20:21], 1.0 op_sel_hi:[1,0]
	s_andn2_b64 vcc, exec, s[0:1]
	v_rcp_f32_e32 v20, v20
	v_rcp_f32_e32 v21, v21
	v_pk_add_f32 v[12:13], v[12:13], 1.0 op_sel_hi:[1,0]
	s_mov_b64 s[0:1], -1
	v_rcp_f32_e32 v12, v12
	v_rcp_f32_e32 v13, v13
	v_pk_mul_f32 v[14:15], v[16:17], v[20:21] op_sel_hi:[0,1]
	v_pk_mul_f32 v[8:9], v[8:9], v[14:15]
	v_pk_mul_f32 v[14:15], v[4:5], v[18:19] op_sel_hi:[1,0]
	v_pk_mul_f32 v[12:13], v[16:17], v[12:13] op_sel_hi:[0,1]
	v_exp_f32_e32 v14, v14
	v_exp_f32_e32 v15, v15
	v_pk_mul_f32 v[10:11], v[10:11], v[12:13]
	v_pk_mul_f32 v[12:13], v[6:7], v[18:19] op_sel_hi:[1,0]
	v_cvt_pk_bf16_f32 v8, v8, v9
	v_exp_f32_e32 v12, v12
	v_exp_f32_e32 v13, v13
	v_cvt_pk_bf16_f32 v9, v10, v11
	v_pk_add_f32 v[10:11], v[14:15], 1.0 op_sel_hi:[1,0]
	v_pk_add_f32 v[4:5], v[12:13], 1.0 op_sel_hi:[1,0]
	v_rcp_f32_e32 v10, v10
	v_rcp_f32_e32 v11, v11
	v_rcp_f32_e32 v4, v4
	v_rcp_f32_e32 v5, v5
	v_pk_mul_f32 v[6:7], v[16:17], v[10:11] op_sel_hi:[0,1]
	v_pk_mul_f32 v[0:1], v[0:1], v[6:7]
	s_nop 0
	v_cvt_pk_bf16_f32 v10, v0, v1
	v_pk_mul_f32 v[0:1], v[16:17], v[4:5] op_sel_hi:[0,1]
	v_pk_mul_f32 v[0:1], v[2:3], v[0:1]
	s_nop 0
	v_cvt_pk_bf16_f32 v11, v0, v1
	v_mad_i64_i32 v[0:1], s[2:3], v158, s49, v[120:121]
	v_lshl_add_u64 v[0:1], v[0:1], 0, v[116:117]
	global_store_dwordx4 v[0:1], v[8:11], off nt
	s_cbranch_vccnz .LBB0_364
	s_andn2_b64 vcc, exec, s[6:7]
	s_cbranch_vccnz .LBB0_363
	s_barrier
	s_branch .LBB0_363

.LBB0_458:
	s_lshl_b32 s22, s59, 8
	s_add_i32 s22, s22, s43
	v_or_b32_e32 v130, s22, v170
	v_ashrrev_i32_e32 v131, 31, v130
	v_lshl_or_b32 v128, s64, 8, v145
	v_lshlrev_b64 v[130:131], 11, v[130:131]
	v_ashrrev_i32_e32 v129, 31, v128
	v_lshl_add_u64 v[130:131], s[84:85], 0, v[130:131]
	v_lshl_add_u64 v[164:165], v[128:129], 1, v[130:131]
	global_load_dwordx4 v[190:193], v[164:165], off
	global_load_dwordx4 v[196:199], v[164:165], off offset:256
	v_add_co_u32_e32 v212, vcc, s47, v164
	v_and_b32_e32 v129, 64, v186
	s_nop 0
	v_addc_co_u32_e32 v213, vcc, 0, v165, vcc
	global_load_dwordx4 v[200:203], v[212:213], off
	v_xor_b32_e32 v128, 16, v186
	v_add_u32_e32 v129, 64, v129
	v_xor_b32_e32 v130, 32, v186
	v_cmp_lt_i32_e32 vcc, v128, v129
	s_waitcnt vmcnt(0)
	v_lshlrev_b32_e32 v214, 16, v190
	v_cndmask_b32_e32 v128, v186, v128, vcc
	v_cmp_lt_i32_e32 vcc, v130, v129
	v_lshlrev_b32_e32 v188, 2, v128
	v_and_b32_e32 v215, 0xffff0000, v190
	v_cndmask_b32_e32 v129, v186, v130, vcc
	v_add_co_u32_e32 v168, vcc, s42, v164
	v_lshlrev_b32_e32 v187, 2, v129
	s_nop 0
	v_addc_co_u32_e32 v169, vcc, 0, v165, vcc
	v_add_co_u32_e32 v166, vcc, s46, v164
	v_lshlrev_b32_e32 v190, 16, v191
	s_nop 0
	v_addc_co_u32_e32 v167, vcc, 0, v165, vcc
	global_load_dwordx4 v[204:207], v[212:213], off offset:256
	global_load_dwordx4 v[208:211], v[168:169], off
	global_load_dwordx4 v[136:139], v[168:169], off offset:256
	global_load_dwordx4 v[132:135], v[166:167], off
	global_load_dwordx4 v[128:131], v[166:167], off offset:256
	v_and_b32_e32 v191, 0xffff0000, v191
	v_lshlrev_b32_e32 v216, 16, v192
	v_and_b32_e32 v217, 0xffff0000, v192
	v_lshlrev_b32_e32 v192, 16, v193
	v_and_b32_e32 v193, 0xffff0000, v193
	v_lshlrev_b32_e32 v218, 16, v196
	v_and_b32_e32 v219, 0xffff0000, v196
	v_lshlrev_b32_e32 v196, 16, v197
	v_and_b32_e32 v197, 0xffff0000, v197
	v_lshlrev_b32_e32 v220, 16, v198
	v_and_b32_e32 v221, 0xffff0000, v198
	v_lshlrev_b32_e32 v198, 16, v199
	v_and_b32_e32 v199, 0xffff0000, v199
	v_pk_add_f32 v[126:127], v[126:127], v[190:191]
	v_pk_add_f32 v[124:125], v[124:125], v[214:215]
	v_pk_add_f32 v[122:123], v[122:123], v[192:193]
	v_pk_add_f32 v[190:191], v[118:119], v[196:197]
	v_pk_add_f32 v[192:193], v[116:117], v[218:219]
	v_pk_add_f32 v[120:121], v[120:121], v[216:217]
	v_pk_add_f32 v[196:197], v[114:115], v[198:199]
	v_pk_add_f32 v[198:199], v[112:113], v[220:221]
	v_cvt_pk_bf16_f32 v112, v124, v125
	v_cvt_pk_bf16_f32 v113, v126, v127
	v_mul_f32_e32 v125, v125, v125
	v_mul_f32_e32 v127, v127, v127
	v_cvt_pk_bf16_f32 v117, v190, v191
	v_mul_f32_e32 v189, v193, v193
	v_mul_f32_e32 v191, v191, v191
	v_cvt_pk_bf16_f32 v114, v120, v121
	v_cvt_pk_bf16_f32 v115, v122, v123
	v_mul_f32_e32 v121, v121, v121
	v_cvt_pk_bf16_f32 v116, v192, v193
	v_mul_f32_e32 v193, v199, v199
	v_fmac_f32_e32 v125, v124, v124
	v_fmac_f32_e32 v127, v126, v126
	v_fmac_f32_e32 v189, v192, v192
	v_fmac_f32_e32 v191, v190, v190
	v_mul_f32_e32 v123, v123, v123
	v_cvt_pk_bf16_f32 v119, v196, v197
	v_mul_f32_e32 v197, v197, v197
	global_store_dwordx4 v[164:165], v[112:115], off nt
	v_fmac_f32_e32 v121, v120, v120
	v_fmac_f32_e32 v193, v198, v198
	v_add_f32_e32 v112, v125, v127
	v_add_f32_e32 v113, v189, v191
	v_fmac_f32_e32 v123, v122, v122
	v_fmac_f32_e32 v197, v196, v196
	v_add_f32_e32 v112, v121, v112
	v_add_f32_e32 v113, v193, v113
	v_cvt_pk_bf16_f32 v118, v198, v199
	v_add_f32_e32 v112, v123, v112
	v_add_f32_e32 v113, v197, v113
	global_store_dwordx4 v[164:165], v[116:119], off offset:256 nt
	v_add_f32_e32 v120, v112, v113
	v_lshlrev_b32_e32 v112, 16, v200
	v_and_b32_e32 v113, 0xffff0000, v200
	v_lshlrev_b32_e32 v114, 16, v201
	v_and_b32_e32 v115, 0xffff0000, v201
	v_lshlrev_b32_e32 v116, 16, v202
	v_and_b32_e32 v117, 0xffff0000, v202
	v_lshlrev_b32_e32 v118, 16, v203
	v_and_b32_e32 v119, 0xffff0000, v203
	v_pk_add_f32 v[110:111], v[110:111], v[114:115]
	v_pk_add_f32 v[108:109], v[108:109], v[112:113]
	v_pk_add_f32 v[112:113], v[106:107], v[118:119]
	v_pk_add_f32 v[114:115], v[104:105], v[116:117]
	v_cvt_pk_bf16_f32 v104, v108, v109
	v_cvt_pk_bf16_f32 v105, v110, v111
	v_cvt_pk_bf16_f32 v106, v114, v115
	v_cvt_pk_bf16_f32 v107, v112, v113
	global_store_dwordx4 v[212:213], v[104:107], off nt
	v_cmp_lt_i32_e32 vcc, 0, v171
	s_nop 0
	v_mul_f32_e32 v104, v109, v109
	v_mul_f32_e32 v105, v111, v111
	v_fmac_f32_e32 v104, v108, v108
	v_fmac_f32_e32 v105, v110, v110
	v_add_f32_e32 v104, v104, v105
	v_mul_f32_e32 v105, v115, v115
	v_fmac_f32_e32 v105, v114, v114
	v_add_f32_e32 v104, v105, v104
	v_mul_f32_e32 v105, v113, v113
	v_fmac_f32_e32 v105, v112, v112
	v_add_f32_e32 v112, v105, v104
	s_waitcnt vmcnt(7)
	v_lshlrev_b32_e32 v104, 16, v204
	v_and_b32_e32 v105, 0xffff0000, v204
	v_lshlrev_b32_e32 v106, 16, v205
	v_and_b32_e32 v107, 0xffff0000, v205
	v_lshlrev_b32_e32 v108, 16, v206
	v_and_b32_e32 v109, 0xffff0000, v206
	v_lshlrev_b32_e32 v110, 16, v207
	v_and_b32_e32 v111, 0xffff0000, v207
	v_pk_add_f32 v[102:103], v[102:103], v[106:107]
	v_pk_add_f32 v[100:101], v[100:101], v[104:105]
	v_pk_add_f32 v[104:105], v[98:99], v[110:111]
	v_pk_add_f32 v[106:107], v[96:97], v[108:109]
	v_cvt_pk_bf16_f32 v96, v100, v101
	v_cvt_pk_bf16_f32 v97, v102, v103
	v_cvt_pk_bf16_f32 v98, v106, v107
	v_cvt_pk_bf16_f32 v99, v104, v105
	global_store_dwordx4 v[212:213], v[96:99], off offset:256 nt
	s_nop 1
	v_mul_f32_e32 v96, v101, v101
	v_mul_f32_e32 v97, v103, v103
	v_fmac_f32_e32 v96, v100, v100
	v_fmac_f32_e32 v97, v102, v102
	v_add_f32_e32 v96, v96, v97
	v_mul_f32_e32 v97, v107, v107
	v_fmac_f32_e32 v97, v106, v106
	v_add_f32_e32 v96, v97, v96
	v_mul_f32_e32 v97, v105, v105
	v_fmac_f32_e32 v97, v104, v104
	v_add_f32_e32 v96, v97, v96
	v_add_f32_e32 v104, v112, v96
	s_waitcnt vmcnt(7)
	v_lshlrev_b32_e32 v96, 16, v208
	v_and_b32_e32 v97, 0xffff0000, v208
	v_lshlrev_b32_e32 v98, 16, v209
	v_and_b32_e32 v99, 0xffff0000, v209
	v_lshlrev_b32_e32 v100, 16, v210
	v_and_b32_e32 v101, 0xffff0000, v210
	v_lshlrev_b32_e32 v102, 16, v211
	v_and_b32_e32 v103, 0xffff0000, v211
	v_pk_add_f32 v[94:95], v[94:95], v[98:99]
	v_pk_add_f32 v[92:93], v[92:93], v[96:97]
	v_pk_add_f32 v[96:97], v[90:91], v[102:103]
	v_pk_add_f32 v[98:99], v[88:89], v[100:101]
	v_cvt_pk_bf16_f32 v88, v92, v93
	v_cvt_pk_bf16_f32 v89, v94, v95
	v_cvt_pk_bf16_f32 v90, v98, v99
	v_cvt_pk_bf16_f32 v91, v96, v97
	global_store_dwordx4 v[168:169], v[88:91], off nt
	s_nop 1
	v_mul_f32_e32 v88, v93, v93
	v_mul_f32_e32 v89, v95, v95
	v_fmac_f32_e32 v88, v92, v92
	v_fmac_f32_e32 v89, v94, v94
	v_add_f32_e32 v88, v88, v89
	v_mul_f32_e32 v89, v99, v99
	v_fmac_f32_e32 v89, v98, v98
	v_add_f32_e32 v88, v89, v88
	v_mul_f32_e32 v89, v97, v97
	v_fmac_f32_e32 v89, v96, v96
	v_add_f32_e32 v96, v89, v88
	s_waitcnt vmcnt(7)
	v_lshlrev_b32_e32 v88, 16, v136
	v_and_b32_e32 v89, 0xffff0000, v136
	v_lshlrev_b32_e32 v90, 16, v137
	v_and_b32_e32 v91, 0xffff0000, v137
	v_lshlrev_b32_e32 v92, 16, v138
	v_and_b32_e32 v93, 0xffff0000, v138
	v_lshlrev_b32_e32 v94, 16, v139
	v_and_b32_e32 v95, 0xffff0000, v139
	v_pk_add_f32 v[86:87], v[86:87], v[90:91]
	v_pk_add_f32 v[84:85], v[84:85], v[88:89]
	v_pk_add_f32 v[88:89], v[82:83], v[94:95]
	v_pk_add_f32 v[90:91], v[80:81], v[92:93]
	v_cvt_pk_bf16_f32 v80, v84, v85
	v_cvt_pk_bf16_f32 v81, v86, v87
	v_cvt_pk_bf16_f32 v82, v90, v91
	v_cvt_pk_bf16_f32 v83, v88, v89
	global_store_dwordx4 v[168:169], v[80:83], off offset:256 nt
	s_nop 1
	v_mul_f32_e32 v80, v85, v85
	v_mul_f32_e32 v81, v87, v87
	v_fmac_f32_e32 v80, v84, v84
	v_fmac_f32_e32 v81, v86, v86
	v_add_f32_e32 v80, v80, v81
	v_mul_f32_e32 v81, v91, v91
	v_fmac_f32_e32 v81, v90, v90
	v_add_f32_e32 v80, v81, v80
	v_mul_f32_e32 v81, v89, v89
	v_fmac_f32_e32 v81, v88, v88
	v_add_f32_e32 v80, v81, v80
	v_add_f32_e32 v88, v96, v80
	s_waitcnt vmcnt(7)
	v_lshlrev_b32_e32 v80, 16, v132
	v_and_b32_e32 v81, 0xffff0000, v132
	v_lshlrev_b32_e32 v82, 16, v133
	v_and_b32_e32 v83, 0xffff0000, v133
	v_lshlrev_b32_e32 v84, 16, v134
	v_and_b32_e32 v85, 0xffff0000, v134
	v_lshlrev_b32_e32 v86, 16, v135
	v_and_b32_e32 v87, 0xffff0000, v135
	v_pk_add_f32 v[78:79], v[78:79], v[82:83]
	v_pk_add_f32 v[76:77], v[76:77], v[80:81]
	v_pk_add_f32 v[80:81], v[74:75], v[86:87]
	v_pk_add_f32 v[82:83], v[72:73], v[84:85]
	v_cvt_pk_bf16_f32 v72, v76, v77
	v_cvt_pk_bf16_f32 v73, v78, v79
	v_cvt_pk_bf16_f32 v74, v82, v83
	v_cvt_pk_bf16_f32 v75, v80, v81
	global_store_dwordx4 v[166:167], v[72:75], off nt
	s_nop 1
	v_mul_f32_e32 v72, v77, v77
	v_mul_f32_e32 v73, v79, v79
	v_fmac_f32_e32 v72, v76, v76
	v_fmac_f32_e32 v73, v78, v78
	v_add_f32_e32 v72, v72, v73
	v_mul_f32_e32 v73, v83, v83
	v_fmac_f32_e32 v73, v82, v82
	v_add_f32_e32 v72, v73, v72
	v_mul_f32_e32 v73, v81, v81
	v_fmac_f32_e32 v73, v80, v80
	v_add_f32_e32 v82, v73, v72
	s_waitcnt vmcnt(7)
	v_lshlrev_b32_e32 v72, 16, v128
	v_and_b32_e32 v73, 0xffff0000, v128
	v_lshlrev_b32_e32 v74, 16, v129
	v_and_b32_e32 v75, 0xffff0000, v129
	v_lshlrev_b32_e32 v76, 16, v130
	v_and_b32_e32 v77, 0xffff0000, v130
	v_pk_add_f32 v[80:81], v[70:71], v[74:75]
	v_pk_add_f32 v[68:69], v[68:69], v[72:73]
	v_pk_add_f32 v[76:77], v[64:65], v[76:77]
	v_mul_f32_e32 v64, v69, v69
	v_mul_f32_e32 v65, v81, v81
	v_fmac_f32_e32 v64, v68, v68
	v_fmac_f32_e32 v65, v80, v80
	v_lshlrev_b32_e32 v78, 16, v131
	v_and_b32_e32 v79, 0xffff0000, v131
	v_add_f32_e32 v64, v64, v65
	v_mul_f32_e32 v65, v77, v77
	v_pk_add_f32 v[78:79], v[66:67], v[78:79]
	v_fmac_f32_e32 v65, v76, v76
	v_add_f32_e32 v64, v65, v64
	v_mul_f32_e32 v65, v79, v79
	v_fmac_f32_e32 v65, v78, v78
	v_add_f32_e32 v64, v65, v64
	v_add_f32_e32 v64, v82, v64
	v_cvt_pk_bf16_f32 v74, v68, v69
	ds_bpermute_b32 v66, v188, v120
	ds_bpermute_b32 v65, v188, v104
	ds_bpermute_b32 v69, v188, v88
	ds_bpermute_b32 v71, v188, v64
	v_cvt_pk_bf16_f32 v75, v80, v81
	s_waitcnt lgkmcnt(3)
	v_add_f32_e32 v67, v120, v66
	s_waitcnt lgkmcnt(2)
	v_add_f32_e32 v65, v104, v65
	s_waitcnt lgkmcnt(1)
	v_add_f32_e32 v69, v88, v69
	s_waitcnt lgkmcnt(0)
	v_add_f32_e32 v71, v64, v71
	ds_bpermute_b32 v68, v187, v67
	ds_bpermute_b32 v66, v187, v65
	ds_bpermute_b32 v70, v187, v69
	ds_bpermute_b32 v72, v187, v71
	v_cvt_pk_bf16_f32 v76, v76, v77
	v_cvt_pk_bf16_f32 v77, v78, v79
	global_store_dwordx4 v[166:167], v[74:77], off offset:256 nt
	s_and_saveexec_b64 s[2:3], vcc
	s_xor_b64 s[2:3], exec, s[2:3]
	s_cbranch_execz .LBB0_464
	v_cmp_ne_u32_e32 vcc, 1, v171
	s_and_saveexec_b64 s[14:15], vcc
	s_xor_b64 s[14:15], exec, s[14:15]
	s_cbranch_execz .LBB0_461
	s_waitcnt lgkmcnt(0)
	v_add_f32_e32 v64, v71, v72
	v_add_f32_e32 v65, v69, v70
	v_cndmask_b32_e64 v64, v64, v65, s[4:5]

.LBB0_466:
	s_or_b64 exec, exec, s[2:3]
	v_mul_f32_e32 v64, 0x49800000, v64
	v_trunc_f32_e32 v64, v64
	v_mul_f32_e32 v65, 0x2f800000, v64
	v_floor_f32_e32 v65, v65
	v_fmac_f32_e32 v64, 0xcf800000, v65
	v_cvt_u32_f32_e32 v64, v64
	v_cvt_u32_f32_e32 v65, v65
	v_or_b32_e32 v76, s22, v143
	v_ashrrev_i32_e32 v77, 31, v76
	s_waitcnt lgkmcnt(2)
	v_lshl_add_u64 v[66:67], v[76:77], 3, s[20:21]
	v_add_co_u32_e32 v102, vcc, s53, v164
	global_atomic_add_x2 v[66:67], v[64:65], off
	s_nop 0
	v_addc_co_u32_e32 v103, vcc, 0, v165, vcc
	global_load_dwordx4 v[82:85], v[102:103], off
	global_load_dwordx4 v[86:89], v[102:103], off offset:256
	v_add_co_u32_e32 v104, vcc, s54, v164
	s_waitcnt vmcnt(1)
	v_lshlrev_b32_e32 v106, 16, v82
	v_addc_co_u32_e32 v105, vcc, 0, v165, vcc
	global_load_dwordx4 v[90:93], v[104:105], off
	v_add_co_u32_e32 v80, vcc, s55, v164
	v_and_b32_e32 v107, 0xffff0000, v82
	s_nop 0
	v_addc_co_u32_e32 v81, vcc, 0, v165, vcc
	v_add_co_u32_e32 v78, vcc, s56, v164
	v_lshlrev_b32_e32 v82, 16, v83
	s_nop 0
	v_addc_co_u32_e32 v79, vcc, 0, v165, vcc
	global_load_dwordx4 v[94:97], v[104:105], off offset:256
	global_load_dwordx4 v[98:101], v[80:81], off
	s_waitcnt lgkmcnt(0)
	global_load_dwordx4 v[72:75], v[80:81], off offset:256
	global_load_dwordx4 v[68:71], v[78:79], off
	global_load_dwordx4 v[64:67], v[78:79], off offset:256
	v_and_b32_e32 v83, 0xffff0000, v83
	v_lshlrev_b32_e32 v108, 16, v84
	v_and_b32_e32 v109, 0xffff0000, v84
	v_lshlrev_b32_e32 v84, 16, v85
	v_and_b32_e32 v85, 0xffff0000, v85
	s_waitcnt vmcnt(6)
	v_lshlrev_b32_e32 v110, 16, v86
	v_and_b32_e32 v111, 0xffff0000, v86
	v_lshlrev_b32_e32 v86, 16, v87
	v_and_b32_e32 v87, 0xffff0000, v87
	v_lshlrev_b32_e32 v112, 16, v88
	v_and_b32_e32 v113, 0xffff0000, v88
	v_lshlrev_b32_e32 v88, 16, v89
	v_and_b32_e32 v89, 0xffff0000, v89
	v_pk_add_f32 v[62:63], v[62:63], v[82:83]
	v_pk_add_f32 v[60:61], v[60:61], v[106:107]
	v_pk_add_f32 v[58:59], v[58:59], v[84:85]
	v_pk_add_f32 v[82:83], v[54:55], v[86:87]
	v_pk_add_f32 v[84:85], v[52:53], v[110:111]
	v_pk_add_f32 v[56:57], v[56:57], v[108:109]
	v_pk_add_f32 v[86:87], v[50:51], v[88:89]
	v_pk_add_f32 v[88:89], v[48:49], v[112:113]
	v_cvt_pk_bf16_f32 v48, v60, v61
	v_cvt_pk_bf16_f32 v49, v62, v63
	v_mul_f32_e32 v61, v61, v61
	v_mul_f32_e32 v63, v63, v63
	v_cvt_pk_bf16_f32 v53, v82, v83
	v_mul_f32_e32 v77, v85, v85
	v_mul_f32_e32 v83, v83, v83
	v_cvt_pk_bf16_f32 v50, v56, v57
	v_cvt_pk_bf16_f32 v51, v58, v59
	v_mul_f32_e32 v57, v57, v57
	v_cvt_pk_bf16_f32 v52, v84, v85
	v_mul_f32_e32 v85, v89, v89
	v_fmac_f32_e32 v61, v60, v60
	v_fmac_f32_e32 v63, v62, v62
	v_fmac_f32_e32 v77, v84, v84
	v_fmac_f32_e32 v83, v82, v82
	v_mul_f32_e32 v59, v59, v59
	v_cvt_pk_bf16_f32 v55, v86, v87
	v_mul_f32_e32 v87, v87, v87
	global_store_dwordx4 v[102:103], v[48:51], off nt
	v_fmac_f32_e32 v57, v56, v56
	v_fmac_f32_e32 v85, v88, v88
	v_add_f32_e32 v48, v61, v63
	v_add_f32_e32 v49, v77, v83
	v_fmac_f32_e32 v59, v58, v58
	v_fmac_f32_e32 v87, v86, v86
	v_add_f32_e32 v48, v57, v48
	v_add_f32_e32 v49, v85, v49
	v_cvt_pk_bf16_f32 v54, v88, v89
	v_add_f32_e32 v48, v59, v48
	v_add_f32_e32 v49, v87, v49
	global_store_dwordx4 v[102:103], v[52:55], off offset:256 nt
	v_cmp_lt_i32_e32 vcc, 0, v171
	s_waitcnt vmcnt(7)
	v_lshlrev_b32_e32 v114, 16, v90
	v_and_b32_e32 v115, 0xffff0000, v90
	v_add_f32_e32 v54, v48, v49
	v_lshlrev_b32_e32 v48, 16, v91
	v_and_b32_e32 v49, 0xffff0000, v91
	v_lshlrev_b32_e32 v50, 16, v92
	v_and_b32_e32 v51, 0xffff0000, v92
	v_lshlrev_b32_e32 v52, 16, v93
	v_and_b32_e32 v53, 0xffff0000, v93
	v_pk_add_f32 v[46:47], v[46:47], v[48:49]
	v_pk_add_f32 v[44:45], v[44:45], v[114:115]
	v_pk_add_f32 v[48:49], v[42:43], v[52:53]
	v_pk_add_f32 v[50:51], v[40:41], v[50:51]
	v_cvt_pk_bf16_f32 v40, v44, v45
	v_cvt_pk_bf16_f32 v41, v46, v47
	v_cvt_pk_bf16_f32 v42, v50, v51
	v_cvt_pk_bf16_f32 v43, v48, v49
	global_store_dwordx4 v[104:105], v[40:43], off nt
	s_nop 1
	v_mul_f32_e32 v40, v45, v45
	v_mul_f32_e32 v41, v47, v47
	v_fmac_f32_e32 v40, v44, v44
	v_fmac_f32_e32 v41, v46, v46
	v_add_f32_e32 v40, v40, v41
	v_mul_f32_e32 v41, v51, v51
	v_fmac_f32_e32 v41, v50, v50
	v_add_f32_e32 v40, v41, v40
	v_mul_f32_e32 v41, v49, v49
	v_fmac_f32_e32 v41, v48, v48
	v_add_f32_e32 v48, v41, v40
	s_waitcnt vmcnt(7)
	v_lshlrev_b32_e32 v40, 16, v94
	v_and_b32_e32 v41, 0xffff0000, v94
	v_lshlrev_b32_e32 v42, 16, v95
	v_and_b32_e32 v43, 0xffff0000, v95
	v_lshlrev_b32_e32 v44, 16, v96
	v_and_b32_e32 v45, 0xffff0000, v96
	v_lshlrev_b32_e32 v46, 16, v97
	v_and_b32_e32 v47, 0xffff0000, v97
	v_pk_add_f32 v[38:39], v[38:39], v[42:43]
	v_pk_add_f32 v[36:37], v[36:37], v[40:41]
	v_pk_add_f32 v[40:41], v[34:35], v[46:47]
	v_pk_add_f32 v[42:43], v[32:33], v[44:45]
	v_cvt_pk_bf16_f32 v32, v36, v37
	v_cvt_pk_bf16_f32 v33, v38, v39
	v_cvt_pk_bf16_f32 v34, v42, v43
	v_cvt_pk_bf16_f32 v35, v40, v41
	global_store_dwordx4 v[104:105], v[32:35], off offset:256 nt
	s_nop 1
	v_mul_f32_e32 v32, v37, v37
	v_mul_f32_e32 v33, v39, v39
	v_fmac_f32_e32 v32, v36, v36
	v_fmac_f32_e32 v33, v38, v38
	v_add_f32_e32 v32, v32, v33
	v_mul_f32_e32 v33, v43, v43
	v_fmac_f32_e32 v33, v42, v42
	v_add_f32_e32 v32, v33, v32
	v_mul_f32_e32 v33, v41, v41
	v_fmac_f32_e32 v33, v40, v40
	v_add_f32_e32 v32, v33, v32
	v_add_f32_e32 v40, v48, v32
	s_waitcnt vmcnt(7)
	v_lshlrev_b32_e32 v32, 16, v98
	v_and_b32_e32 v33, 0xffff0000, v98
	v_lshlrev_b32_e32 v34, 16, v99
	v_and_b32_e32 v35, 0xffff0000, v99
	v_lshlrev_b32_e32 v36, 16, v100
	v_and_b32_e32 v37, 0xffff0000, v100
	v_lshlrev_b32_e32 v38, 16, v101
	v_and_b32_e32 v39, 0xffff0000, v101
	v_pk_add_f32 v[30:31], v[30:31], v[34:35]
	v_pk_add_f32 v[28:29], v[28:29], v[32:33]
	v_pk_add_f32 v[32:33], v[26:27], v[38:39]
	v_pk_add_f32 v[34:35], v[24:25], v[36:37]
	v_cvt_pk_bf16_f32 v24, v28, v29
	v_cvt_pk_bf16_f32 v25, v30, v31
	v_cvt_pk_bf16_f32 v26, v34, v35
	v_cvt_pk_bf16_f32 v27, v32, v33
	global_store_dwordx4 v[80:81], v[24:27], off nt
	s_nop 1
	v_mul_f32_e32 v24, v29, v29
	v_mul_f32_e32 v25, v31, v31
	v_fmac_f32_e32 v24, v28, v28
	v_fmac_f32_e32 v25, v30, v30
	v_add_f32_e32 v24, v24, v25
	v_mul_f32_e32 v25, v35, v35
	v_fmac_f32_e32 v25, v34, v34
	v_add_f32_e32 v24, v25, v24
	v_mul_f32_e32 v25, v33, v33
	v_fmac_f32_e32 v25, v32, v32
	v_add_f32_e32 v32, v25, v24
	s_waitcnt vmcnt(7)
	v_lshlrev_b32_e32 v24, 16, v72
	v_and_b32_e32 v25, 0xffff0000, v72
	v_lshlrev_b32_e32 v26, 16, v73
	v_and_b32_e32 v27, 0xffff0000, v73
	v_lshlrev_b32_e32 v28, 16, v74
	v_and_b32_e32 v29, 0xffff0000, v74
	v_lshlrev_b32_e32 v30, 16, v75
	v_and_b32_e32 v31, 0xffff0000, v75
	v_pk_add_f32 v[22:23], v[22:23], v[26:27]
	v_pk_add_f32 v[20:21], v[20:21], v[24:25]
	v_pk_add_f32 v[24:25], v[18:19], v[30:31]
	v_pk_add_f32 v[26:27], v[16:17], v[28:29]
	v_cvt_pk_bf16_f32 v16, v20, v21
	v_cvt_pk_bf16_f32 v17, v22, v23
	v_cvt_pk_bf16_f32 v18, v26, v27
	v_cvt_pk_bf16_f32 v19, v24, v25
	global_store_dwordx4 v[80:81], v[16:19], off offset:256 nt
	s_nop 1
	v_mul_f32_e32 v16, v21, v21
	v_mul_f32_e32 v17, v23, v23
	v_fmac_f32_e32 v16, v20, v20
	v_fmac_f32_e32 v17, v22, v22
	v_add_f32_e32 v16, v16, v17
	v_mul_f32_e32 v17, v27, v27
	v_fmac_f32_e32 v17, v26, v26
	v_add_f32_e32 v16, v17, v16
	v_mul_f32_e32 v17, v25, v25
	v_fmac_f32_e32 v17, v24, v24
	v_add_f32_e32 v16, v17, v16
	v_add_f32_e32 v24, v32, v16
	s_waitcnt vmcnt(7)
	v_lshlrev_b32_e32 v16, 16, v68
	v_and_b32_e32 v17, 0xffff0000, v68
	v_lshlrev_b32_e32 v18, 16, v69
	v_and_b32_e32 v19, 0xffff0000, v69
	v_lshlrev_b32_e32 v20, 16, v70
	v_and_b32_e32 v21, 0xffff0000, v70
	v_lshlrev_b32_e32 v22, 16, v71
	v_and_b32_e32 v23, 0xffff0000, v71
	v_pk_add_f32 v[14:15], v[14:15], v[18:19]
	v_pk_add_f32 v[12:13], v[12:13], v[16:17]
	v_pk_add_f32 v[16:17], v[10:11], v[22:23]
	v_pk_add_f32 v[18:19], v[8:9], v[20:21]
	v_cvt_pk_bf16_f32 v8, v12, v13
	v_cvt_pk_bf16_f32 v9, v14, v15
	v_cvt_pk_bf16_f32 v10, v18, v19
	v_cvt_pk_bf16_f32 v11, v16, v17
	global_store_dwordx4 v[78:79], v[8:11], off nt
	s_nop 1
	v_mul_f32_e32 v8, v13, v13
	v_mul_f32_e32 v9, v15, v15
	v_fmac_f32_e32 v8, v12, v12
	v_fmac_f32_e32 v9, v14, v14
	v_add_f32_e32 v8, v8, v9
	v_mul_f32_e32 v9, v19, v19
	v_fmac_f32_e32 v9, v18, v18
	v_add_f32_e32 v8, v9, v8
	v_mul_f32_e32 v9, v17, v17
	v_fmac_f32_e32 v9, v16, v16
	v_add_f32_e32 v18, v9, v8
	s_waitcnt vmcnt(7)
	v_lshlrev_b32_e32 v8, 16, v64
	v_and_b32_e32 v9, 0xffff0000, v64
	v_lshlrev_b32_e32 v10, 16, v65
	v_and_b32_e32 v11, 0xffff0000, v65
	v_lshlrev_b32_e32 v12, 16, v66
	v_and_b32_e32 v13, 0xffff0000, v66
	v_pk_add_f32 v[16:17], v[6:7], v[10:11]
	v_pk_add_f32 v[4:5], v[4:5], v[8:9]
	v_pk_add_f32 v[12:13], v[0:1], v[12:13]
	v_mul_f32_e32 v0, v5, v5
	v_mul_f32_e32 v1, v17, v17
	v_fmac_f32_e32 v0, v4, v4
	v_fmac_f32_e32 v1, v16, v16
	v_lshlrev_b32_e32 v14, 16, v67
	v_and_b32_e32 v15, 0xffff0000, v67
	v_add_f32_e32 v0, v0, v1
	v_mul_f32_e32 v1, v13, v13
	v_pk_add_f32 v[14:15], v[2:3], v[14:15]
	v_fmac_f32_e32 v1, v12, v12
	v_add_f32_e32 v0, v1, v0
	v_mul_f32_e32 v1, v15, v15
	v_fmac_f32_e32 v1, v14, v14
	v_add_f32_e32 v0, v1, v0
	v_add_f32_e32 v0, v18, v0
	v_cvt_pk_bf16_f32 v10, v4, v5
	ds_bpermute_b32 v2, v188, v54
	ds_bpermute_b32 v1, v188, v40
	ds_bpermute_b32 v5, v188, v24
	ds_bpermute_b32 v7, v188, v0
	v_cvt_pk_bf16_f32 v11, v16, v17
	s_waitcnt lgkmcnt(3)
	v_add_f32_e32 v3, v54, v2
	s_waitcnt lgkmcnt(2)
	v_add_f32_e32 v1, v40, v1
	s_waitcnt lgkmcnt(1)
	v_add_f32_e32 v5, v24, v5
	s_waitcnt lgkmcnt(0)
	v_add_f32_e32 v7, v0, v7
	ds_bpermute_b32 v4, v187, v3
	ds_bpermute_b32 v2, v187, v1
	ds_bpermute_b32 v6, v187, v5
	ds_bpermute_b32 v8, v187, v7
	v_cvt_pk_bf16_f32 v12, v12, v13
	v_cvt_pk_bf16_f32 v13, v14, v15
	global_store_dwordx4 v[78:79], v[10:13], off offset:256 nt
	s_and_saveexec_b64 s[2:3], vcc
	s_xor_b64 s[2:3], exec, s[2:3]
	s_cbranch_execz .LBB0_472
	v_cmp_ne_u32_e32 vcc, 1, v171
	s_and_saveexec_b64 s[14:15], vcc
	s_xor_b64 s[14:15], exec, s[14:15]
	s_cbranch_execz .LBB0_469
	s_waitcnt lgkmcnt(0)
	v_add_f32_e32 v0, v7, v8
	v_add_f32_e32 v1, v5, v6
	v_cndmask_b32_e64 v0, v0, v1, s[4:5]

.LBB0_555:
	v_lshl_add_u32 v138, s0, 8, v149
	v_ashrrev_i32_e32 v139, 31, v138
	v_lshl_add_u64 v[156:157], v[138:139], 3, s[20:21]
	v_or_b32_e32 v186, 16, v138
	global_load_dwordx2 v[184:185], v[156:157], off
	v_ashrrev_i32_e32 v187, 31, v186
	v_or_b32_e32 v188, 32, v138
	v_lshl_add_u64 v[158:159], v[186:187], 3, s[20:21]
	v_ashrrev_i32_e32 v189, 31, v188
	v_lshl_add_u64 v[160:161], v[188:189], 3, s[20:21]
	global_load_dwordx2 v[190:191], v[158:159], off
	global_load_dwordx2 v[192:193], v[160:161], off
	v_or_b32_e32 v162, 48, v138
	v_ashrrev_i32_e32 v163, 31, v162
	v_lshl_add_u64 v[196:197], v[162:163], 3, s[20:21]
	global_load_dwordx2 v[164:165], v[156:157], off offset:1024
	global_load_dwordx2 v[160:161], v[156:157], off offset:1152
	global_load_dwordx2 v[158:159], v[156:157], off offset:1280
	s_nop 0
	global_load_dwordx2 v[196:197], v[196:197], off
	s_nop 0
	global_load_dwordx2 v[156:157], v[156:157], off offset:1408
	s_ashr_i32 s0, s1, 2
	s_sub_i32 s2, 1, s0
	s_cmp_lg_u32 s0, 2
	s_cselect_b32 s2, s2, 2
	s_mul_hi_i32 s3, s2, 0x4080000
	s_mul_i32 s2, s2, 0x4080000
	s_add_u32 s2, s16, s2
	s_addc_u32 s3, s17, s3
	s_lshl_b32 s1, s1, 8
	s_cmp_eq_u32 s0, 1
	s_cselect_b64 vcc, -1, 0
	s_and_b32 s0, s1, 0x300
	v_or_b32_e32 v128, s0, v153
	v_lshlrev_b32_e32 v128, 1, v128
	v_lshl_add_u64 v[198:199], s[2:3], 0, v[128:129]
	v_cndmask_b32_e32 v200, 1.0, v169, vcc
	v_lshlrev_b64 v[138:139], 11, v[138:139]
	v_lshlrev_b64 v[186:187], 11, v[186:187]
	v_lshl_add_u64 v[138:139], v[198:199], 0, v[138:139]
	v_lshl_add_u64 v[186:187], v[198:199], 0, v[186:187]
	v_readlane_b32 s72, v248, 23
	v_readlane_b32 s73, v248, 24
	s_waitcnt vmcnt(0)
	v_ffbh_u32_e32 v128, v185
	v_min_u32_e32 v128, 32, v128
	v_lshlrev_b64 v[184:185], v128, v[184:185]
	v_min_u32_e32 v184, 1, v184
	v_or_b32_e32 v184, v185, v184
	v_ffbh_u32_e32 v201, v191
	v_min_u32_e32 v201, 32, v201
	v_lshlrev_b64 v[190:191], v201, v[190:191]
	v_min_u32_e32 v185, 1, v190
	v_cvt_f32_u32_e32 v190, v184
	v_or_b32_e32 v184, v191, v185
	v_cvt_f32_u32_e32 v191, v184
	v_sub_u32_e32 v128, 32, v128
	v_sub_u32_e32 v201, 32, v201
	v_ldexp_f32 v128, v190, v128
	v_fmamk_f32 v128, v128, 0x30800000, v168
	v_ldexp_f32 v190, v191, v201
	v_fmamk_f32 v190, v190, 0x30800000, v168
	v_ffbh_u32_e32 v202, v193
	v_rsq_f32_e32 v128, v128
	v_rsq_f32_e32 v190, v190
	v_min_u32_e32 v202, 32, v202
	v_mul_f32_e32 v128, v200, v128
	v_mov_b32_e32 v201, v190
	v_lshlrev_b64 v[184:185], v202, v[192:193]
	v_pk_mul_f32 v[126:127], v[126:127], v[128:129] op_sel_hi:[1,0]
	v_pk_mul_f32 v[124:125], v[124:125], v[128:129] op_sel_hi:[1,0]
	v_pk_mul_f32 v[122:123], v[122:123], v[128:129] op_sel_hi:[1,0]
	v_pk_mul_f32 v[120:121], v[120:121], v[128:129] op_sel_hi:[1,0]
	v_pk_mul_f32 v[110:111], v[110:111], v[128:129] op_sel_hi:[1,0]
	v_pk_mul_f32 v[108:109], v[108:109], v[128:129] op_sel_hi:[1,0]
	v_pk_mul_f32 v[190:191], v[106:107], v[128:129] op_sel_hi:[1,0]
	v_pk_mul_f32 v[192:193], v[104:105], v[128:129] op_sel_hi:[1,0]
	v_mul_f32_e32 v128, v200, v201
	v_pk_mul_f32 v[118:119], v[118:119], v[128:129] op_sel_hi:[1,0]
	v_pk_mul_f32 v[116:117], v[116:117], v[128:129] op_sel_hi:[1,0]
	v_pk_mul_f32 v[114:115], v[114:115], v[128:129] op_sel_hi:[1,0]
	v_pk_mul_f32 v[112:113], v[112:113], v[128:129] op_sel_hi:[1,0]
	v_min_u32_e32 v184, 1, v184
	v_cvt_pk_bf16_f32 v104, v124, v125
	v_cvt_pk_bf16_f32 v105, v126, v127
	v_cvt_pk_bf16_f32 v106, v120, v121
	v_cvt_pk_bf16_f32 v107, v122, v123
	v_pk_mul_f32 v[120:121], v[98:99], v[128:129] op_sel_hi:[1,0]
	v_pk_mul_f32 v[122:123], v[96:97], v[128:129] op_sel_hi:[1,0]
	v_cvt_pk_bf16_f32 v96, v116, v117
	v_cvt_pk_bf16_f32 v97, v118, v119
	v_cvt_pk_bf16_f32 v98, v112, v113
	v_cvt_pk_bf16_f32 v99, v114, v115
	v_cvt_pk_bf16_f32 v108, v108, v109
	v_cvt_pk_bf16_f32 v109, v110, v111
	v_cvt_pk_bf16_f32 v110, v192, v193
	v_cvt_pk_bf16_f32 v111, v190, v191
	global_store_dwordx4 v[138:139], v[104:107], off nt
	global_store_dwordx4 v[138:139], v[108:111], off offset:256 nt
	global_store_dwordx4 v[186:187], v[96:99], off nt
	v_pk_mul_f32 v[100:101], v[100:101], v[128:129] op_sel_hi:[1,0]
	v_pk_mul_f32 v[102:103], v[102:103], v[128:129] op_sel_hi:[1,0]
	v_or_b32_e32 v96, v185, v184
	v_cvt_f32_u32_e32 v98, v96
	v_sub_u32_e32 v99, 32, v202
	v_cvt_pk_bf16_f32 v96, v100, v101
	v_cvt_pk_bf16_f32 v97, v102, v103
	v_ldexp_f32 v98, v98, v99
	v_fmamk_f32 v98, v98, 0x30800000, v168
	s_mov_b64 s[0:1], -1
	s_nop 0
	v_rsq_f32_e32 v100, v98
	v_cvt_pk_bf16_f32 v98, v122, v123
	v_cvt_pk_bf16_f32 v99, v120, v121
	global_store_dwordx4 v[186:187], v[96:99], off offset:256 nt
	s_nop 1
	v_mov_b32_e32 v96, v100
	v_mul_f32_e32 v96, v200, v96
	v_lshlrev_b64 v[98:99], 11, v[188:189]
	v_pk_mul_f32 v[94:95], v[94:95], v[96:97] op_sel_hi:[1,0]
	v_pk_mul_f32 v[92:93], v[92:93], v[96:97] op_sel_hi:[1,0]
	v_pk_mul_f32 v[100:101], v[90:91], v[96:97] op_sel_hi:[1,0]
	v_pk_mul_f32 v[90:91], v[88:89], v[96:97] op_sel_hi:[1,0]
	v_lshl_add_u64 v[98:99], v[198:199], 0, v[98:99]
	v_cvt_pk_bf16_f32 v88, v92, v93
	v_cvt_pk_bf16_f32 v89, v94, v95
	v_cvt_pk_bf16_f32 v90, v90, v91
	v_cvt_pk_bf16_f32 v91, v100, v101
	global_store_dwordx4 v[98:99], v[88:91], off nt
	v_pk_mul_f32 v[84:85], v[84:85], v[96:97] op_sel_hi:[1,0]
	v_pk_mul_f32 v[86:87], v[86:87], v[96:97] op_sel_hi:[1,0]
	v_pk_mul_f32 v[88:89], v[82:83], v[96:97] op_sel_hi:[1,0]
	v_pk_mul_f32 v[82:83], v[80:81], v[96:97] op_sel_hi:[1,0]
	v_ffbh_u32_e32 v80, v197
	v_min_u32_e32 v90, 32, v80
	v_lshlrev_b64 v[80:81], v90, v[196:197]
	v_min_u32_e32 v80, 1, v80
	v_or_b32_e32 v80, v81, v80
	v_cvt_f32_u32_e32 v91, v80
	v_cvt_pk_bf16_f32 v80, v84, v85
	v_sub_u32_e32 v84, 32, v90
	v_cvt_pk_bf16_f32 v81, v86, v87
	v_ldexp_f32 v84, v91, v84
	v_fmamk_f32 v84, v84, 0x30800000, v168
	v_cvt_pk_bf16_f32 v82, v82, v83
	v_cvt_pk_bf16_f32 v83, v88, v89
	v_rsq_f32_e32 v84, v84
	global_store_dwordx4 v[98:99], v[80:83], off offset:256 nt
	s_nop 1
	v_mov_b32_e32 v80, v84
	v_mul_f32_e32 v80, v200, v80
	v_lshlrev_b64 v[82:83], 11, v[162:163]
	v_pk_mul_f32 v[78:79], v[78:79], v[80:81] op_sel_hi:[1,0]
	v_pk_mul_f32 v[76:77], v[76:77], v[80:81] op_sel_hi:[1,0]
	v_pk_mul_f32 v[84:85], v[74:75], v[80:81] op_sel_hi:[1,0]
	v_pk_mul_f32 v[74:75], v[72:73], v[80:81] op_sel_hi:[1,0]
	v_lshl_add_u64 v[82:83], v[198:199], 0, v[82:83]
	v_cvt_pk_bf16_f32 v72, v76, v77
	v_cvt_pk_bf16_f32 v73, v78, v79
	v_cvt_pk_bf16_f32 v74, v74, v75
	v_cvt_pk_bf16_f32 v75, v84, v85
	global_store_dwordx4 v[82:83], v[72:75], off nt
	v_pk_mul_f32 v[68:69], v[68:69], v[80:81] op_sel_hi:[1,0]
	v_pk_mul_f32 v[70:71], v[70:71], v[80:81] op_sel_hi:[1,0]
	v_pk_mul_f32 v[72:73], v[66:67], v[80:81] op_sel_hi:[1,0]
	v_pk_mul_f32 v[66:67], v[64:65], v[80:81] op_sel_hi:[1,0]
	v_ffbh_u32_e32 v64, v165
	v_min_u32_e32 v74, 32, v64
	v_lshlrev_b64 v[64:65], v74, v[164:165]
	v_min_u32_e32 v64, 1, v64
	v_or_b32_e32 v64, v65, v64
	v_cvt_f32_u32_e32 v75, v64
	v_cvt_pk_bf16_f32 v64, v68, v69
	v_sub_u32_e32 v68, 32, v74
	v_cvt_pk_bf16_f32 v65, v70, v71
	v_ldexp_f32 v68, v75, v68
	v_fmamk_f32 v68, v68, 0x30800000, v168
	v_cvt_pk_bf16_f32 v66, v66, v67
	v_cvt_pk_bf16_f32 v67, v72, v73
	v_rsq_f32_e32 v68, v68
	global_store_dwordx4 v[82:83], v[64:67], off offset:256 nt
	s_nop 1
	v_mov_b32_e32 v64, v68
	v_mul_f32_e32 v64, v200, v64
	v_pk_mul_f32 v[60:61], v[60:61], v[64:65] op_sel_hi:[1,0]
	v_pk_mul_f32 v[62:63], v[62:63], v[64:65] op_sel_hi:[1,0]
	v_pk_mul_f32 v[68:69], v[58:59], v[64:65] op_sel_hi:[1,0]
	v_pk_mul_f32 v[58:59], v[56:57], v[64:65] op_sel_hi:[1,0]
	v_cvt_pk_bf16_f32 v56, v60, v61
	v_add_co_u32_e32 v60, vcc, s65, v138
	v_cvt_pk_bf16_f32 v57, v62, v63
	v_cvt_pk_bf16_f32 v58, v58, v59
	v_cvt_pk_bf16_f32 v59, v68, v69
	v_addc_co_u32_e32 v61, vcc, 0, v139, vcc
	global_store_dwordx4 v[60:61], v[56:59], off nt
	v_pk_mul_f32 v[52:53], v[52:53], v[64:65] op_sel_hi:[1,0]
	v_pk_mul_f32 v[54:55], v[54:55], v[64:65] op_sel_hi:[1,0]
	v_pk_mul_f32 v[56:57], v[50:51], v[64:65] op_sel_hi:[1,0]
	v_pk_mul_f32 v[50:51], v[48:49], v[64:65] op_sel_hi:[1,0]
	v_ffbh_u32_e32 v48, v161
	v_min_u32_e32 v58, 32, v48
	v_lshlrev_b64 v[48:49], v58, v[160:161]
	v_min_u32_e32 v48, 1, v48
	v_or_b32_e32 v48, v49, v48
	v_cvt_f32_u32_e32 v59, v48
	v_cvt_pk_bf16_f32 v48, v52, v53
	v_sub_u32_e32 v52, 32, v58
	v_lshl_add_u64 v[66:67], v[138:139], 0, s[6:7]
	v_ldexp_f32 v52, v59, v52
	v_fmamk_f32 v52, v52, 0x30800000, v168
	v_cvt_pk_bf16_f32 v49, v54, v55
	v_cvt_pk_bf16_f32 v50, v50, v51
	v_rsq_f32_e32 v52, v52
	v_cvt_pk_bf16_f32 v51, v56, v57
	global_store_dwordx4 v[66:67], v[48:51], off offset:256 nt
	s_nop 1
	v_mov_b32_e32 v48, v52
	v_mul_f32_e32 v48, v200, v48
	v_pk_mul_f32 v[44:45], v[44:45], v[48:49] op_sel_hi:[1,0]
	v_pk_mul_f32 v[46:47], v[46:47], v[48:49] op_sel_hi:[1,0]
	v_pk_mul_f32 v[52:53], v[42:43], v[48:49] op_sel_hi:[1,0]
	v_pk_mul_f32 v[42:43], v[40:41], v[48:49] op_sel_hi:[1,0]
	v_cvt_pk_bf16_f32 v40, v44, v45
	v_add_co_u32_e32 v44, vcc, s66, v138
	v_cvt_pk_bf16_f32 v41, v46, v47
	v_cvt_pk_bf16_f32 v42, v42, v43
	v_cvt_pk_bf16_f32 v43, v52, v53
	v_addc_co_u32_e32 v45, vcc, 0, v139, vcc
	global_store_dwordx4 v[44:45], v[40:43], off nt
	v_pk_mul_f32 v[36:37], v[36:37], v[48:49] op_sel_hi:[1,0]
	v_pk_mul_f32 v[38:39], v[38:39], v[48:49] op_sel_hi:[1,0]
	v_pk_mul_f32 v[40:41], v[34:35], v[48:49] op_sel_hi:[1,0]
	v_pk_mul_f32 v[34:35], v[32:33], v[48:49] op_sel_hi:[1,0]
	v_ffbh_u32_e32 v32, v159
	v_min_u32_e32 v42, 32, v32
	v_lshlrev_b64 v[32:33], v42, v[158:159]
	v_min_u32_e32 v32, 1, v32
	v_or_b32_e32 v32, v33, v32
	v_cvt_f32_u32_e32 v43, v32
	v_cvt_pk_bf16_f32 v32, v36, v37
	v_sub_u32_e32 v36, 32, v42
	v_lshl_add_u64 v[50:51], v[138:139], 0, s[28:29]
	v_ldexp_f32 v36, v43, v36
	v_fmamk_f32 v36, v36, 0x30800000, v168
	v_cvt_pk_bf16_f32 v33, v38, v39
	v_cvt_pk_bf16_f32 v34, v34, v35
	v_rsq_f32_e32 v36, v36
	v_cvt_pk_bf16_f32 v35, v40, v41
	global_store_dwordx4 v[50:51], v[32:35], off offset:256 nt
	s_nop 1
	v_mov_b32_e32 v32, v36
	v_mul_f32_e32 v32, v200, v32
	v_pk_mul_f32 v[28:29], v[28:29], v[32:33] op_sel_hi:[1,0]
	v_pk_mul_f32 v[30:31], v[30:31], v[32:33] op_sel_hi:[1,0]
	v_pk_mul_f32 v[36:37], v[26:27], v[32:33] op_sel_hi:[1,0]
	v_pk_mul_f32 v[26:27], v[24:25], v[32:33] op_sel_hi:[1,0]
	v_cvt_pk_bf16_f32 v24, v28, v29
	v_add_co_u32_e32 v28, vcc, s67, v138
	v_cvt_pk_bf16_f32 v25, v30, v31
	v_cvt_pk_bf16_f32 v26, v26, v27
	v_cvt_pk_bf16_f32 v27, v36, v37
	v_addc_co_u32_e32 v29, vcc, 0, v139, vcc
	global_store_dwordx4 v[28:29], v[24:27], off nt
	v_pk_mul_f32 v[20:21], v[20:21], v[32:33] op_sel_hi:[1,0]
	v_pk_mul_f32 v[22:23], v[22:23], v[32:33] op_sel_hi:[1,0]
	v_pk_mul_f32 v[24:25], v[18:19], v[32:33] op_sel_hi:[1,0]
	v_pk_mul_f32 v[18:19], v[16:17], v[32:33] op_sel_hi:[1,0]
	v_ffbh_u32_e32 v16, v157
	v_min_u32_e32 v26, 32, v16
	v_lshlrev_b64 v[16:17], v26, v[156:157]
	v_min_u32_e32 v16, 1, v16
	v_or_b32_e32 v16, v17, v16
	v_cvt_f32_u32_e32 v27, v16
	v_cvt_pk_bf16_f32 v16, v20, v21
	v_sub_u32_e32 v20, 32, v26
	v_lshl_add_u64 v[34:35], v[138:139], 0, s[30:31]
	v_ldexp_f32 v20, v27, v20
	v_fmamk_f32 v20, v20, 0x30800000, v168
	v_cvt_pk_bf16_f32 v17, v22, v23
	v_cvt_pk_bf16_f32 v18, v18, v19
	v_rsq_f32_e32 v20, v20
	v_cvt_pk_bf16_f32 v19, v24, v25
	global_store_dwordx4 v[34:35], v[16:19], off offset:256 nt
	s_nop 1
	v_mov_b32_e32 v16, v20
	v_mul_f32_e32 v16, v200, v16
	v_pk_mul_f32 v[12:13], v[12:13], v[16:17] op_sel_hi:[1,0]
	v_pk_mul_f32 v[14:15], v[14:15], v[16:17] op_sel_hi:[1,0]
	v_pk_mul_f32 v[20:21], v[10:11], v[16:17] op_sel_hi:[1,0]
	v_pk_mul_f32 v[10:11], v[8:9], v[16:17] op_sel_hi:[1,0]
	v_cvt_pk_bf16_f32 v8, v12, v13
	v_add_co_u32_e32 v12, vcc, s68, v138
	v_cvt_pk_bf16_f32 v9, v14, v15
	v_cvt_pk_bf16_f32 v10, v10, v11
	v_cvt_pk_bf16_f32 v11, v20, v21
	v_addc_co_u32_e32 v13, vcc, 0, v139, vcc
	global_store_dwordx4 v[12:13], v[8:11], off nt
	v_pk_mul_f32 v[6:7], v[6:7], v[16:17] op_sel_hi:[1,0]
	v_pk_mul_f32 v[4:5], v[4:5], v[16:17] op_sel_hi:[1,0]
	v_pk_mul_f32 v[8:9], v[2:3], v[16:17] op_sel_hi:[1,0]
	v_pk_mul_f32 v[2:3], v[0:1], v[16:17] op_sel_hi:[1,0]
	v_lshl_add_u64 v[18:19], v[138:139], 0, s[36:37]
	v_cvt_pk_bf16_f32 v0, v4, v5
	v_cvt_pk_bf16_f32 v1, v6, v7
	v_cvt_pk_bf16_f32 v2, v2, v3
	v_cvt_pk_bf16_f32 v3, v8, v9
	s_andn2_b64 vcc, exec, s[4:5]
	global_store_dwordx4 v[18:19], v[0:3], off offset:256 nt
	s_cbranch_vccnz .LBB0_548
	s_andn2_b64 vcc, exec, s[10:11]
	s_cbranch_vccnz .LBB0_547
	s_barrier
	s_branch .LBB0_547

.LBB0_728:
	s_lshl_b32 s22, s36, 8
	s_add_i32 s22, s22, s45
	v_or_b32_e32 v130, s22, v170
	v_ashrrev_i32_e32 v131, 31, v130
	v_lshl_or_b32 v128, s58, 8, v153
	v_lshlrev_b64 v[130:131], 11, v[130:131]
	v_ashrrev_i32_e32 v129, 31, v128
	v_lshl_add_u64 v[130:131], s[84:85], 0, v[130:131]
	v_lshl_add_u64 v[164:165], v[128:129], 1, v[130:131]
	global_load_dwordx4 v[190:193], v[164:165], off
	global_load_dwordx4 v[196:199], v[164:165], off offset:256
	v_add_co_u32_e32 v212, vcc, s49, v164
	v_and_b32_e32 v129, 64, v186
	s_nop 0
	v_addc_co_u32_e32 v213, vcc, 0, v165, vcc
	global_load_dwordx4 v[200:203], v[212:213], off
	v_xor_b32_e32 v128, 16, v186
	v_add_u32_e32 v129, 64, v129
	v_xor_b32_e32 v130, 32, v186
	v_cmp_lt_i32_e32 vcc, v128, v129
	s_waitcnt vmcnt(0)
	v_lshlrev_b32_e32 v214, 16, v190
	v_cndmask_b32_e32 v128, v186, v128, vcc
	v_cmp_lt_i32_e32 vcc, v130, v129
	v_lshlrev_b32_e32 v188, 2, v128
	v_and_b32_e32 v215, 0xffff0000, v190
	v_cndmask_b32_e32 v129, v186, v130, vcc
	v_add_co_u32_e32 v168, vcc, s44, v164
	v_lshlrev_b32_e32 v187, 2, v129
	s_nop 0
	v_addc_co_u32_e32 v169, vcc, 0, v165, vcc
	v_add_co_u32_e32 v166, vcc, s48, v164
	v_lshlrev_b32_e32 v190, 16, v191
	s_nop 0
	v_addc_co_u32_e32 v167, vcc, 0, v165, vcc
	global_load_dwordx4 v[204:207], v[212:213], off offset:256
	global_load_dwordx4 v[208:211], v[168:169], off
	global_load_dwordx4 v[136:139], v[168:169], off offset:256
	global_load_dwordx4 v[132:135], v[166:167], off
	global_load_dwordx4 v[128:131], v[166:167], off offset:256
	v_and_b32_e32 v191, 0xffff0000, v191
	v_lshlrev_b32_e32 v216, 16, v192
	v_and_b32_e32 v217, 0xffff0000, v192
	v_lshlrev_b32_e32 v192, 16, v193
	v_and_b32_e32 v193, 0xffff0000, v193
	v_lshlrev_b32_e32 v218, 16, v196
	v_and_b32_e32 v219, 0xffff0000, v196
	v_lshlrev_b32_e32 v196, 16, v197
	v_and_b32_e32 v197, 0xffff0000, v197
	v_lshlrev_b32_e32 v220, 16, v198
	v_and_b32_e32 v221, 0xffff0000, v198
	v_lshlrev_b32_e32 v198, 16, v199
	v_and_b32_e32 v199, 0xffff0000, v199
	v_pk_add_f32 v[126:127], v[126:127], v[190:191]
	v_pk_add_f32 v[124:125], v[124:125], v[214:215]
	v_pk_add_f32 v[122:123], v[122:123], v[192:193]
	v_pk_add_f32 v[190:191], v[118:119], v[196:197]
	v_pk_add_f32 v[192:193], v[116:117], v[218:219]
	v_pk_add_f32 v[120:121], v[120:121], v[216:217]
	v_pk_add_f32 v[196:197], v[114:115], v[198:199]
	v_pk_add_f32 v[198:199], v[112:113], v[220:221]
	v_cvt_pk_bf16_f32 v112, v124, v125
	v_cvt_pk_bf16_f32 v113, v126, v127
	v_mul_f32_e32 v125, v125, v125
	v_mul_f32_e32 v127, v127, v127
	v_cvt_pk_bf16_f32 v117, v190, v191
	v_mul_f32_e32 v189, v193, v193
	v_mul_f32_e32 v191, v191, v191
	v_cvt_pk_bf16_f32 v114, v120, v121
	v_cvt_pk_bf16_f32 v115, v122, v123
	v_mul_f32_e32 v121, v121, v121
	v_cvt_pk_bf16_f32 v116, v192, v193
	v_mul_f32_e32 v193, v199, v199
	v_fmac_f32_e32 v125, v124, v124
	v_fmac_f32_e32 v127, v126, v126
	v_fmac_f32_e32 v189, v192, v192
	v_fmac_f32_e32 v191, v190, v190
	v_mul_f32_e32 v123, v123, v123
	v_cvt_pk_bf16_f32 v119, v196, v197
	v_mul_f32_e32 v197, v197, v197
	global_store_dwordx4 v[164:165], v[112:115], off nt
	v_fmac_f32_e32 v121, v120, v120
	v_fmac_f32_e32 v193, v198, v198
	v_add_f32_e32 v112, v125, v127
	v_add_f32_e32 v113, v189, v191
	v_fmac_f32_e32 v123, v122, v122
	v_fmac_f32_e32 v197, v196, v196
	v_add_f32_e32 v112, v121, v112
	v_add_f32_e32 v113, v193, v113
	v_cvt_pk_bf16_f32 v118, v198, v199
	v_add_f32_e32 v112, v123, v112
	v_add_f32_e32 v113, v197, v113
	global_store_dwordx4 v[164:165], v[116:119], off offset:256 nt
	v_add_f32_e32 v120, v112, v113
	v_lshlrev_b32_e32 v112, 16, v200
	v_and_b32_e32 v113, 0xffff0000, v200
	v_lshlrev_b32_e32 v114, 16, v201
	v_and_b32_e32 v115, 0xffff0000, v201
	v_lshlrev_b32_e32 v116, 16, v202
	v_and_b32_e32 v117, 0xffff0000, v202
	v_lshlrev_b32_e32 v118, 16, v203
	v_and_b32_e32 v119, 0xffff0000, v203
	v_pk_add_f32 v[110:111], v[110:111], v[114:115]
	v_pk_add_f32 v[108:109], v[108:109], v[112:113]
	v_pk_add_f32 v[112:113], v[106:107], v[118:119]
	v_pk_add_f32 v[114:115], v[104:105], v[116:117]
	v_cvt_pk_bf16_f32 v104, v108, v109
	v_cvt_pk_bf16_f32 v105, v110, v111
	v_cvt_pk_bf16_f32 v106, v114, v115
	v_cvt_pk_bf16_f32 v107, v112, v113
	global_store_dwordx4 v[212:213], v[104:107], off nt
	v_cmp_lt_i32_e32 vcc, 0, v171
	s_nop 0
	v_mul_f32_e32 v104, v109, v109
	v_mul_f32_e32 v105, v111, v111
	v_fmac_f32_e32 v104, v108, v108
	v_fmac_f32_e32 v105, v110, v110
	v_add_f32_e32 v104, v104, v105
	v_mul_f32_e32 v105, v115, v115
	v_fmac_f32_e32 v105, v114, v114
	v_add_f32_e32 v104, v105, v104
	v_mul_f32_e32 v105, v113, v113
	v_fmac_f32_e32 v105, v112, v112
	v_add_f32_e32 v112, v105, v104
	s_waitcnt vmcnt(7)
	v_lshlrev_b32_e32 v104, 16, v204
	v_and_b32_e32 v105, 0xffff0000, v204
	v_lshlrev_b32_e32 v106, 16, v205
	v_and_b32_e32 v107, 0xffff0000, v205
	v_lshlrev_b32_e32 v108, 16, v206
	v_and_b32_e32 v109, 0xffff0000, v206
	v_lshlrev_b32_e32 v110, 16, v207
	v_and_b32_e32 v111, 0xffff0000, v207
	v_pk_add_f32 v[102:103], v[102:103], v[106:107]
	v_pk_add_f32 v[100:101], v[100:101], v[104:105]
	v_pk_add_f32 v[104:105], v[98:99], v[110:111]
	v_pk_add_f32 v[106:107], v[96:97], v[108:109]
	v_cvt_pk_bf16_f32 v96, v100, v101
	v_cvt_pk_bf16_f32 v97, v102, v103
	v_cvt_pk_bf16_f32 v98, v106, v107
	v_cvt_pk_bf16_f32 v99, v104, v105
	global_store_dwordx4 v[212:213], v[96:99], off offset:256 nt
	s_nop 1
	v_mul_f32_e32 v96, v101, v101
	v_mul_f32_e32 v97, v103, v103
	v_fmac_f32_e32 v96, v100, v100
	v_fmac_f32_e32 v97, v102, v102
	v_add_f32_e32 v96, v96, v97
	v_mul_f32_e32 v97, v107, v107
	v_fmac_f32_e32 v97, v106, v106
	v_add_f32_e32 v96, v97, v96
	v_mul_f32_e32 v97, v105, v105
	v_fmac_f32_e32 v97, v104, v104
	v_add_f32_e32 v96, v97, v96
	v_add_f32_e32 v104, v112, v96
	s_waitcnt vmcnt(7)
	v_lshlrev_b32_e32 v96, 16, v208
	v_and_b32_e32 v97, 0xffff0000, v208
	v_lshlrev_b32_e32 v98, 16, v209
	v_and_b32_e32 v99, 0xffff0000, v209
	v_lshlrev_b32_e32 v100, 16, v210
	v_and_b32_e32 v101, 0xffff0000, v210
	v_lshlrev_b32_e32 v102, 16, v211
	v_and_b32_e32 v103, 0xffff0000, v211
	v_pk_add_f32 v[94:95], v[94:95], v[98:99]
	v_pk_add_f32 v[92:93], v[92:93], v[96:97]
	v_pk_add_f32 v[96:97], v[90:91], v[102:103]
	v_pk_add_f32 v[98:99], v[88:89], v[100:101]
	v_cvt_pk_bf16_f32 v88, v92, v93
	v_cvt_pk_bf16_f32 v89, v94, v95
	v_cvt_pk_bf16_f32 v90, v98, v99
	v_cvt_pk_bf16_f32 v91, v96, v97
	global_store_dwordx4 v[168:169], v[88:91], off nt
	s_nop 1
	v_mul_f32_e32 v88, v93, v93
	v_mul_f32_e32 v89, v95, v95
	v_fmac_f32_e32 v88, v92, v92
	v_fmac_f32_e32 v89, v94, v94
	v_add_f32_e32 v88, v88, v89
	v_mul_f32_e32 v89, v99, v99
	v_fmac_f32_e32 v89, v98, v98
	v_add_f32_e32 v88, v89, v88
	v_mul_f32_e32 v89, v97, v97
	v_fmac_f32_e32 v89, v96, v96
	v_add_f32_e32 v96, v89, v88
	s_waitcnt vmcnt(7)
	v_lshlrev_b32_e32 v88, 16, v136
	v_and_b32_e32 v89, 0xffff0000, v136
	v_lshlrev_b32_e32 v90, 16, v137
	v_and_b32_e32 v91, 0xffff0000, v137
	v_lshlrev_b32_e32 v92, 16, v138
	v_and_b32_e32 v93, 0xffff0000, v138
	v_lshlrev_b32_e32 v94, 16, v139
	v_and_b32_e32 v95, 0xffff0000, v139
	v_pk_add_f32 v[86:87], v[86:87], v[90:91]
	v_pk_add_f32 v[84:85], v[84:85], v[88:89]
	v_pk_add_f32 v[88:89], v[82:83], v[94:95]
	v_pk_add_f32 v[90:91], v[80:81], v[92:93]
	v_cvt_pk_bf16_f32 v80, v84, v85
	v_cvt_pk_bf16_f32 v81, v86, v87
	v_cvt_pk_bf16_f32 v82, v90, v91
	v_cvt_pk_bf16_f32 v83, v88, v89
	global_store_dwordx4 v[168:169], v[80:83], off offset:256 nt
	s_nop 1
	v_mul_f32_e32 v80, v85, v85
	v_mul_f32_e32 v81, v87, v87
	v_fmac_f32_e32 v80, v84, v84
	v_fmac_f32_e32 v81, v86, v86
	v_add_f32_e32 v80, v80, v81
	v_mul_f32_e32 v81, v91, v91
	v_fmac_f32_e32 v81, v90, v90
	v_add_f32_e32 v80, v81, v80
	v_mul_f32_e32 v81, v89, v89
	v_fmac_f32_e32 v81, v88, v88
	v_add_f32_e32 v80, v81, v80
	v_add_f32_e32 v88, v96, v80
	s_waitcnt vmcnt(7)
	v_lshlrev_b32_e32 v80, 16, v132
	v_and_b32_e32 v81, 0xffff0000, v132
	v_lshlrev_b32_e32 v82, 16, v133
	v_and_b32_e32 v83, 0xffff0000, v133
	v_lshlrev_b32_e32 v84, 16, v134
	v_and_b32_e32 v85, 0xffff0000, v134
	v_lshlrev_b32_e32 v86, 16, v135
	v_and_b32_e32 v87, 0xffff0000, v135
	v_pk_add_f32 v[78:79], v[78:79], v[82:83]
	v_pk_add_f32 v[76:77], v[76:77], v[80:81]
	v_pk_add_f32 v[80:81], v[74:75], v[86:87]
	v_pk_add_f32 v[82:83], v[72:73], v[84:85]
	v_cvt_pk_bf16_f32 v72, v76, v77
	v_cvt_pk_bf16_f32 v73, v78, v79
	v_cvt_pk_bf16_f32 v74, v82, v83
	v_cvt_pk_bf16_f32 v75, v80, v81
	global_store_dwordx4 v[166:167], v[72:75], off nt
	s_nop 1
	v_mul_f32_e32 v72, v77, v77
	v_mul_f32_e32 v73, v79, v79
	v_fmac_f32_e32 v72, v76, v76
	v_fmac_f32_e32 v73, v78, v78
	v_add_f32_e32 v72, v72, v73
	v_mul_f32_e32 v73, v83, v83
	v_fmac_f32_e32 v73, v82, v82
	v_add_f32_e32 v72, v73, v72
	v_mul_f32_e32 v73, v81, v81
	v_fmac_f32_e32 v73, v80, v80
	v_add_f32_e32 v82, v73, v72
	s_waitcnt vmcnt(7)
	v_lshlrev_b32_e32 v72, 16, v128
	v_and_b32_e32 v73, 0xffff0000, v128
	v_lshlrev_b32_e32 v74, 16, v129
	v_and_b32_e32 v75, 0xffff0000, v129
	v_lshlrev_b32_e32 v76, 16, v130
	v_and_b32_e32 v77, 0xffff0000, v130
	v_pk_add_f32 v[80:81], v[70:71], v[74:75]
	v_pk_add_f32 v[68:69], v[68:69], v[72:73]
	v_pk_add_f32 v[76:77], v[64:65], v[76:77]
	v_mul_f32_e32 v64, v69, v69
	v_mul_f32_e32 v65, v81, v81
	v_fmac_f32_e32 v64, v68, v68
	v_fmac_f32_e32 v65, v80, v80
	v_lshlrev_b32_e32 v78, 16, v131
	v_and_b32_e32 v79, 0xffff0000, v131
	v_add_f32_e32 v64, v64, v65
	v_mul_f32_e32 v65, v77, v77
	v_pk_add_f32 v[78:79], v[66:67], v[78:79]
	v_fmac_f32_e32 v65, v76, v76
	v_add_f32_e32 v64, v65, v64
	v_mul_f32_e32 v65, v79, v79
	v_fmac_f32_e32 v65, v78, v78
	v_add_f32_e32 v64, v65, v64
	v_add_f32_e32 v64, v82, v64
	v_cvt_pk_bf16_f32 v74, v68, v69
	ds_bpermute_b32 v66, v188, v120
	ds_bpermute_b32 v65, v188, v104
	ds_bpermute_b32 v69, v188, v88
	ds_bpermute_b32 v71, v188, v64
	v_cvt_pk_bf16_f32 v75, v80, v81
	s_waitcnt lgkmcnt(3)
	v_add_f32_e32 v67, v120, v66
	s_waitcnt lgkmcnt(2)
	v_add_f32_e32 v65, v104, v65
	s_waitcnt lgkmcnt(1)
	v_add_f32_e32 v69, v88, v69
	s_waitcnt lgkmcnt(0)
	v_add_f32_e32 v71, v64, v71
	ds_bpermute_b32 v68, v187, v67
	ds_bpermute_b32 v66, v187, v65
	ds_bpermute_b32 v70, v187, v69
	ds_bpermute_b32 v72, v187, v71
	v_cvt_pk_bf16_f32 v76, v76, v77
	v_cvt_pk_bf16_f32 v77, v78, v79
	global_store_dwordx4 v[166:167], v[74:77], off offset:256 nt
	s_and_saveexec_b64 s[2:3], vcc
	s_xor_b64 s[2:3], exec, s[2:3]
	s_cbranch_execz .LBB0_734
	v_cmp_ne_u32_e32 vcc, 1, v171
	s_and_saveexec_b64 s[14:15], vcc
	s_xor_b64 s[14:15], exec, s[14:15]
	s_cbranch_execz .LBB0_731
	s_waitcnt lgkmcnt(0)
	v_add_f32_e32 v64, v71, v72
	v_add_f32_e32 v65, v69, v70
	v_cndmask_b32_e64 v64, v64, v65, s[4:5]

.LBB0_736:
	s_or_b64 exec, exec, s[2:3]
	v_mul_f32_e32 v64, 0x49800000, v64
	v_trunc_f32_e32 v64, v64
	v_mul_f32_e32 v65, 0x2f800000, v64
	v_floor_f32_e32 v65, v65
	v_fmac_f32_e32 v64, 0xcf800000, v65
	v_cvt_u32_f32_e32 v64, v64
	v_cvt_u32_f32_e32 v65, v65
	v_or_b32_e32 v76, s22, v151
	v_ashrrev_i32_e32 v77, 31, v76
	s_waitcnt lgkmcnt(2)
	v_lshl_add_u64 v[66:67], v[76:77], 3, s[10:11]
	v_add_co_u32_e32 v102, vcc, s54, v164
	global_atomic_add_x2 v[66:67], v[64:65], off
	s_nop 0
	v_addc_co_u32_e32 v103, vcc, 0, v165, vcc
	global_load_dwordx4 v[82:85], v[102:103], off
	global_load_dwordx4 v[86:89], v[102:103], off offset:256
	v_add_co_u32_e32 v104, vcc, s55, v164
	s_waitcnt vmcnt(1)
	v_lshlrev_b32_e32 v106, 16, v82
	v_addc_co_u32_e32 v105, vcc, 0, v165, vcc
	global_load_dwordx4 v[90:93], v[104:105], off
	v_add_co_u32_e32 v80, vcc, s56, v164
	v_and_b32_e32 v107, 0xffff0000, v82
	s_nop 0
	v_addc_co_u32_e32 v81, vcc, 0, v165, vcc
	v_add_co_u32_e32 v78, vcc, s57, v164
	v_lshlrev_b32_e32 v82, 16, v83
	s_nop 0
	v_addc_co_u32_e32 v79, vcc, 0, v165, vcc
	global_load_dwordx4 v[94:97], v[104:105], off offset:256
	global_load_dwordx4 v[98:101], v[80:81], off
	s_waitcnt lgkmcnt(0)
	global_load_dwordx4 v[72:75], v[80:81], off offset:256
	global_load_dwordx4 v[68:71], v[78:79], off
	global_load_dwordx4 v[64:67], v[78:79], off offset:256
	v_and_b32_e32 v83, 0xffff0000, v83
	v_lshlrev_b32_e32 v108, 16, v84
	v_and_b32_e32 v109, 0xffff0000, v84
	v_lshlrev_b32_e32 v84, 16, v85
	v_and_b32_e32 v85, 0xffff0000, v85
	s_waitcnt vmcnt(6)
	v_lshlrev_b32_e32 v110, 16, v86
	v_and_b32_e32 v111, 0xffff0000, v86
	v_lshlrev_b32_e32 v86, 16, v87
	v_and_b32_e32 v87, 0xffff0000, v87
	v_lshlrev_b32_e32 v112, 16, v88
	v_and_b32_e32 v113, 0xffff0000, v88
	v_lshlrev_b32_e32 v88, 16, v89
	v_and_b32_e32 v89, 0xffff0000, v89
	v_pk_add_f32 v[62:63], v[62:63], v[82:83]
	v_pk_add_f32 v[60:61], v[60:61], v[106:107]
	v_pk_add_f32 v[58:59], v[58:59], v[84:85]
	v_pk_add_f32 v[82:83], v[54:55], v[86:87]
	v_pk_add_f32 v[84:85], v[52:53], v[110:111]
	v_pk_add_f32 v[56:57], v[56:57], v[108:109]
	v_pk_add_f32 v[86:87], v[50:51], v[88:89]
	v_pk_add_f32 v[88:89], v[48:49], v[112:113]
	v_cvt_pk_bf16_f32 v48, v60, v61
	v_cvt_pk_bf16_f32 v49, v62, v63
	v_mul_f32_e32 v61, v61, v61
	v_mul_f32_e32 v63, v63, v63
	v_cvt_pk_bf16_f32 v53, v82, v83
	v_mul_f32_e32 v77, v85, v85
	v_mul_f32_e32 v83, v83, v83
	v_cvt_pk_bf16_f32 v50, v56, v57
	v_cvt_pk_bf16_f32 v51, v58, v59
	v_mul_f32_e32 v57, v57, v57
	v_cvt_pk_bf16_f32 v52, v84, v85
	v_mul_f32_e32 v85, v89, v89
	v_fmac_f32_e32 v61, v60, v60
	v_fmac_f32_e32 v63, v62, v62
	v_fmac_f32_e32 v77, v84, v84
	v_fmac_f32_e32 v83, v82, v82
	v_mul_f32_e32 v59, v59, v59
	v_cvt_pk_bf16_f32 v55, v86, v87
	v_mul_f32_e32 v87, v87, v87
	global_store_dwordx4 v[102:103], v[48:51], off nt
	v_fmac_f32_e32 v57, v56, v56
	v_fmac_f32_e32 v85, v88, v88
	v_add_f32_e32 v48, v61, v63
	v_add_f32_e32 v49, v77, v83
	v_fmac_f32_e32 v59, v58, v58
	v_fmac_f32_e32 v87, v86, v86
	v_add_f32_e32 v48, v57, v48
	v_add_f32_e32 v49, v85, v49
	v_cvt_pk_bf16_f32 v54, v88, v89
	v_add_f32_e32 v48, v59, v48
	v_add_f32_e32 v49, v87, v49
	global_store_dwordx4 v[102:103], v[52:55], off offset:256 nt
	v_cmp_lt_i32_e32 vcc, 0, v171
	s_waitcnt vmcnt(7)
	v_lshlrev_b32_e32 v114, 16, v90
	v_and_b32_e32 v115, 0xffff0000, v90
	v_add_f32_e32 v54, v48, v49
	v_lshlrev_b32_e32 v48, 16, v91
	v_and_b32_e32 v49, 0xffff0000, v91
	v_lshlrev_b32_e32 v50, 16, v92
	v_and_b32_e32 v51, 0xffff0000, v92
	v_lshlrev_b32_e32 v52, 16, v93
	v_and_b32_e32 v53, 0xffff0000, v93
	v_pk_add_f32 v[46:47], v[46:47], v[48:49]
	v_pk_add_f32 v[44:45], v[44:45], v[114:115]
	v_pk_add_f32 v[48:49], v[42:43], v[52:53]
	v_pk_add_f32 v[50:51], v[40:41], v[50:51]
	v_cvt_pk_bf16_f32 v40, v44, v45
	v_cvt_pk_bf16_f32 v41, v46, v47
	v_cvt_pk_bf16_f32 v42, v50, v51
	v_cvt_pk_bf16_f32 v43, v48, v49
	global_store_dwordx4 v[104:105], v[40:43], off nt
	s_nop 1
	v_mul_f32_e32 v40, v45, v45
	v_mul_f32_e32 v41, v47, v47
	v_fmac_f32_e32 v40, v44, v44
	v_fmac_f32_e32 v41, v46, v46
	v_add_f32_e32 v40, v40, v41
	v_mul_f32_e32 v41, v51, v51
	v_fmac_f32_e32 v41, v50, v50
	v_add_f32_e32 v40, v41, v40
	v_mul_f32_e32 v41, v49, v49
	v_fmac_f32_e32 v41, v48, v48
	v_add_f32_e32 v48, v41, v40
	s_waitcnt vmcnt(7)
	v_lshlrev_b32_e32 v40, 16, v94
	v_and_b32_e32 v41, 0xffff0000, v94
	v_lshlrev_b32_e32 v42, 16, v95
	v_and_b32_e32 v43, 0xffff0000, v95
	v_lshlrev_b32_e32 v44, 16, v96
	v_and_b32_e32 v45, 0xffff0000, v96
	v_lshlrev_b32_e32 v46, 16, v97
	v_and_b32_e32 v47, 0xffff0000, v97
	v_pk_add_f32 v[38:39], v[38:39], v[42:43]
	v_pk_add_f32 v[36:37], v[36:37], v[40:41]
	v_pk_add_f32 v[40:41], v[34:35], v[46:47]
	v_pk_add_f32 v[42:43], v[32:33], v[44:45]
	v_cvt_pk_bf16_f32 v32, v36, v37
	v_cvt_pk_bf16_f32 v33, v38, v39
	v_cvt_pk_bf16_f32 v34, v42, v43
	v_cvt_pk_bf16_f32 v35, v40, v41
	global_store_dwordx4 v[104:105], v[32:35], off offset:256 nt
	s_nop 1
	v_mul_f32_e32 v32, v37, v37
	v_mul_f32_e32 v33, v39, v39
	v_fmac_f32_e32 v32, v36, v36
	v_fmac_f32_e32 v33, v38, v38
	v_add_f32_e32 v32, v32, v33
	v_mul_f32_e32 v33, v43, v43
	v_fmac_f32_e32 v33, v42, v42
	v_add_f32_e32 v32, v33, v32
	v_mul_f32_e32 v33, v41, v41
	v_fmac_f32_e32 v33, v40, v40
	v_add_f32_e32 v32, v33, v32
	v_add_f32_e32 v40, v48, v32
	s_waitcnt vmcnt(7)
	v_lshlrev_b32_e32 v32, 16, v98
	v_and_b32_e32 v33, 0xffff0000, v98
	v_lshlrev_b32_e32 v34, 16, v99
	v_and_b32_e32 v35, 0xffff0000, v99
	v_lshlrev_b32_e32 v36, 16, v100
	v_and_b32_e32 v37, 0xffff0000, v100
	v_lshlrev_b32_e32 v38, 16, v101
	v_and_b32_e32 v39, 0xffff0000, v101
	v_pk_add_f32 v[30:31], v[30:31], v[34:35]
	v_pk_add_f32 v[28:29], v[28:29], v[32:33]
	v_pk_add_f32 v[32:33], v[26:27], v[38:39]
	v_pk_add_f32 v[34:35], v[24:25], v[36:37]
	v_cvt_pk_bf16_f32 v24, v28, v29
	v_cvt_pk_bf16_f32 v25, v30, v31
	v_cvt_pk_bf16_f32 v26, v34, v35
	v_cvt_pk_bf16_f32 v27, v32, v33
	global_store_dwordx4 v[80:81], v[24:27], off nt
	s_nop 1
	v_mul_f32_e32 v24, v29, v29
	v_mul_f32_e32 v25, v31, v31
	v_fmac_f32_e32 v24, v28, v28
	v_fmac_f32_e32 v25, v30, v30
	v_add_f32_e32 v24, v24, v25
	v_mul_f32_e32 v25, v35, v35
	v_fmac_f32_e32 v25, v34, v34
	v_add_f32_e32 v24, v25, v24
	v_mul_f32_e32 v25, v33, v33
	v_fmac_f32_e32 v25, v32, v32
	v_add_f32_e32 v32, v25, v24
	s_waitcnt vmcnt(7)
	v_lshlrev_b32_e32 v24, 16, v72
	v_and_b32_e32 v25, 0xffff0000, v72
	v_lshlrev_b32_e32 v26, 16, v73
	v_and_b32_e32 v27, 0xffff0000, v73
	v_lshlrev_b32_e32 v28, 16, v74
	v_and_b32_e32 v29, 0xffff0000, v74
	v_lshlrev_b32_e32 v30, 16, v75
	v_and_b32_e32 v31, 0xffff0000, v75
	v_pk_add_f32 v[22:23], v[22:23], v[26:27]
	v_pk_add_f32 v[20:21], v[20:21], v[24:25]
	v_pk_add_f32 v[24:25], v[18:19], v[30:31]
	v_pk_add_f32 v[26:27], v[16:17], v[28:29]
	v_cvt_pk_bf16_f32 v16, v20, v21
	v_cvt_pk_bf16_f32 v17, v22, v23
	v_cvt_pk_bf16_f32 v18, v26, v27
	v_cvt_pk_bf16_f32 v19, v24, v25
	global_store_dwordx4 v[80:81], v[16:19], off offset:256 nt
	s_nop 1
	v_mul_f32_e32 v16, v21, v21
	v_mul_f32_e32 v17, v23, v23
	v_fmac_f32_e32 v16, v20, v20
	v_fmac_f32_e32 v17, v22, v22
	v_add_f32_e32 v16, v16, v17
	v_mul_f32_e32 v17, v27, v27
	v_fmac_f32_e32 v17, v26, v26
	v_add_f32_e32 v16, v17, v16
	v_mul_f32_e32 v17, v25, v25
	v_fmac_f32_e32 v17, v24, v24
	v_add_f32_e32 v16, v17, v16
	v_add_f32_e32 v24, v32, v16
	s_waitcnt vmcnt(7)
	v_lshlrev_b32_e32 v16, 16, v68
	v_and_b32_e32 v17, 0xffff0000, v68
	v_lshlrev_b32_e32 v18, 16, v69
	v_and_b32_e32 v19, 0xffff0000, v69
	v_lshlrev_b32_e32 v20, 16, v70
	v_and_b32_e32 v21, 0xffff0000, v70
	v_lshlrev_b32_e32 v22, 16, v71
	v_and_b32_e32 v23, 0xffff0000, v71
	v_pk_add_f32 v[14:15], v[14:15], v[18:19]
	v_pk_add_f32 v[12:13], v[12:13], v[16:17]
	v_pk_add_f32 v[16:17], v[10:11], v[22:23]
	v_pk_add_f32 v[18:19], v[8:9], v[20:21]
	v_cvt_pk_bf16_f32 v8, v12, v13
	v_cvt_pk_bf16_f32 v9, v14, v15
	v_cvt_pk_bf16_f32 v10, v18, v19
	v_cvt_pk_bf16_f32 v11, v16, v17
	global_store_dwordx4 v[78:79], v[8:11], off nt
	s_nop 1
	v_mul_f32_e32 v8, v13, v13
	v_mul_f32_e32 v9, v15, v15
	v_fmac_f32_e32 v8, v12, v12
	v_fmac_f32_e32 v9, v14, v14
	v_add_f32_e32 v8, v8, v9
	v_mul_f32_e32 v9, v19, v19
	v_fmac_f32_e32 v9, v18, v18
	v_add_f32_e32 v8, v9, v8
	v_mul_f32_e32 v9, v17, v17
	v_fmac_f32_e32 v9, v16, v16
	v_add_f32_e32 v18, v9, v8
	s_waitcnt vmcnt(7)
	v_lshlrev_b32_e32 v8, 16, v64
	v_and_b32_e32 v9, 0xffff0000, v64
	v_lshlrev_b32_e32 v10, 16, v65
	v_and_b32_e32 v11, 0xffff0000, v65
	v_lshlrev_b32_e32 v12, 16, v66
	v_and_b32_e32 v13, 0xffff0000, v66
	v_pk_add_f32 v[16:17], v[6:7], v[10:11]
	v_pk_add_f32 v[4:5], v[4:5], v[8:9]
	v_pk_add_f32 v[12:13], v[0:1], v[12:13]
	v_mul_f32_e32 v0, v5, v5
	v_mul_f32_e32 v1, v17, v17
	v_fmac_f32_e32 v0, v4, v4
	v_fmac_f32_e32 v1, v16, v16
	v_lshlrev_b32_e32 v14, 16, v67
	v_and_b32_e32 v15, 0xffff0000, v67
	v_add_f32_e32 v0, v0, v1
	v_mul_f32_e32 v1, v13, v13
	v_pk_add_f32 v[14:15], v[2:3], v[14:15]
	v_fmac_f32_e32 v1, v12, v12
	v_add_f32_e32 v0, v1, v0
	v_mul_f32_e32 v1, v15, v15
	v_fmac_f32_e32 v1, v14, v14
	v_add_f32_e32 v0, v1, v0
	v_add_f32_e32 v0, v18, v0
	v_cvt_pk_bf16_f32 v10, v4, v5
	ds_bpermute_b32 v2, v188, v54
	ds_bpermute_b32 v1, v188, v40
	ds_bpermute_b32 v5, v188, v24
	ds_bpermute_b32 v7, v188, v0
	v_cvt_pk_bf16_f32 v11, v16, v17
	s_waitcnt lgkmcnt(3)
	v_add_f32_e32 v3, v54, v2
	s_waitcnt lgkmcnt(2)
	v_add_f32_e32 v1, v40, v1
	s_waitcnt lgkmcnt(1)
	v_add_f32_e32 v5, v24, v5
	s_waitcnt lgkmcnt(0)
	v_add_f32_e32 v7, v0, v7
	ds_bpermute_b32 v4, v187, v3
	ds_bpermute_b32 v2, v187, v1
	ds_bpermute_b32 v6, v187, v5
	ds_bpermute_b32 v8, v187, v7
	v_cvt_pk_bf16_f32 v12, v12, v13
	v_cvt_pk_bf16_f32 v13, v14, v15
	global_store_dwordx4 v[78:79], v[10:13], off offset:256 nt
	s_and_saveexec_b64 s[2:3], vcc
	s_xor_b64 s[2:3], exec, s[2:3]
	s_cbranch_execz .LBB0_742
	v_cmp_ne_u32_e32 vcc, 1, v171
	s_and_saveexec_b64 s[14:15], vcc
	s_xor_b64 s[14:15], exec, s[14:15]
	s_cbranch_execz .LBB0_739
	s_waitcnt lgkmcnt(0)
	v_add_f32_e32 v0, v7, v8
	v_add_f32_e32 v1, v5, v6
	v_cndmask_b32_e64 v0, v0, v1, s[4:5]

.LBB0_812:
	v_lshl_add_u32 v136, s0, 8, v149
	v_ashrrev_i32_e32 v137, 31, v136
	v_lshl_add_u64 v[164:165], v[136:137], 3, s[10:11]
	v_or_b32_e32 v138, 16, v136
	global_load_dwordx2 v[166:167], v[164:165], off
	v_ashrrev_i32_e32 v139, 31, v138
	v_lshl_add_u64 v[156:157], v[138:139], 3, s[10:11]
	global_load_dwordx2 v[168:169], v[156:157], off
	v_lshl_or_b32 v178, s1, 7, v153
	v_pk_mul_f32 v[180:181], v[114:115], v[126:127]
	v_or_b32_e32 v156, 32, v136
	v_or_b32_e32 v126, 48, v136
	v_ashrrev_i32_e32 v179, 31, v178
	v_ashrrev_i32_e32 v157, 31, v156
	v_ashrrev_i32_e32 v127, 31, v126
	v_pk_mul_f32 v[188:189], v[108:109], v[120:121]
	v_mov_b64_e32 v[120:121], s[16:17]
	v_pk_mul_f32 v[190:191], v[106:107], v[118:119]
	v_pk_mul_f32 v[192:193], v[104:105], v[116:117]
	v_lshlrev_b64 v[116:117], 1, v[178:179]
	v_lshl_add_u64 v[118:119], v[156:157], 3, s[10:11]
	v_lshl_add_u64 v[178:179], v[126:127], 3, s[10:11]
	v_pk_mul_f32 v[184:185], v[112:113], v[124:125]
	v_pk_mul_f32 v[186:187], v[110:111], v[122:123]
	v_add_u32_e32 v163, 0x80, v136
	v_add_u32_e32 v162, 0x90, v136
	v_add_u32_e32 v161, 0xa0, v136
	v_add_u32_e32 v139, 0xb0, v136
	v_mad_i64_i32 v[196:197], s[0:1], v136, s49, v[120:121]
	global_load_dwordx2 v[136:137], v[164:165], off offset:1024
	global_load_dwordx2 v[124:125], v[164:165], off offset:1152
	global_load_dwordx2 v[122:123], v[164:165], off offset:1280
	global_load_dwordx2 v[198:199], v[118:119], off
	s_nop 0
	global_load_dwordx2 v[178:179], v[178:179], off
	s_nop 0
	global_load_dwordx2 v[118:119], v[164:165], off offset:1408
	v_pk_mul_f32 v[96:97], v[100:101], v[96:97]
	v_pk_mul_f32 v[98:99], v[102:103], v[98:99]
	v_pk_mul_f32 v[88:89], v[92:93], v[88:89]
	v_pk_mul_f32 v[90:91], v[94:95], v[90:91]
	v_pk_mul_f32 v[80:81], v[84:85], v[80:81]
	v_pk_mul_f32 v[82:83], v[86:87], v[82:83]
	v_pk_mul_f32 v[72:73], v[76:77], v[72:73]
	v_pk_mul_f32 v[74:75], v[78:79], v[74:75]
	v_pk_mul_f32 v[64:65], v[68:69], v[64:65]
	v_pk_mul_f32 v[66:67], v[70:71], v[66:67]
	v_pk_mul_f32 v[56:57], v[60:61], v[56:57]
	v_pk_mul_f32 v[58:59], v[62:63], v[58:59]
	v_pk_mul_f32 v[48:49], v[52:53], v[48:49]
	v_pk_mul_f32 v[50:51], v[54:55], v[50:51]
	v_pk_mul_f32 v[40:41], v[44:45], v[40:41]
	v_pk_mul_f32 v[42:43], v[46:47], v[42:43]
	v_pk_mul_f32 v[32:33], v[36:37], v[32:33]
	v_pk_mul_f32 v[34:35], v[38:39], v[34:35]
	v_pk_mul_f32 v[24:25], v[28:29], v[24:25]
	v_pk_mul_f32 v[26:27], v[30:31], v[26:27]
	v_pk_mul_f32 v[16:17], v[20:21], v[16:17]
	v_pk_mul_f32 v[18:19], v[22:23], v[18:19]
	v_pk_mul_f32 v[8:9], v[12:13], v[8:9]
	v_pk_mul_f32 v[10:11], v[14:15], v[10:11]
	v_pk_mul_f32 v[0:1], v[4:5], v[0:1]
	v_pk_mul_f32 v[2:3], v[6:7], v[2:3]
	s_waitcnt vmcnt(0)
	v_ffbh_u32_e32 v127, v167
	v_min_u32_e32 v127, 32, v127
	v_lshlrev_b64 v[164:165], v127, v[166:167]
	v_ffbh_u32_e32 v157, v169
	v_min_u32_e32 v157, 32, v157
	v_min_u32_e32 v164, 1, v164
	v_lshlrev_b64 v[166:167], v157, v[168:169]
	v_or_b32_e32 v164, v165, v164
	v_min_u32_e32 v165, 1, v166
	v_cvt_f32_u32_e32 v164, v164
	v_or_b32_e32 v165, v167, v165
	v_cvt_f32_u32_e32 v165, v165
	v_sub_u32_e32 v127, 32, v127
	v_ldexp_f32 v127, v164, v127
	v_sub_u32_e32 v157, 32, v157
	v_fmamk_f32 v127, v127, 0x30800000, v160
	v_ldexp_f32 v157, v165, v157
	v_fmamk_f32 v157, v157, 0x30800000, v160
	v_rsq_f32_e32 v127, v127
	v_rsq_f32_e32 v157, v157
	v_lshl_add_u64 v[164:165], v[196:197], 0, v[116:117]
	v_mul_f32_e32 v166, 0xbfb8aa3b, v127
	v_pk_mul_f32 v[112:113], v[112:113], v[166:167] op_sel_hi:[1,0]
	v_pk_mul_f32 v[114:115], v[114:115], v[166:167] op_sel_hi:[1,0]
	v_pk_mul_f32 v[108:109], v[108:109], v[166:167] op_sel_hi:[1,0]
	v_pk_mul_f32 v[110:111], v[110:111], v[166:167] op_sel_hi:[1,0]
	v_exp_f32_e32 v112, v112
	v_exp_f32_e32 v113, v113
	v_exp_f32_e32 v114, v114
	v_exp_f32_e32 v115, v115
	v_exp_f32_e32 v108, v108
	v_exp_f32_e32 v109, v109
	v_exp_f32_e32 v110, v110
	v_exp_f32_e32 v111, v111
	v_mul_f32_e32 v168, v127, v127
	v_mov_b32_e32 v127, v157
	v_mul_f32_e32 v166, 0xbfb8aa3b, v127
	v_pk_mul_f32 v[104:105], v[104:105], v[166:167] op_sel_hi:[1,0]
	v_pk_mul_f32 v[106:107], v[106:107], v[166:167] op_sel_hi:[1,0]
	v_exp_f32_e32 v104, v104
	v_exp_f32_e32 v105, v105
	v_exp_f32_e32 v200, v106
	v_exp_f32_e32 v201, v107
	v_pk_add_f32 v[106:107], v[112:113], 1.0 op_sel_hi:[1,0]
	v_pk_add_f32 v[112:113], v[114:115], 1.0 op_sel_hi:[1,0]
	v_pk_add_f32 v[108:109], v[108:109], 1.0 op_sel_hi:[1,0]
	v_pk_add_f32 v[110:111], v[110:111], 1.0 op_sel_hi:[1,0]
	v_rcp_f32_e32 v106, v106
	v_rcp_f32_e32 v107, v107
	v_rcp_f32_e32 v112, v112
	v_rcp_f32_e32 v113, v113
	v_rcp_f32_e32 v108, v108
	v_rcp_f32_e32 v109, v109
	v_rcp_f32_e32 v110, v110
	v_rcp_f32_e32 v111, v111
	v_pk_add_f32 v[104:105], v[104:105], 1.0 op_sel_hi:[1,0]
	v_pk_mul_f32 v[108:109], v[168:169], v[108:109] op_sel_hi:[0,1]
	v_rcp_f32_e32 v114, v104
	v_rcp_f32_e32 v115, v105
	v_pk_mul_f32 v[104:105], v[168:169], v[106:107] op_sel_hi:[0,1]
	v_pk_mul_f32 v[106:107], v[168:169], v[112:113] op_sel_hi:[0,1]
	v_pk_mul_f32 v[110:111], v[168:169], v[110:111] op_sel_hi:[0,1]
	v_pk_mul_f32 v[104:105], v[184:185], v[104:105]
	v_pk_mul_f32 v[106:107], v[180:181], v[106:107]
	v_pk_mul_f32 v[108:109], v[188:189], v[108:109]
	v_pk_mul_f32 v[110:111], v[186:187], v[110:111]
	v_cvt_pk_bf16_f32 v104, v104, v105
	v_cvt_pk_bf16_f32 v105, v106, v107
	v_cvt_pk_bf16_f32 v106, v108, v109
	v_cvt_pk_bf16_f32 v107, v110, v111
	global_store_dwordx4 v[164:165], v[104:107], off nt
	v_pk_mul_f32 v[108:109], v[100:101], v[166:167] op_sel_hi:[1,0]
	v_mul_f32_e32 v196, v127, v127
	v_pk_add_f32 v[106:107], v[200:201], 1.0 op_sel_hi:[1,0]
	v_exp_f32_e32 v108, v108
	v_rcp_f32_e32 v106, v106
	v_rcp_f32_e32 v107, v107
	v_exp_f32_e32 v109, v109
	v_pk_mul_f32 v[104:105], v[196:197], v[114:115] op_sel_hi:[0,1]
	v_pk_mul_f32 v[104:105], v[192:193], v[104:105]
	v_pk_mul_f32 v[106:107], v[196:197], v[106:107] op_sel_hi:[0,1]
	v_pk_mul_f32 v[106:107], v[190:191], v[106:107]
	v_cvt_pk_bf16_f32 v104, v104, v105
	v_cvt_pk_bf16_f32 v105, v106, v107
	v_pk_add_f32 v[106:107], v[108:109], 1.0 op_sel_hi:[1,0]
	v_pk_mul_f32 v[100:101], v[102:103], v[166:167] op_sel_hi:[1,0]
	v_rcp_f32_e32 v106, v106
	v_rcp_f32_e32 v107, v107
	v_exp_f32_e32 v100, v100
	v_exp_f32_e32 v101, v101
	v_pk_mul_f32 v[102:103], v[196:197], v[106:107] op_sel_hi:[0,1]
	v_pk_mul_f32 v[96:97], v[96:97], v[102:103]
	s_nop 0
	v_cvt_pk_bf16_f32 v106, v96, v97
	v_pk_add_f32 v[96:97], v[100:101], 1.0 op_sel_hi:[1,0]
	v_ffbh_u32_e32 v100, v199
	v_min_u32_e32 v102, 32, v100
	v_lshlrev_b64 v[100:101], v102, v[198:199]
	v_rcp_f32_e32 v96, v96
	v_rcp_f32_e32 v97, v97
	v_min_u32_e32 v100, 1, v100
	v_or_b32_e32 v100, v101, v100
	v_cvt_f32_u32_e32 v100, v100
	v_pk_mul_f32 v[96:97], v[196:197], v[96:97] op_sel_hi:[0,1]
	v_pk_mul_f32 v[96:97], v[98:99], v[96:97]
	v_sub_u32_e32 v98, 32, v102
	v_ldexp_f32 v98, v100, v98
	v_fmamk_f32 v98, v98, 0x30800000, v160
	v_cvt_pk_bf16_f32 v107, v96, v97
	v_mad_i64_i32 v[96:97], s[0:1], v138, s49, v[120:121]
	v_rsq_f32_e32 v98, v98
	v_lshl_add_u64 v[96:97], v[96:97], 0, v[116:117]
	global_store_dwordx4 v[96:97], v[104:107], off nt
	v_mov_b32_e32 v99, v98
	v_mul_f32_e32 v98, 0xbfb8aa3b, v99
	v_pk_mul_f32 v[100:101], v[92:93], v[98:99] op_sel_hi:[1,0]
	v_pk_mul_f32 v[92:93], v[94:95], v[98:99] op_sel_hi:[1,0]
	v_exp_f32_e32 v100, v100
	v_exp_f32_e32 v101, v101
	v_exp_f32_e32 v92, v92
	v_exp_f32_e32 v93, v93
	v_mul_f32_e32 v96, v99, v99
	v_pk_add_f32 v[100:101], v[100:101], 1.0 op_sel_hi:[1,0]
	v_pk_add_f32 v[92:93], v[92:93], 1.0 op_sel_hi:[1,0]
	v_rcp_f32_e32 v100, v100
	v_rcp_f32_e32 v101, v101
	v_rcp_f32_e32 v92, v92
	v_rcp_f32_e32 v93, v93
	v_pk_mul_f32 v[94:95], v[96:97], v[100:101] op_sel_hi:[0,1]
	v_pk_mul_f32 v[88:89], v[88:89], v[94:95]
	v_pk_mul_f32 v[94:95], v[84:85], v[98:99] op_sel_hi:[1,0]
	v_pk_mul_f32 v[92:93], v[96:97], v[92:93] op_sel_hi:[0,1]
	v_exp_f32_e32 v94, v94
	v_exp_f32_e32 v95, v95
	v_pk_mul_f32 v[90:91], v[90:91], v[92:93]
	v_cvt_pk_bf16_f32 v88, v88, v89
	v_cvt_pk_bf16_f32 v89, v90, v91
	v_pk_add_f32 v[90:91], v[94:95], 1.0 op_sel_hi:[1,0]
	v_pk_mul_f32 v[84:85], v[86:87], v[98:99] op_sel_hi:[1,0]
	v_rcp_f32_e32 v90, v90
	v_rcp_f32_e32 v91, v91
	v_exp_f32_e32 v84, v84
	v_exp_f32_e32 v85, v85
	v_pk_mul_f32 v[86:87], v[96:97], v[90:91] op_sel_hi:[0,1]
	v_pk_mul_f32 v[80:81], v[80:81], v[86:87]
	s_nop 0
	v_cvt_pk_bf16_f32 v90, v80, v81
	v_pk_add_f32 v[80:81], v[84:85], 1.0 op_sel_hi:[1,0]
	v_ffbh_u32_e32 v84, v179
	v_min_u32_e32 v86, 32, v84
	v_lshlrev_b64 v[84:85], v86, v[178:179]
	v_rcp_f32_e32 v80, v80
	v_rcp_f32_e32 v81, v81
	v_min_u32_e32 v84, 1, v84
	v_or_b32_e32 v84, v85, v84
	v_cvt_f32_u32_e32 v84, v84
	v_pk_mul_f32 v[80:81], v[96:97], v[80:81] op_sel_hi:[0,1]
	v_pk_mul_f32 v[80:81], v[82:83], v[80:81]
	v_sub_u32_e32 v82, 32, v86
	v_ldexp_f32 v82, v84, v82
	v_fmamk_f32 v82, v82, 0x30800000, v160
	v_cvt_pk_bf16_f32 v91, v80, v81
	v_mad_i64_i32 v[80:81], s[0:1], v156, s49, v[120:121]
	v_rsq_f32_e32 v82, v82
	v_lshl_add_u64 v[80:81], v[80:81], 0, v[116:117]
	global_store_dwordx4 v[80:81], v[88:91], off nt
	v_mov_b32_e32 v83, v82
	v_mul_f32_e32 v82, 0xbfb8aa3b, v83
	v_pk_mul_f32 v[84:85], v[76:77], v[82:83] op_sel_hi:[1,0]
	v_pk_mul_f32 v[76:77], v[78:79], v[82:83] op_sel_hi:[1,0]
	v_exp_f32_e32 v84, v84
	v_exp_f32_e32 v85, v85
	v_exp_f32_e32 v76, v76
	v_exp_f32_e32 v77, v77
	v_mul_f32_e32 v80, v83, v83
	v_pk_add_f32 v[84:85], v[84:85], 1.0 op_sel_hi:[1,0]
	v_pk_add_f32 v[76:77], v[76:77], 1.0 op_sel_hi:[1,0]
	v_rcp_f32_e32 v84, v84
	v_rcp_f32_e32 v85, v85
	v_rcp_f32_e32 v76, v76
	v_rcp_f32_e32 v77, v77
	v_pk_mul_f32 v[78:79], v[80:81], v[84:85] op_sel_hi:[0,1]
	v_pk_mul_f32 v[72:73], v[72:73], v[78:79]
	v_pk_mul_f32 v[78:79], v[68:69], v[82:83] op_sel_hi:[1,0]
	v_pk_mul_f32 v[76:77], v[80:81], v[76:77] op_sel_hi:[0,1]
	v_exp_f32_e32 v78, v78
	v_exp_f32_e32 v79, v79
	v_pk_mul_f32 v[74:75], v[74:75], v[76:77]
	v_cvt_pk_bf16_f32 v72, v72, v73
	v_cvt_pk_bf16_f32 v73, v74, v75
	v_pk_add_f32 v[74:75], v[78:79], 1.0 op_sel_hi:[1,0]
	v_pk_mul_f32 v[68:69], v[70:71], v[82:83] op_sel_hi:[1,0]
	v_rcp_f32_e32 v74, v74
	v_rcp_f32_e32 v75, v75
	v_exp_f32_e32 v68, v68
	v_exp_f32_e32 v69, v69
	v_pk_mul_f32 v[70:71], v[80:81], v[74:75] op_sel_hi:[0,1]
	v_pk_mul_f32 v[64:65], v[64:65], v[70:71]
	s_nop 0
	v_cvt_pk_bf16_f32 v74, v64, v65
	v_pk_add_f32 v[64:65], v[68:69], 1.0 op_sel_hi:[1,0]
	v_ffbh_u32_e32 v68, v137
	v_min_u32_e32 v70, 32, v68
	v_lshlrev_b64 v[68:69], v70, v[136:137]
	v_rcp_f32_e32 v64, v64
	v_rcp_f32_e32 v65, v65
	v_min_u32_e32 v68, 1, v68
	v_or_b32_e32 v68, v69, v68
	v_cvt_f32_u32_e32 v68, v68
	v_pk_mul_f32 v[64:65], v[80:81], v[64:65] op_sel_hi:[0,1]
	v_pk_mul_f32 v[64:65], v[66:67], v[64:65]
	v_sub_u32_e32 v66, 32, v70
	v_ldexp_f32 v66, v68, v66
	v_fmamk_f32 v66, v66, 0x30800000, v160
	v_cvt_pk_bf16_f32 v75, v64, v65
	v_mad_i64_i32 v[64:65], s[0:1], v126, s49, v[120:121]
	v_rsq_f32_e32 v66, v66
	v_lshl_add_u64 v[64:65], v[64:65], 0, v[116:117]
	global_store_dwordx4 v[64:65], v[72:75], off nt
	v_mov_b32_e32 v67, v66
	v_mul_f32_e32 v66, 0xbfb8aa3b, v67
	v_pk_mul_f32 v[68:69], v[60:61], v[66:67] op_sel_hi:[1,0]
	v_pk_mul_f32 v[60:61], v[62:63], v[66:67] op_sel_hi:[1,0]
	v_exp_f32_e32 v68, v68
	v_exp_f32_e32 v69, v69
	v_exp_f32_e32 v60, v60
	v_exp_f32_e32 v61, v61
	v_mul_f32_e32 v64, v67, v67
	v_pk_add_f32 v[68:69], v[68:69], 1.0 op_sel_hi:[1,0]
	v_pk_add_f32 v[60:61], v[60:61], 1.0 op_sel_hi:[1,0]
	v_rcp_f32_e32 v68, v68
	v_rcp_f32_e32 v69, v69
	v_rcp_f32_e32 v60, v60
	v_rcp_f32_e32 v61, v61
	v_pk_mul_f32 v[62:63], v[64:65], v[68:69] op_sel_hi:[0,1]
	v_pk_mul_f32 v[56:57], v[56:57], v[62:63]
	v_pk_mul_f32 v[62:63], v[52:53], v[66:67] op_sel_hi:[1,0]
	v_pk_mul_f32 v[60:61], v[64:65], v[60:61] op_sel_hi:[0,1]
	v_exp_f32_e32 v62, v62
	v_exp_f32_e32 v63, v63
	v_pk_mul_f32 v[58:59], v[58:59], v[60:61]
	v_cvt_pk_bf16_f32 v56, v56, v57
	v_cvt_pk_bf16_f32 v57, v58, v59
	v_pk_add_f32 v[58:59], v[62:63], 1.0 op_sel_hi:[1,0]
	v_pk_mul_f32 v[52:53], v[54:55], v[66:67] op_sel_hi:[1,0]
	v_rcp_f32_e32 v58, v58
	v_rcp_f32_e32 v59, v59
	v_exp_f32_e32 v52, v52
	v_exp_f32_e32 v53, v53
	v_pk_mul_f32 v[54:55], v[64:65], v[58:59] op_sel_hi:[0,1]
	v_pk_mul_f32 v[48:49], v[48:49], v[54:55]
	s_nop 0
	v_cvt_pk_bf16_f32 v58, v48, v49
	v_pk_add_f32 v[48:49], v[52:53], 1.0 op_sel_hi:[1,0]
	v_ffbh_u32_e32 v52, v125
	v_min_u32_e32 v54, 32, v52
	v_lshlrev_b64 v[52:53], v54, v[124:125]
	v_rcp_f32_e32 v48, v48
	v_rcp_f32_e32 v49, v49
	v_min_u32_e32 v52, 1, v52
	v_or_b32_e32 v52, v53, v52
	v_cvt_f32_u32_e32 v52, v52
	v_pk_mul_f32 v[48:49], v[64:65], v[48:49] op_sel_hi:[0,1]
	v_pk_mul_f32 v[48:49], v[50:51], v[48:49]
	v_sub_u32_e32 v50, 32, v54
	v_ldexp_f32 v50, v52, v50
	v_fmamk_f32 v50, v50, 0x30800000, v160
	v_cvt_pk_bf16_f32 v59, v48, v49
	v_mad_i64_i32 v[48:49], s[0:1], v163, s49, v[120:121]
	v_rsq_f32_e32 v50, v50
	v_lshl_add_u64 v[48:49], v[48:49], 0, v[116:117]
	global_store_dwordx4 v[48:49], v[56:59], off nt
	v_mov_b32_e32 v51, v50
	v_mul_f32_e32 v50, 0xbfb8aa3b, v51
	v_pk_mul_f32 v[52:53], v[44:45], v[50:51] op_sel_hi:[1,0]
	v_pk_mul_f32 v[44:45], v[46:47], v[50:51] op_sel_hi:[1,0]
	v_exp_f32_e32 v52, v52
	v_exp_f32_e32 v53, v53
	v_exp_f32_e32 v44, v44
	v_exp_f32_e32 v45, v45
	v_mul_f32_e32 v48, v51, v51
	v_pk_add_f32 v[52:53], v[52:53], 1.0 op_sel_hi:[1,0]
	v_pk_add_f32 v[44:45], v[44:45], 1.0 op_sel_hi:[1,0]
	v_rcp_f32_e32 v52, v52
	v_rcp_f32_e32 v53, v53
	v_rcp_f32_e32 v44, v44
	v_rcp_f32_e32 v45, v45
	v_pk_mul_f32 v[46:47], v[48:49], v[52:53] op_sel_hi:[0,1]
	v_pk_mul_f32 v[40:41], v[40:41], v[46:47]
	v_pk_mul_f32 v[46:47], v[36:37], v[50:51] op_sel_hi:[1,0]
	v_pk_mul_f32 v[44:45], v[48:49], v[44:45] op_sel_hi:[0,1]
	v_exp_f32_e32 v46, v46
	v_exp_f32_e32 v47, v47
	v_pk_mul_f32 v[42:43], v[42:43], v[44:45]
	v_cvt_pk_bf16_f32 v40, v40, v41
	v_cvt_pk_bf16_f32 v41, v42, v43
	v_pk_add_f32 v[42:43], v[46:47], 1.0 op_sel_hi:[1,0]
	v_pk_mul_f32 v[36:37], v[38:39], v[50:51] op_sel_hi:[1,0]
	v_rcp_f32_e32 v42, v42
	v_rcp_f32_e32 v43, v43
	v_exp_f32_e32 v36, v36
	v_exp_f32_e32 v37, v37
	v_pk_mul_f32 v[38:39], v[48:49], v[42:43] op_sel_hi:[0,1]
	v_pk_mul_f32 v[32:33], v[32:33], v[38:39]
	s_nop 0
	v_cvt_pk_bf16_f32 v42, v32, v33
	v_pk_add_f32 v[32:33], v[36:37], 1.0 op_sel_hi:[1,0]
	v_ffbh_u32_e32 v36, v123
	v_min_u32_e32 v38, 32, v36
	v_lshlrev_b64 v[36:37], v38, v[122:123]
	v_rcp_f32_e32 v32, v32
	v_rcp_f32_e32 v33, v33
	v_min_u32_e32 v36, 1, v36
	v_or_b32_e32 v36, v37, v36
	v_cvt_f32_u32_e32 v36, v36
	v_pk_mul_f32 v[32:33], v[48:49], v[32:33] op_sel_hi:[0,1]
	v_pk_mul_f32 v[32:33], v[34:35], v[32:33]
	v_sub_u32_e32 v34, 32, v38
	v_ldexp_f32 v34, v36, v34
	v_fmamk_f32 v34, v34, 0x30800000, v160
	v_cvt_pk_bf16_f32 v43, v32, v33
	v_mad_i64_i32 v[32:33], s[0:1], v162, s49, v[120:121]
	v_rsq_f32_e32 v34, v34
	v_lshl_add_u64 v[32:33], v[32:33], 0, v[116:117]
	global_store_dwordx4 v[32:33], v[40:43], off nt
	v_mov_b32_e32 v35, v34
	v_mul_f32_e32 v34, 0xbfb8aa3b, v35
	v_pk_mul_f32 v[36:37], v[28:29], v[34:35] op_sel_hi:[1,0]
	v_pk_mul_f32 v[28:29], v[30:31], v[34:35] op_sel_hi:[1,0]
	v_exp_f32_e32 v36, v36
	v_exp_f32_e32 v37, v37
	v_exp_f32_e32 v28, v28
	v_exp_f32_e32 v29, v29
	v_mul_f32_e32 v32, v35, v35
	v_pk_add_f32 v[36:37], v[36:37], 1.0 op_sel_hi:[1,0]
	v_pk_add_f32 v[28:29], v[28:29], 1.0 op_sel_hi:[1,0]
	v_rcp_f32_e32 v36, v36
	v_rcp_f32_e32 v37, v37
	v_rcp_f32_e32 v28, v28
	v_rcp_f32_e32 v29, v29
	v_pk_mul_f32 v[30:31], v[32:33], v[36:37] op_sel_hi:[0,1]
	v_pk_mul_f32 v[24:25], v[24:25], v[30:31]
	v_pk_mul_f32 v[30:31], v[20:21], v[34:35] op_sel_hi:[1,0]
	v_pk_mul_f32 v[28:29], v[32:33], v[28:29] op_sel_hi:[0,1]
	v_exp_f32_e32 v30, v30
	v_exp_f32_e32 v31, v31
	v_pk_mul_f32 v[26:27], v[26:27], v[28:29]
	v_cvt_pk_bf16_f32 v24, v24, v25
	v_cvt_pk_bf16_f32 v25, v26, v27
	v_pk_add_f32 v[26:27], v[30:31], 1.0 op_sel_hi:[1,0]
	v_pk_mul_f32 v[20:21], v[22:23], v[34:35] op_sel_hi:[1,0]
	v_rcp_f32_e32 v26, v26
	v_rcp_f32_e32 v27, v27
	v_exp_f32_e32 v20, v20
	v_exp_f32_e32 v21, v21
	v_pk_mul_f32 v[22:23], v[32:33], v[26:27] op_sel_hi:[0,1]
	v_pk_mul_f32 v[16:17], v[16:17], v[22:23]
	s_nop 0
	v_cvt_pk_bf16_f32 v26, v16, v17
	v_pk_add_f32 v[16:17], v[20:21], 1.0 op_sel_hi:[1,0]
	v_ffbh_u32_e32 v20, v119
	v_min_u32_e32 v22, 32, v20
	v_lshlrev_b64 v[20:21], v22, v[118:119]
	v_rcp_f32_e32 v16, v16
	v_rcp_f32_e32 v17, v17
	v_min_u32_e32 v20, 1, v20
	v_or_b32_e32 v20, v21, v20
	v_cvt_f32_u32_e32 v20, v20
	v_pk_mul_f32 v[16:17], v[32:33], v[16:17] op_sel_hi:[0,1]
	v_pk_mul_f32 v[16:17], v[18:19], v[16:17]
	v_sub_u32_e32 v18, 32, v22
	v_ldexp_f32 v18, v20, v18
	v_fmamk_f32 v18, v18, 0x30800000, v160
	v_cvt_pk_bf16_f32 v27, v16, v17
	v_mad_i64_i32 v[16:17], s[0:1], v161, s49, v[120:121]
	v_rsq_f32_e32 v18, v18
	v_lshl_add_u64 v[16:17], v[16:17], 0, v[116:117]
	global_store_dwordx4 v[16:17], v[24:27], off nt
	v_mov_b32_e32 v19, v18
	v_mul_f32_e32 v18, 0xbfb8aa3b, v19
	v_pk_mul_f32 v[20:21], v[12:13], v[18:19] op_sel_hi:[1,0]
	v_pk_mul_f32 v[12:13], v[14:15], v[18:19] op_sel_hi:[1,0]
	v_exp_f32_e32 v20, v20
	v_exp_f32_e32 v21, v21
	v_exp_f32_e32 v12, v12
	v_exp_f32_e32 v13, v13
	v_mul_f32_e32 v16, v19, v19
	v_pk_add_f32 v[20:21], v[20:21], 1.0 op_sel_hi:[1,0]
	s_andn2_b64 vcc, exec, s[4:5]
	v_rcp_f32_e32 v20, v20
	v_rcp_f32_e32 v21, v21
	v_pk_add_f32 v[12:13], v[12:13], 1.0 op_sel_hi:[1,0]
	v_pk_mul_f32 v[14:15], v[16:17], v[20:21] op_sel_hi:[0,1]
	v_rcp_f32_e32 v12, v12
	v_rcp_f32_e32 v13, v13
	v_pk_mul_f32 v[8:9], v[8:9], v[14:15]
	v_pk_mul_f32 v[14:15], v[4:5], v[18:19] op_sel_hi:[1,0]
	v_cvt_pk_bf16_f32 v8, v8, v9
	v_exp_f32_e32 v14, v14
	v_exp_f32_e32 v15, v15
	v_pk_mul_f32 v[12:13], v[16:17], v[12:13] op_sel_hi:[0,1]
	v_pk_mul_f32 v[10:11], v[10:11], v[12:13]
	v_pk_mul_f32 v[12:13], v[6:7], v[18:19] op_sel_hi:[1,0]
	v_cvt_pk_bf16_f32 v9, v10, v11
	v_exp_f32_e32 v12, v12
	v_exp_f32_e32 v13, v13
	v_pk_add_f32 v[10:11], v[14:15], 1.0 op_sel_hi:[1,0]
	v_pk_add_f32 v[4:5], v[12:13], 1.0 op_sel_hi:[1,0]
	v_rcp_f32_e32 v10, v10
	v_rcp_f32_e32 v11, v11
	v_rcp_f32_e32 v4, v4
	v_rcp_f32_e32 v5, v5
	v_pk_mul_f32 v[6:7], v[16:17], v[10:11] op_sel_hi:[0,1]
	v_pk_mul_f32 v[0:1], v[0:1], v[6:7]
	s_nop 0
	v_cvt_pk_bf16_f32 v10, v0, v1
	v_pk_mul_f32 v[0:1], v[16:17], v[4:5] op_sel_hi:[0,1]
	v_pk_mul_f32 v[0:1], v[2:3], v[0:1]
	s_nop 0
	v_cvt_pk_bf16_f32 v11, v0, v1
	v_mad_i64_i32 v[0:1], s[0:1], v139, s49, v[120:121]
	v_lshl_add_u64 v[0:1], v[0:1], 0, v[116:117]
	s_mov_b64 s[0:1], -1
	global_store_dwordx4 v[0:1], v[8:11], off nt
	s_cbranch_vccnz .LBB0_805
	s_andn2_b64 vcc, exec, s[6:7]
	s_cbranch_vccnz .LBB0_804
	s_barrier
	s_branch .LBB0_804

.LBB0_894:
	s_lshl_b32 s22, s51, 8
	s_add_i32 s22, s22, s35
	v_or_b32_e32 v130, s22, v170
	v_ashrrev_i32_e32 v131, 31, v130
	v_lshl_or_b32 v128, s52, 8, v164
	v_lshlrev_b64 v[130:131], 11, v[130:131]
	v_ashrrev_i32_e32 v129, 31, v128
	v_lshl_add_u64 v[130:131], s[84:85], 0, v[130:131]
	v_lshl_add_u64 v[156:157], v[128:129], 1, v[130:131]
	global_load_dwordx4 v[174:177], v[156:157], off
	global_load_dwordx4 v[178:181], v[156:157], off offset:256
	v_add_co_u32_e32 v196, vcc, s39, v156
	v_and_b32_e32 v129, 64, v168
	s_nop 0
	v_addc_co_u32_e32 v197, vcc, 0, v157, vcc
	global_load_dwordx4 v[182:185], v[196:197], off
	v_xor_b32_e32 v128, 16, v168
	v_add_u32_e32 v129, 64, v129
	v_xor_b32_e32 v130, 32, v168
	v_cmp_lt_i32_e32 vcc, v128, v129
	s_waitcnt vmcnt(0)
	v_lshlrev_b32_e32 v198, 16, v174
	v_cndmask_b32_e32 v128, v168, v128, vcc
	v_cmp_lt_i32_e32 vcc, v130, v129
	v_lshlrev_b32_e32 v172, 2, v128
	v_and_b32_e32 v199, 0xffff0000, v174
	v_cndmask_b32_e32 v129, v168, v130, vcc
	v_add_co_u32_e32 v160, vcc, s34, v156
	v_lshlrev_b32_e32 v169, 2, v129
	s_nop 0
	v_addc_co_u32_e32 v161, vcc, 0, v157, vcc
	v_add_co_u32_e32 v158, vcc, s38, v156
	v_lshlrev_b32_e32 v174, 16, v175
	s_nop 0
	v_addc_co_u32_e32 v159, vcc, 0, v157, vcc
	global_load_dwordx4 v[186:189], v[196:197], off offset:256
	global_load_dwordx4 v[190:193], v[160:161], off
	global_load_dwordx4 v[136:139], v[160:161], off offset:256
	global_load_dwordx4 v[132:135], v[158:159], off
	global_load_dwordx4 v[128:131], v[158:159], off offset:256
	v_and_b32_e32 v175, 0xffff0000, v175
	v_lshlrev_b32_e32 v200, 16, v176
	v_and_b32_e32 v201, 0xffff0000, v176
	v_lshlrev_b32_e32 v176, 16, v177
	v_and_b32_e32 v177, 0xffff0000, v177
	v_lshlrev_b32_e32 v202, 16, v178
	v_and_b32_e32 v203, 0xffff0000, v178
	v_lshlrev_b32_e32 v178, 16, v179
	v_and_b32_e32 v179, 0xffff0000, v179
	v_lshlrev_b32_e32 v204, 16, v180
	v_and_b32_e32 v205, 0xffff0000, v180
	v_lshlrev_b32_e32 v180, 16, v181
	v_and_b32_e32 v181, 0xffff0000, v181
	v_pk_add_f32 v[126:127], v[126:127], v[174:175]
	v_pk_add_f32 v[124:125], v[124:125], v[198:199]
	v_pk_add_f32 v[122:123], v[122:123], v[176:177]
	v_pk_add_f32 v[174:175], v[118:119], v[178:179]
	v_pk_add_f32 v[176:177], v[116:117], v[202:203]
	v_pk_add_f32 v[120:121], v[120:121], v[200:201]
	v_pk_add_f32 v[178:179], v[114:115], v[180:181]
	v_pk_add_f32 v[180:181], v[112:113], v[204:205]
	v_cvt_pk_bf16_f32 v112, v124, v125
	v_cvt_pk_bf16_f32 v113, v126, v127
	v_mul_f32_e32 v125, v125, v125
	v_mul_f32_e32 v127, v127, v127
	v_cvt_pk_bf16_f32 v117, v174, v175
	v_mul_f32_e32 v173, v177, v177
	v_mul_f32_e32 v175, v175, v175
	v_cvt_pk_bf16_f32 v114, v120, v121
	v_cvt_pk_bf16_f32 v115, v122, v123
	v_mul_f32_e32 v121, v121, v121
	v_cvt_pk_bf16_f32 v116, v176, v177
	v_mul_f32_e32 v177, v181, v181
	v_fmac_f32_e32 v125, v124, v124
	v_fmac_f32_e32 v127, v126, v126
	v_fmac_f32_e32 v173, v176, v176
	v_fmac_f32_e32 v175, v174, v174
	v_mul_f32_e32 v123, v123, v123
	v_cvt_pk_bf16_f32 v119, v178, v179
	v_mul_f32_e32 v179, v179, v179
	global_store_dwordx4 v[156:157], v[112:115], off nt
	v_fmac_f32_e32 v121, v120, v120
	v_fmac_f32_e32 v177, v180, v180
	v_add_f32_e32 v112, v125, v127
	v_add_f32_e32 v113, v173, v175
	v_fmac_f32_e32 v123, v122, v122
	v_fmac_f32_e32 v179, v178, v178
	v_add_f32_e32 v112, v121, v112
	v_add_f32_e32 v113, v177, v113
	v_cvt_pk_bf16_f32 v118, v180, v181
	v_add_f32_e32 v112, v123, v112
	v_add_f32_e32 v113, v179, v113
	global_store_dwordx4 v[156:157], v[116:119], off offset:256 nt
	v_add_f32_e32 v120, v112, v113
	v_lshlrev_b32_e32 v112, 16, v182
	v_and_b32_e32 v113, 0xffff0000, v182
	v_lshlrev_b32_e32 v114, 16, v183
	v_and_b32_e32 v115, 0xffff0000, v183
	v_lshlrev_b32_e32 v116, 16, v184
	v_and_b32_e32 v117, 0xffff0000, v184
	v_lshlrev_b32_e32 v118, 16, v185
	v_and_b32_e32 v119, 0xffff0000, v185
	v_pk_add_f32 v[110:111], v[110:111], v[114:115]
	v_pk_add_f32 v[108:109], v[108:109], v[112:113]
	v_pk_add_f32 v[112:113], v[106:107], v[118:119]
	v_pk_add_f32 v[114:115], v[104:105], v[116:117]
	v_cvt_pk_bf16_f32 v104, v108, v109
	v_cvt_pk_bf16_f32 v105, v110, v111
	v_cvt_pk_bf16_f32 v106, v114, v115
	v_cvt_pk_bf16_f32 v107, v112, v113
	global_store_dwordx4 v[196:197], v[104:107], off nt
	v_cmp_lt_i32_e32 vcc, 0, v171
	s_nop 0
	v_mul_f32_e32 v104, v109, v109
	v_mul_f32_e32 v105, v111, v111
	v_fmac_f32_e32 v104, v108, v108
	v_fmac_f32_e32 v105, v110, v110
	v_add_f32_e32 v104, v104, v105
	v_mul_f32_e32 v105, v115, v115
	v_fmac_f32_e32 v105, v114, v114
	v_add_f32_e32 v104, v105, v104
	v_mul_f32_e32 v105, v113, v113
	v_fmac_f32_e32 v105, v112, v112
	v_add_f32_e32 v112, v105, v104
	s_waitcnt vmcnt(7)
	v_lshlrev_b32_e32 v104, 16, v186
	v_and_b32_e32 v105, 0xffff0000, v186
	v_lshlrev_b32_e32 v106, 16, v187
	v_and_b32_e32 v107, 0xffff0000, v187
	v_lshlrev_b32_e32 v108, 16, v188
	v_and_b32_e32 v109, 0xffff0000, v188
	v_lshlrev_b32_e32 v110, 16, v189
	v_and_b32_e32 v111, 0xffff0000, v189
	v_pk_add_f32 v[102:103], v[102:103], v[106:107]
	v_pk_add_f32 v[100:101], v[100:101], v[104:105]
	v_pk_add_f32 v[104:105], v[98:99], v[110:111]
	v_pk_add_f32 v[106:107], v[96:97], v[108:109]
	v_cvt_pk_bf16_f32 v96, v100, v101
	v_cvt_pk_bf16_f32 v97, v102, v103
	v_cvt_pk_bf16_f32 v98, v106, v107
	v_cvt_pk_bf16_f32 v99, v104, v105
	global_store_dwordx4 v[196:197], v[96:99], off offset:256 nt
	s_nop 1
	v_mul_f32_e32 v96, v101, v101
	v_mul_f32_e32 v97, v103, v103
	v_fmac_f32_e32 v96, v100, v100
	v_fmac_f32_e32 v97, v102, v102
	v_add_f32_e32 v96, v96, v97
	v_mul_f32_e32 v97, v107, v107
	v_fmac_f32_e32 v97, v106, v106
	v_add_f32_e32 v96, v97, v96
	v_mul_f32_e32 v97, v105, v105
	v_fmac_f32_e32 v97, v104, v104
	v_add_f32_e32 v96, v97, v96
	v_add_f32_e32 v104, v112, v96
	s_waitcnt vmcnt(7)
	v_lshlrev_b32_e32 v96, 16, v190
	v_and_b32_e32 v97, 0xffff0000, v190
	v_lshlrev_b32_e32 v98, 16, v191
	v_and_b32_e32 v99, 0xffff0000, v191
	v_lshlrev_b32_e32 v100, 16, v192
	v_and_b32_e32 v101, 0xffff0000, v192
	v_lshlrev_b32_e32 v102, 16, v193
	v_and_b32_e32 v103, 0xffff0000, v193
	v_pk_add_f32 v[94:95], v[94:95], v[98:99]
	v_pk_add_f32 v[92:93], v[92:93], v[96:97]
	v_pk_add_f32 v[96:97], v[90:91], v[102:103]
	v_pk_add_f32 v[98:99], v[88:89], v[100:101]
	v_cvt_pk_bf16_f32 v88, v92, v93
	v_cvt_pk_bf16_f32 v89, v94, v95
	v_cvt_pk_bf16_f32 v90, v98, v99
	v_cvt_pk_bf16_f32 v91, v96, v97
	global_store_dwordx4 v[160:161], v[88:91], off nt
	s_nop 1
	v_mul_f32_e32 v88, v93, v93
	v_mul_f32_e32 v89, v95, v95
	v_fmac_f32_e32 v88, v92, v92
	v_fmac_f32_e32 v89, v94, v94
	v_add_f32_e32 v88, v88, v89
	v_mul_f32_e32 v89, v99, v99
	v_fmac_f32_e32 v89, v98, v98
	v_add_f32_e32 v88, v89, v88
	v_mul_f32_e32 v89, v97, v97
	v_fmac_f32_e32 v89, v96, v96
	v_add_f32_e32 v96, v89, v88
	s_waitcnt vmcnt(7)
	v_lshlrev_b32_e32 v88, 16, v136
	v_and_b32_e32 v89, 0xffff0000, v136
	v_lshlrev_b32_e32 v90, 16, v137
	v_and_b32_e32 v91, 0xffff0000, v137
	v_lshlrev_b32_e32 v92, 16, v138
	v_and_b32_e32 v93, 0xffff0000, v138
	v_lshlrev_b32_e32 v94, 16, v139
	v_and_b32_e32 v95, 0xffff0000, v139
	v_pk_add_f32 v[86:87], v[86:87], v[90:91]
	v_pk_add_f32 v[84:85], v[84:85], v[88:89]
	v_pk_add_f32 v[88:89], v[82:83], v[94:95]
	v_pk_add_f32 v[90:91], v[80:81], v[92:93]
	v_cvt_pk_bf16_f32 v80, v84, v85
	v_cvt_pk_bf16_f32 v81, v86, v87
	v_cvt_pk_bf16_f32 v82, v90, v91
	v_cvt_pk_bf16_f32 v83, v88, v89
	global_store_dwordx4 v[160:161], v[80:83], off offset:256 nt
	s_nop 1
	v_mul_f32_e32 v80, v85, v85
	v_mul_f32_e32 v81, v87, v87
	v_fmac_f32_e32 v80, v84, v84
	v_fmac_f32_e32 v81, v86, v86
	v_add_f32_e32 v80, v80, v81
	v_mul_f32_e32 v81, v91, v91
	v_fmac_f32_e32 v81, v90, v90
	v_add_f32_e32 v80, v81, v80
	v_mul_f32_e32 v81, v89, v89
	v_fmac_f32_e32 v81, v88, v88
	v_add_f32_e32 v80, v81, v80
	v_add_f32_e32 v88, v96, v80
	s_waitcnt vmcnt(7)
	v_lshlrev_b32_e32 v80, 16, v132
	v_and_b32_e32 v81, 0xffff0000, v132
	v_lshlrev_b32_e32 v82, 16, v133
	v_and_b32_e32 v83, 0xffff0000, v133
	v_lshlrev_b32_e32 v84, 16, v134
	v_and_b32_e32 v85, 0xffff0000, v134
	v_lshlrev_b32_e32 v86, 16, v135
	v_and_b32_e32 v87, 0xffff0000, v135
	v_pk_add_f32 v[78:79], v[78:79], v[82:83]
	v_pk_add_f32 v[76:77], v[76:77], v[80:81]
	v_pk_add_f32 v[80:81], v[74:75], v[86:87]
	v_pk_add_f32 v[82:83], v[72:73], v[84:85]
	v_cvt_pk_bf16_f32 v72, v76, v77
	v_cvt_pk_bf16_f32 v73, v78, v79
	v_cvt_pk_bf16_f32 v74, v82, v83
	v_cvt_pk_bf16_f32 v75, v80, v81
	global_store_dwordx4 v[158:159], v[72:75], off nt
	s_nop 1
	v_mul_f32_e32 v72, v77, v77
	v_mul_f32_e32 v73, v79, v79
	v_fmac_f32_e32 v72, v76, v76
	v_fmac_f32_e32 v73, v78, v78
	v_add_f32_e32 v72, v72, v73
	v_mul_f32_e32 v73, v83, v83
	v_fmac_f32_e32 v73, v82, v82
	v_add_f32_e32 v72, v73, v72
	v_mul_f32_e32 v73, v81, v81
	v_fmac_f32_e32 v73, v80, v80
	v_add_f32_e32 v82, v73, v72
	s_waitcnt vmcnt(7)
	v_lshlrev_b32_e32 v72, 16, v128
	v_and_b32_e32 v73, 0xffff0000, v128
	v_lshlrev_b32_e32 v74, 16, v129
	v_and_b32_e32 v75, 0xffff0000, v129
	v_lshlrev_b32_e32 v76, 16, v130
	v_and_b32_e32 v77, 0xffff0000, v130
	v_pk_add_f32 v[80:81], v[70:71], v[74:75]
	v_pk_add_f32 v[68:69], v[68:69], v[72:73]
	v_pk_add_f32 v[76:77], v[64:65], v[76:77]
	v_mul_f32_e32 v64, v69, v69
	v_mul_f32_e32 v65, v81, v81
	v_fmac_f32_e32 v64, v68, v68
	v_fmac_f32_e32 v65, v80, v80
	v_lshlrev_b32_e32 v78, 16, v131
	v_and_b32_e32 v79, 0xffff0000, v131
	v_add_f32_e32 v64, v64, v65
	v_mul_f32_e32 v65, v77, v77
	v_pk_add_f32 v[78:79], v[66:67], v[78:79]
	v_fmac_f32_e32 v65, v76, v76
	v_add_f32_e32 v64, v65, v64
	v_mul_f32_e32 v65, v79, v79
	v_fmac_f32_e32 v65, v78, v78
	v_add_f32_e32 v64, v65, v64
	v_add_f32_e32 v64, v82, v64
	v_cvt_pk_bf16_f32 v74, v68, v69
	ds_bpermute_b32 v66, v172, v120
	ds_bpermute_b32 v65, v172, v104
	ds_bpermute_b32 v69, v172, v88
	ds_bpermute_b32 v71, v172, v64
	v_cvt_pk_bf16_f32 v75, v80, v81
	s_waitcnt lgkmcnt(3)
	v_add_f32_e32 v67, v120, v66
	s_waitcnt lgkmcnt(2)
	v_add_f32_e32 v65, v104, v65
	s_waitcnt lgkmcnt(1)
	v_add_f32_e32 v69, v88, v69
	s_waitcnt lgkmcnt(0)
	v_add_f32_e32 v71, v64, v71
	ds_bpermute_b32 v68, v169, v67
	ds_bpermute_b32 v66, v169, v65
	ds_bpermute_b32 v70, v169, v69
	ds_bpermute_b32 v72, v169, v71
	v_cvt_pk_bf16_f32 v76, v76, v77
	v_cvt_pk_bf16_f32 v77, v78, v79
	global_store_dwordx4 v[158:159], v[74:77], off offset:256 nt
	s_and_saveexec_b64 s[2:3], vcc
	s_xor_b64 s[2:3], exec, s[2:3]
	s_cbranch_execz .LBB0_900
	v_cmp_ne_u32_e32 vcc, 1, v171
	s_and_saveexec_b64 s[14:15], vcc
	s_xor_b64 s[14:15], exec, s[14:15]
	s_cbranch_execz .LBB0_897
	s_waitcnt lgkmcnt(0)
	v_add_f32_e32 v64, v71, v72
	v_add_f32_e32 v65, v69, v70
	v_cndmask_b32_e64 v64, v64, v65, s[6:7]

.LBB0_902:
	s_or_b64 exec, exec, s[2:3]
	v_mul_f32_e32 v64, 0x49800000, v64
	v_trunc_f32_e32 v64, v64
	v_mul_f32_e32 v65, 0x2f800000, v64
	v_floor_f32_e32 v65, v65
	v_fmac_f32_e32 v64, 0xcf800000, v65
	v_cvt_u32_f32_e32 v64, v64
	v_cvt_u32_f32_e32 v65, v65
	v_or_b32_e32 v76, s22, v163
	v_ashrrev_i32_e32 v77, 31, v76
	s_waitcnt lgkmcnt(2)
	v_lshl_add_u64 v[66:67], v[76:77], 3, s[10:11]
	v_add_co_u32_e32 v102, vcc, s45, v156
	global_atomic_add_x2 v[66:67], v[64:65], off
	s_nop 0
	v_addc_co_u32_e32 v103, vcc, 0, v157, vcc
	global_load_dwordx4 v[82:85], v[102:103], off
	global_load_dwordx4 v[86:89], v[102:103], off offset:256
	v_add_co_u32_e32 v104, vcc, s46, v156
	s_waitcnt vmcnt(1)
	v_lshlrev_b32_e32 v106, 16, v82
	v_addc_co_u32_e32 v105, vcc, 0, v157, vcc
	global_load_dwordx4 v[90:93], v[104:105], off
	v_add_co_u32_e32 v80, vcc, s47, v156
	v_and_b32_e32 v107, 0xffff0000, v82
	s_nop 0
	v_addc_co_u32_e32 v81, vcc, 0, v157, vcc
	v_add_co_u32_e32 v78, vcc, s48, v156
	v_lshlrev_b32_e32 v82, 16, v83
	s_nop 0
	v_addc_co_u32_e32 v79, vcc, 0, v157, vcc
	global_load_dwordx4 v[94:97], v[104:105], off offset:256
	global_load_dwordx4 v[98:101], v[80:81], off
	s_waitcnt lgkmcnt(0)
	global_load_dwordx4 v[72:75], v[80:81], off offset:256
	global_load_dwordx4 v[68:71], v[78:79], off
	global_load_dwordx4 v[64:67], v[78:79], off offset:256
	v_and_b32_e32 v83, 0xffff0000, v83
	v_lshlrev_b32_e32 v108, 16, v84
	v_and_b32_e32 v109, 0xffff0000, v84
	v_lshlrev_b32_e32 v84, 16, v85
	v_and_b32_e32 v85, 0xffff0000, v85
	s_waitcnt vmcnt(6)
	v_lshlrev_b32_e32 v110, 16, v86
	v_and_b32_e32 v111, 0xffff0000, v86
	v_lshlrev_b32_e32 v86, 16, v87
	v_and_b32_e32 v87, 0xffff0000, v87
	v_lshlrev_b32_e32 v112, 16, v88
	v_and_b32_e32 v113, 0xffff0000, v88
	v_lshlrev_b32_e32 v88, 16, v89
	v_and_b32_e32 v89, 0xffff0000, v89
	v_pk_add_f32 v[62:63], v[62:63], v[82:83]
	v_pk_add_f32 v[60:61], v[60:61], v[106:107]
	v_pk_add_f32 v[58:59], v[58:59], v[84:85]
	v_pk_add_f32 v[82:83], v[54:55], v[86:87]
	v_pk_add_f32 v[84:85], v[52:53], v[110:111]
	v_pk_add_f32 v[56:57], v[56:57], v[108:109]
	v_pk_add_f32 v[86:87], v[50:51], v[88:89]
	v_pk_add_f32 v[88:89], v[48:49], v[112:113]
	v_cvt_pk_bf16_f32 v48, v60, v61
	v_cvt_pk_bf16_f32 v49, v62, v63
	v_mul_f32_e32 v61, v61, v61
	v_mul_f32_e32 v63, v63, v63
	v_cvt_pk_bf16_f32 v53, v82, v83
	v_mul_f32_e32 v77, v85, v85
	v_mul_f32_e32 v83, v83, v83
	v_cvt_pk_bf16_f32 v50, v56, v57
	v_cvt_pk_bf16_f32 v51, v58, v59
	v_mul_f32_e32 v57, v57, v57
	v_cvt_pk_bf16_f32 v52, v84, v85
	v_mul_f32_e32 v85, v89, v89
	v_fmac_f32_e32 v61, v60, v60
	v_fmac_f32_e32 v63, v62, v62
	v_fmac_f32_e32 v77, v84, v84
	v_fmac_f32_e32 v83, v82, v82
	v_mul_f32_e32 v59, v59, v59
	v_cvt_pk_bf16_f32 v55, v86, v87
	v_mul_f32_e32 v87, v87, v87
	global_store_dwordx4 v[102:103], v[48:51], off nt
	v_fmac_f32_e32 v57, v56, v56
	v_fmac_f32_e32 v85, v88, v88
	v_add_f32_e32 v48, v61, v63
	v_add_f32_e32 v49, v77, v83
	v_fmac_f32_e32 v59, v58, v58
	v_fmac_f32_e32 v87, v86, v86
	v_add_f32_e32 v48, v57, v48
	v_add_f32_e32 v49, v85, v49
	v_cvt_pk_bf16_f32 v54, v88, v89
	v_add_f32_e32 v48, v59, v48
	v_add_f32_e32 v49, v87, v49
	global_store_dwordx4 v[102:103], v[52:55], off offset:256 nt
	v_cmp_lt_i32_e32 vcc, 0, v171
	s_waitcnt vmcnt(7)
	v_lshlrev_b32_e32 v114, 16, v90
	v_and_b32_e32 v115, 0xffff0000, v90
	v_add_f32_e32 v54, v48, v49
	v_lshlrev_b32_e32 v48, 16, v91
	v_and_b32_e32 v49, 0xffff0000, v91
	v_lshlrev_b32_e32 v50, 16, v92
	v_and_b32_e32 v51, 0xffff0000, v92
	v_lshlrev_b32_e32 v52, 16, v93
	v_and_b32_e32 v53, 0xffff0000, v93
	v_pk_add_f32 v[46:47], v[46:47], v[48:49]
	v_pk_add_f32 v[44:45], v[44:45], v[114:115]
	v_pk_add_f32 v[48:49], v[42:43], v[52:53]
	v_pk_add_f32 v[50:51], v[40:41], v[50:51]
	v_cvt_pk_bf16_f32 v40, v44, v45
	v_cvt_pk_bf16_f32 v41, v46, v47
	v_cvt_pk_bf16_f32 v42, v50, v51
	v_cvt_pk_bf16_f32 v43, v48, v49
	global_store_dwordx4 v[104:105], v[40:43], off nt
	s_nop 1
	v_mul_f32_e32 v40, v45, v45
	v_mul_f32_e32 v41, v47, v47
	v_fmac_f32_e32 v40, v44, v44
	v_fmac_f32_e32 v41, v46, v46
	v_add_f32_e32 v40, v40, v41
	v_mul_f32_e32 v41, v51, v51
	v_fmac_f32_e32 v41, v50, v50
	v_add_f32_e32 v40, v41, v40
	v_mul_f32_e32 v41, v49, v49
	v_fmac_f32_e32 v41, v48, v48
	v_add_f32_e32 v48, v41, v40
	s_waitcnt vmcnt(7)
	v_lshlrev_b32_e32 v40, 16, v94
	v_and_b32_e32 v41, 0xffff0000, v94
	v_lshlrev_b32_e32 v42, 16, v95
	v_and_b32_e32 v43, 0xffff0000, v95
	v_lshlrev_b32_e32 v44, 16, v96
	v_and_b32_e32 v45, 0xffff0000, v96
	v_lshlrev_b32_e32 v46, 16, v97
	v_and_b32_e32 v47, 0xffff0000, v97
	v_pk_add_f32 v[38:39], v[38:39], v[42:43]
	v_pk_add_f32 v[36:37], v[36:37], v[40:41]
	v_pk_add_f32 v[40:41], v[34:35], v[46:47]
	v_pk_add_f32 v[42:43], v[32:33], v[44:45]
	v_cvt_pk_bf16_f32 v32, v36, v37
	v_cvt_pk_bf16_f32 v33, v38, v39
	v_cvt_pk_bf16_f32 v34, v42, v43
	v_cvt_pk_bf16_f32 v35, v40, v41
	global_store_dwordx4 v[104:105], v[32:35], off offset:256 nt
	s_nop 1
	v_mul_f32_e32 v32, v37, v37
	v_mul_f32_e32 v33, v39, v39
	v_fmac_f32_e32 v32, v36, v36
	v_fmac_f32_e32 v33, v38, v38
	v_add_f32_e32 v32, v32, v33
	v_mul_f32_e32 v33, v43, v43
	v_fmac_f32_e32 v33, v42, v42
	v_add_f32_e32 v32, v33, v32
	v_mul_f32_e32 v33, v41, v41
	v_fmac_f32_e32 v33, v40, v40
	v_add_f32_e32 v32, v33, v32
	v_add_f32_e32 v40, v48, v32
	s_waitcnt vmcnt(7)
	v_lshlrev_b32_e32 v32, 16, v98
	v_and_b32_e32 v33, 0xffff0000, v98
	v_lshlrev_b32_e32 v34, 16, v99
	v_and_b32_e32 v35, 0xffff0000, v99
	v_lshlrev_b32_e32 v36, 16, v100
	v_and_b32_e32 v37, 0xffff0000, v100
	v_lshlrev_b32_e32 v38, 16, v101
	v_and_b32_e32 v39, 0xffff0000, v101
	v_pk_add_f32 v[30:31], v[30:31], v[34:35]
	v_pk_add_f32 v[28:29], v[28:29], v[32:33]
	v_pk_add_f32 v[32:33], v[26:27], v[38:39]
	v_pk_add_f32 v[34:35], v[24:25], v[36:37]
	v_cvt_pk_bf16_f32 v24, v28, v29
	v_cvt_pk_bf16_f32 v25, v30, v31
	v_cvt_pk_bf16_f32 v26, v34, v35
	v_cvt_pk_bf16_f32 v27, v32, v33
	global_store_dwordx4 v[80:81], v[24:27], off nt
	s_nop 1
	v_mul_f32_e32 v24, v29, v29
	v_mul_f32_e32 v25, v31, v31
	v_fmac_f32_e32 v24, v28, v28
	v_fmac_f32_e32 v25, v30, v30
	v_add_f32_e32 v24, v24, v25
	v_mul_f32_e32 v25, v35, v35
	v_fmac_f32_e32 v25, v34, v34
	v_add_f32_e32 v24, v25, v24
	v_mul_f32_e32 v25, v33, v33
	v_fmac_f32_e32 v25, v32, v32
	v_add_f32_e32 v32, v25, v24
	s_waitcnt vmcnt(7)
	v_lshlrev_b32_e32 v24, 16, v72
	v_and_b32_e32 v25, 0xffff0000, v72
	v_lshlrev_b32_e32 v26, 16, v73
	v_and_b32_e32 v27, 0xffff0000, v73
	v_lshlrev_b32_e32 v28, 16, v74
	v_and_b32_e32 v29, 0xffff0000, v74
	v_lshlrev_b32_e32 v30, 16, v75
	v_and_b32_e32 v31, 0xffff0000, v75
	v_pk_add_f32 v[22:23], v[22:23], v[26:27]
	v_pk_add_f32 v[20:21], v[20:21], v[24:25]
	v_pk_add_f32 v[24:25], v[18:19], v[30:31]
	v_pk_add_f32 v[26:27], v[16:17], v[28:29]
	v_cvt_pk_bf16_f32 v16, v20, v21
	v_cvt_pk_bf16_f32 v17, v22, v23
	v_cvt_pk_bf16_f32 v18, v26, v27
	v_cvt_pk_bf16_f32 v19, v24, v25
	global_store_dwordx4 v[80:81], v[16:19], off offset:256 nt
	s_nop 1
	v_mul_f32_e32 v16, v21, v21
	v_mul_f32_e32 v17, v23, v23
	v_fmac_f32_e32 v16, v20, v20
	v_fmac_f32_e32 v17, v22, v22
	v_add_f32_e32 v16, v16, v17
	v_mul_f32_e32 v17, v27, v27
	v_fmac_f32_e32 v17, v26, v26
	v_add_f32_e32 v16, v17, v16
	v_mul_f32_e32 v17, v25, v25
	v_fmac_f32_e32 v17, v24, v24
	v_add_f32_e32 v16, v17, v16
	v_add_f32_e32 v24, v32, v16
	s_waitcnt vmcnt(7)
	v_lshlrev_b32_e32 v16, 16, v68
	v_and_b32_e32 v17, 0xffff0000, v68
	v_lshlrev_b32_e32 v18, 16, v69
	v_and_b32_e32 v19, 0xffff0000, v69
	v_lshlrev_b32_e32 v20, 16, v70
	v_and_b32_e32 v21, 0xffff0000, v70
	v_lshlrev_b32_e32 v22, 16, v71
	v_and_b32_e32 v23, 0xffff0000, v71
	v_pk_add_f32 v[14:15], v[14:15], v[18:19]
	v_pk_add_f32 v[12:13], v[12:13], v[16:17]
	v_pk_add_f32 v[16:17], v[10:11], v[22:23]
	v_pk_add_f32 v[18:19], v[8:9], v[20:21]
	v_cvt_pk_bf16_f32 v8, v12, v13
	v_cvt_pk_bf16_f32 v9, v14, v15
	v_cvt_pk_bf16_f32 v10, v18, v19
	v_cvt_pk_bf16_f32 v11, v16, v17
	global_store_dwordx4 v[78:79], v[8:11], off nt
	s_nop 1
	v_mul_f32_e32 v8, v13, v13
	v_mul_f32_e32 v9, v15, v15
	v_fmac_f32_e32 v8, v12, v12
	v_fmac_f32_e32 v9, v14, v14
	v_add_f32_e32 v8, v8, v9
	v_mul_f32_e32 v9, v19, v19
	v_fmac_f32_e32 v9, v18, v18
	v_add_f32_e32 v8, v9, v8
	v_mul_f32_e32 v9, v17, v17
	v_fmac_f32_e32 v9, v16, v16
	v_add_f32_e32 v18, v9, v8
	s_waitcnt vmcnt(7)
	v_lshlrev_b32_e32 v8, 16, v64
	v_and_b32_e32 v9, 0xffff0000, v64
	v_lshlrev_b32_e32 v10, 16, v65
	v_and_b32_e32 v11, 0xffff0000, v65
	v_lshlrev_b32_e32 v12, 16, v66
	v_and_b32_e32 v13, 0xffff0000, v66
	v_pk_add_f32 v[16:17], v[6:7], v[10:11]
	v_pk_add_f32 v[4:5], v[4:5], v[8:9]
	v_pk_add_f32 v[12:13], v[0:1], v[12:13]
	v_mul_f32_e32 v0, v5, v5
	v_mul_f32_e32 v1, v17, v17
	v_fmac_f32_e32 v0, v4, v4
	v_fmac_f32_e32 v1, v16, v16
	v_lshlrev_b32_e32 v14, 16, v67
	v_and_b32_e32 v15, 0xffff0000, v67
	v_add_f32_e32 v0, v0, v1
	v_mul_f32_e32 v1, v13, v13
	v_pk_add_f32 v[14:15], v[2:3], v[14:15]
	v_fmac_f32_e32 v1, v12, v12
	v_add_f32_e32 v0, v1, v0
	v_mul_f32_e32 v1, v15, v15
	v_fmac_f32_e32 v1, v14, v14
	v_add_f32_e32 v0, v1, v0
	v_add_f32_e32 v0, v18, v0
	v_cvt_pk_bf16_f32 v10, v4, v5
	ds_bpermute_b32 v2, v172, v54
	ds_bpermute_b32 v1, v172, v40
	ds_bpermute_b32 v5, v172, v24
	ds_bpermute_b32 v7, v172, v0
	v_cvt_pk_bf16_f32 v11, v16, v17
	s_waitcnt lgkmcnt(3)
	v_add_f32_e32 v3, v54, v2
	s_waitcnt lgkmcnt(2)
	v_add_f32_e32 v1, v40, v1
	s_waitcnt lgkmcnt(1)
	v_add_f32_e32 v5, v24, v5
	s_waitcnt lgkmcnt(0)
	v_add_f32_e32 v7, v0, v7
	ds_bpermute_b32 v4, v169, v3
	ds_bpermute_b32 v2, v169, v1
	ds_bpermute_b32 v6, v169, v5
	ds_bpermute_b32 v8, v169, v7
	v_cvt_pk_bf16_f32 v12, v12, v13
	v_cvt_pk_bf16_f32 v13, v14, v15
	global_store_dwordx4 v[78:79], v[10:13], off offset:256 nt
	s_and_saveexec_b64 s[2:3], vcc
	s_xor_b64 s[2:3], exec, s[2:3]
	s_cbranch_execz .LBB0_908
	v_cmp_ne_u32_e32 vcc, 1, v171
	s_and_saveexec_b64 s[14:15], vcc
	s_xor_b64 s[14:15], exec, s[14:15]
	s_cbranch_execz .LBB0_905
	s_waitcnt lgkmcnt(0)
	v_add_f32_e32 v0, v7, v8
	v_add_f32_e32 v1, v5, v6
	v_cndmask_b32_e64 v0, v0, v1, s[6:7]
